# OUT and DOWN GEMMs (full and half-tile loops) also with swapped MFMA operands: no accumulator re-layout, residual epilogue stages f32 tiles with ds_write_b128 (was 128 ds_write_b32 per wave), read/fma
# speedup vs baseline: 1.0351x; 1.0038x over previous
.LBB0_923:
	s_ashr_i32 s2, s4, 31
	s_lshr_b32 s2, s2, 26
	s_add_i32 s2, s4, s2
	s_ashr_i32 s3, s2, 6
	s_lshl_b32 s3, s3, 3
	s_sub_i32 s8, s25, s3
	s_min_i32 s8, s8, 8
	s_abs_i32 s9, s8
	v_cvt_f32_u32_e32 v0, s9
	s_sub_i32 s12, 0, s9
	s_andn2_b32 s2, s2, 63
	s_sub_i32 s10, s4, s2
	v_rcp_iflag_f32_e32 v0, v0
	s_abs_i32 s2, s10
	s_xor_b32 s11, s10, s8
	s_ashr_i32 s11, s11, 31
	v_mul_f32_e32 v0, 0x4f7ffffe, v0
	v_cvt_u32_f32_e32 v0, v0
	v_mov_b32_e32 v181, v179
	v_readfirstlane_b32 s13, v0
	s_mul_i32 s12, s12, s13
	s_mul_hi_u32 s12, s13, s12
	s_add_i32 s13, s13, s12
	s_mul_hi_u32 s12, s2, s13
	s_mul_i32 s13, s12, s9
	s_sub_i32 s2, s2, s13
	s_add_i32 s14, s12, 1
	s_sub_i32 s13, s2, s9
	s_cmp_ge_u32 s2, s9
	s_cselect_b32 s12, s14, s12
	s_cselect_b32 s2, s13, s2
	s_add_i32 s13, s12, 1
	s_cmp_ge_u32 s2, s9
	s_cselect_b32 s2, s13, s12
	s_xor_b32 s2, s2, s11
	s_sub_i32 s2, s2, s11
	s_mul_i32 s8, s8, s2
	s_add_i32 s3, s3, s7
	s_sub_i32 s8, s10, s8
	v_ashrrev_i32_e32 v237, 6, v181
	s_add_i32 s8, s3, s8
	v_lshlrev_b32_e32 v0, 1, v237
	v_lshl_add_u32 v0, s8, 3, v0
	v_ashrrev_i32_e32 v1, 31, v0
	v_bfe_u32 v183, v181, 5, 1
	v_lshlrev_b64 v[0:1], 16, v[0:1]
	v_and_b32_e32 v238, 31, v181
	v_lshl_add_u64 v[0:1], s[64:65], 0, v[0:1]
	v_lshlrev_b32_e32 v176, 9, v183
	s_ashr_i32 s3, s2, 31
	v_lshl_add_u64 v[0:1], v[0:1], 0, v[176:177]
	v_lshlrev_b32_e32 v176, 4, v238
	v_ashrrev_i32_e32 v40, 2, v181
	s_lshl_b64 s[10:11], s[2:3], 18
	v_lshl_add_u64 v[184:185], v[0:1], 0, v[176:177]
	s_add_u32 s10, s5, s10
	v_lshlrev_b32_e32 v0, 5, v40
	s_addc_u32 s11, s6, s11
	v_ashrrev_i32_e32 v1, 31, v0
	v_lshlrev_b32_e32 v2, 4, v181
	v_lshl_add_u64 v[0:1], v[0:1], 1, s[10:11]
	v_and_b32_e32 v176, 48, v2
	v_lshl_add_u64 v[186:187], v[0:1], 0, v[176:177]
	s_movk_i32 s3, 0x2000
	v_add_co_u32_e32 v36, vcc, s3, v186
	v_mul_u32_u24_e32 v38, 40, v238
	s_nop 0
	v_addc_co_u32_e32 v37, vcc, 0, v187, vcc
	v_lshlrev_b32_e32 v39, 4, v183
	v_lshl_add_u32 v240, v38, 1, v39
	v_add_co_u32_e32 v38, vcc, s41, v184
	s_movk_i32 s9, 0x50
	s_nop 0
	v_addc_co_u32_e32 v39, vcc, 0, v185, vcc
	v_and_b32_e32 v239, 63, v181
	s_cmp_eq_u32 s100, 1
	s_cbranch_scc1 .Lhx_out_half
	v_bfe_u32 v247, v181, 4, 2
	v_lshlrev_b32_e32 v247, 1, v247
	v_mov_b32_e32 v176, 0x78
	v_lshrrev_b32_e32 v247, v247, v176
	v_and_b32_e32 v247, 3, v247
	v_and_b32_e32 v246, 3, v181
	v_xor_b32_e32 v247, v247, v246
	v_lshlrev_b32_e32 v247, 4, v247
	v_and_b32_e32 v188, 0xffffffcf, v186
	v_or_b32_e32 v188, v188, v247
	v_mov_b32_e32 v189, v187
	v_lshrrev_b32_e32 v176, 6, v181
	v_lshlrev_b32_e32 v247, 11, v176
	v_lshlrev_b32_e32 v176, 10, v176
	v_lshl_add_u64 v[188:189], v[188:189], 0, v[176:177]
	v_readfirstlane_b32 vcc_lo, v247
	v_bfe_u32 v247, v181, 4, 1
	v_lshlrev_b32_e32 v176, 9, v183
	v_lshl_add_u32 v176, v247, 8, v176
	v_lshl_add_u64 v[184:185], v[184:185], 0, v[176:177]
	v_mov_b32_e32 v176, s41
	v_lshl_add_u64 v[186:187], v[184:185], 0, v[176:177]
	v_mov_b32_e32 v176, 0x78
	v_bfe_u32 v247, v181, 2, 1
	v_lshlrev_b32_e32 v247, 2, v247
	v_lshrrev_b32_e32 v247, v247, v176
	v_and_b32_e32 v247, 3, v247
	v_bfe_u32 v246, v181, 4, 2
	v_xor_b32_e32 v247, v247, v246
	v_lshlrev_b32_e32 v247, 4, v247
	v_bfe_u32 v246, v181, 2, 2
	v_lshlrev_b32_e32 v246, 3, v246
	v_and_b32_e32 v162, 3, v181
	v_add_u32_e32 v246, v246, v162
	v_lshl_add_u32 v246, v246, 6, v247
	v_bfe_u32 v247, v181, 2, 1
	v_lshlrev_b32_e32 v247, 2, v247
	v_add_u32_e32 v247, 2, v247
	v_lshrrev_b32_e32 v247, v247, v176
	v_and_b32_e32 v247, 3, v247
	v_bfe_u32 v162, v181, 4, 2
	v_xor_b32_e32 v247, v247, v162
	v_lshlrev_b32_e32 v247, 4, v247
	v_and_b32_e32 v162, 0xffffffcf, v246
	v_add_u32_e32 v162, 0x100, v162
	v_or_b32_e32 v162, v162, v247
	s_mov_b32 s96, 0
	s_mov_b32 m0, vcc_lo
	v_lshl_add_u64 v[160:161], v[188:189], 0, s[96:97]
	global_load_lds_dwordx4 v[160:161], off
	global_load_lds_dwordx4 v[160:161], off offset:1024
	s_mov_b32 s96, 0
	v_lshl_add_u64 v[248:249], v[184:185], 0, s[96:97]
	v_lshl_add_u64 v[250:251], v[186:187], 0, s[96:97]
	global_load_dwordx4 v[128:131], v[248:249], off
	global_load_dwordx4 v[132:135], v[248:249], off offset:256
	global_load_dwordx4 v[136:139], v[250:251], off
	global_load_dwordx4 v[140:143], v[250:251], off offset:256
	s_movk_i32 s96, 0x2000
	s_add_i32 m0, vcc_lo, 8192
	v_lshl_add_u64 v[160:161], v[188:189], 0, s[96:97]
	global_load_lds_dwordx4 v[160:161], off
	global_load_lds_dwordx4 v[160:161], off offset:1024
	s_movk_i32 s96, 0x800
	v_lshl_add_u64 v[248:249], v[184:185], 0, s[96:97]
	v_lshl_add_u64 v[250:251], v[186:187], 0, s[96:97]
	global_load_dwordx4 v[144:147], v[248:249], off
	global_load_dwordx4 v[148:151], v[248:249], off offset:256
	global_load_dwordx4 v[152:155], v[250:251], off
	global_load_dwordx4 v[156:159], v[250:251], off offset:256
	v_mov_b32_e32 v0, 0
	v_mov_b32_e32 v1, 0
	v_mov_b32_e32 v2, 0
	v_mov_b32_e32 v3, 0
	v_mov_b32_e32 v4, 0
	v_mov_b32_e32 v5, 0
	v_mov_b32_e32 v6, 0
	v_mov_b32_e32 v7, 0
	v_mov_b32_e32 v8, 0
	v_mov_b32_e32 v9, 0
	v_mov_b32_e32 v10, 0
	v_mov_b32_e32 v11, 0
	v_mov_b32_e32 v12, 0
	v_mov_b32_e32 v13, 0
	v_mov_b32_e32 v14, 0
	v_mov_b32_e32 v15, 0
	v_mov_b32_e32 v16, 0
	v_mov_b32_e32 v17, 0
	v_mov_b32_e32 v18, 0
	v_mov_b32_e32 v19, 0
	v_mov_b32_e32 v20, 0
	v_mov_b32_e32 v21, 0
	v_mov_b32_e32 v22, 0
	v_mov_b32_e32 v23, 0
	v_mov_b32_e32 v24, 0
	v_mov_b32_e32 v25, 0
	v_mov_b32_e32 v26, 0
	v_mov_b32_e32 v27, 0
	v_mov_b32_e32 v28, 0
	v_mov_b32_e32 v29, 0
	v_mov_b32_e32 v30, 0
	v_mov_b32_e32 v31, 0
	v_mov_b32_e32 v32, 0
	v_mov_b32_e32 v33, 0
	v_mov_b32_e32 v34, 0
	v_mov_b32_e32 v35, 0
	v_mov_b32_e32 v36, 0
	v_mov_b32_e32 v37, 0
	v_mov_b32_e32 v38, 0
	v_mov_b32_e32 v39, 0
	v_mov_b32_e32 v40, 0
	v_mov_b32_e32 v41, 0
	v_mov_b32_e32 v42, 0
	v_mov_b32_e32 v43, 0
	v_mov_b32_e32 v44, 0
	v_mov_b32_e32 v45, 0
	v_mov_b32_e32 v46, 0
	v_mov_b32_e32 v47, 0
	v_mov_b32_e32 v48, 0
	v_mov_b32_e32 v49, 0
	v_mov_b32_e32 v50, 0
	v_mov_b32_e32 v51, 0
	v_mov_b32_e32 v52, 0
	v_mov_b32_e32 v53, 0
	v_mov_b32_e32 v54, 0
	v_mov_b32_e32 v55, 0
	v_mov_b32_e32 v56, 0
	v_mov_b32_e32 v57, 0
	v_mov_b32_e32 v58, 0
	v_mov_b32_e32 v59, 0
	v_mov_b32_e32 v60, 0
	v_mov_b32_e32 v61, 0
	v_mov_b32_e32 v62, 0
	v_mov_b32_e32 v63, 0
	v_mov_b32_e32 v64, 0
	v_mov_b32_e32 v65, 0
	v_mov_b32_e32 v66, 0
	v_mov_b32_e32 v67, 0
	v_mov_b32_e32 v68, 0
	v_mov_b32_e32 v69, 0
	v_mov_b32_e32 v70, 0
	v_mov_b32_e32 v71, 0
	v_mov_b32_e32 v72, 0
	v_mov_b32_e32 v73, 0
	v_mov_b32_e32 v74, 0
	v_mov_b32_e32 v75, 0
	v_mov_b32_e32 v76, 0
	v_mov_b32_e32 v77, 0
	v_mov_b32_e32 v78, 0
	v_mov_b32_e32 v79, 0
	v_mov_b32_e32 v80, 0
	v_mov_b32_e32 v81, 0
	v_mov_b32_e32 v82, 0
	v_mov_b32_e32 v83, 0
	v_mov_b32_e32 v84, 0
	v_mov_b32_e32 v85, 0
	v_mov_b32_e32 v86, 0
	v_mov_b32_e32 v87, 0
	v_mov_b32_e32 v88, 0
	v_mov_b32_e32 v89, 0
	v_mov_b32_e32 v90, 0
	v_mov_b32_e32 v91, 0
	v_mov_b32_e32 v92, 0
	v_mov_b32_e32 v93, 0
	v_mov_b32_e32 v94, 0
	v_mov_b32_e32 v95, 0
	v_mov_b32_e32 v96, 0
	v_mov_b32_e32 v97, 0
	v_mov_b32_e32 v98, 0
	v_mov_b32_e32 v99, 0
	v_mov_b32_e32 v100, 0
	v_mov_b32_e32 v101, 0
	v_mov_b32_e32 v102, 0
	v_mov_b32_e32 v103, 0
	v_mov_b32_e32 v104, 0
	v_mov_b32_e32 v105, 0
	v_mov_b32_e32 v106, 0
	v_mov_b32_e32 v107, 0
	v_mov_b32_e32 v108, 0
	v_mov_b32_e32 v109, 0
	v_mov_b32_e32 v110, 0
	v_mov_b32_e32 v111, 0
	v_mov_b32_e32 v112, 0
	v_mov_b32_e32 v113, 0
	v_mov_b32_e32 v114, 0
	v_mov_b32_e32 v115, 0
	v_mov_b32_e32 v116, 0
	v_mov_b32_e32 v117, 0
	v_mov_b32_e32 v118, 0
	v_mov_b32_e32 v119, 0
	v_mov_b32_e32 v120, 0
	v_mov_b32_e32 v121, 0
	v_mov_b32_e32 v122, 0
	v_mov_b32_e32 v123, 0
	v_mov_b32_e32 v124, 0
	v_mov_b32_e32 v125, 0
	v_mov_b32_e32 v126, 0
	v_mov_b32_e32 v127, 0
	s_mov_b32 s3, 0
	s_waitcnt vmcnt(4)
	s_barrier
.Lg16_out_k:
	s_add_i32 s9, s3, 2
	s_lshl_b32 s96, s9, 13
	s_add_i32 m0, vcc_lo, 16384
	v_lshl_add_u64 v[160:161], v[188:189], 0, s[96:97]
	global_load_lds_dwordx4 v[160:161], off
	global_load_lds_dwordx4 v[160:161], off offset:1024
	ds_read_b128 v[196:199], v246 offset:0
	ds_read_b128 v[200:203], v162 offset:0
	ds_read_b128 v[204:207], v246 offset:2048
	ds_read_b128 v[242:245], v162 offset:2048
	s_add_i32 s9, s3, 2
	s_lshl_b32 s96, s9, 11
	v_lshl_add_u64 v[248:249], v[184:185], 0, s[96:97]
	v_lshl_add_u64 v[250:251], v[186:187], 0, s[96:97]
	s_waitcnt vmcnt(8) lgkmcnt(3)
	v_mfma_f32_16x16x32_bf16 v[112:115], v[196:199], v[128:131], v[112:115]
	v_mfma_f32_16x16x32_bf16 v[120:123], v[196:199], v[132:135], v[120:123]
	v_mfma_f32_16x16x32_bf16 v[48:51], v[196:199], v[136:139], v[48:51]
	v_mfma_f32_16x16x32_bf16 v[56:59], v[196:199], v[140:143], v[56:59]
	ds_read_b128 v[196:199], v246 offset:4096
	s_waitcnt lgkmcnt(3)
	v_mfma_f32_16x16x32_bf16 v[116:119], v[200:203], v[128:131], v[116:119]
	v_mfma_f32_16x16x32_bf16 v[124:127], v[200:203], v[132:135], v[124:127]
	v_mfma_f32_16x16x32_bf16 v[52:55], v[200:203], v[136:139], v[52:55]
	v_mfma_f32_16x16x32_bf16 v[60:63], v[200:203], v[140:143], v[60:63]
	ds_read_b128 v[200:203], v162 offset:4096
	s_waitcnt lgkmcnt(3)
	v_mfma_f32_16x16x32_bf16 v[96:99], v[204:207], v[128:131], v[96:99]
	v_mfma_f32_16x16x32_bf16 v[104:107], v[204:207], v[132:135], v[104:107]
	v_mfma_f32_16x16x32_bf16 v[32:35], v[204:207], v[136:139], v[32:35]
	v_mfma_f32_16x16x32_bf16 v[40:43], v[204:207], v[140:143], v[40:43]
	ds_read_b128 v[204:207], v246 offset:6144
	s_waitcnt lgkmcnt(3)
	v_mfma_f32_16x16x32_bf16 v[100:103], v[242:245], v[128:131], v[100:103]
	v_mfma_f32_16x16x32_bf16 v[108:111], v[242:245], v[132:135], v[108:111]
	v_mfma_f32_16x16x32_bf16 v[36:39], v[242:245], v[136:139], v[36:39]
	v_mfma_f32_16x16x32_bf16 v[44:47], v[242:245], v[140:143], v[44:47]
	ds_read_b128 v[242:245], v162 offset:6144
	s_waitcnt lgkmcnt(3)
	v_mfma_f32_16x16x32_bf16 v[80:83], v[196:199], v[128:131], v[80:83]
	v_mfma_f32_16x16x32_bf16 v[88:91], v[196:199], v[132:135], v[88:91]
	v_mfma_f32_16x16x32_bf16 v[16:19], v[196:199], v[136:139], v[16:19]
	v_mfma_f32_16x16x32_bf16 v[24:27], v[196:199], v[140:143], v[24:27]
	s_waitcnt lgkmcnt(2)
	v_mfma_f32_16x16x32_bf16 v[84:87], v[200:203], v[128:131], v[84:87]
	v_mfma_f32_16x16x32_bf16 v[92:95], v[200:203], v[132:135], v[92:95]
	v_mfma_f32_16x16x32_bf16 v[20:23], v[200:203], v[136:139], v[20:23]
	v_mfma_f32_16x16x32_bf16 v[28:31], v[200:203], v[140:143], v[28:31]
	s_waitcnt lgkmcnt(1)
	v_mfma_f32_16x16x32_bf16 v[64:67], v[204:207], v[128:131], v[64:67]
	v_mfma_f32_16x16x32_bf16 v[72:75], v[204:207], v[132:135], v[72:75]
	v_mfma_f32_16x16x32_bf16 v[0:3], v[204:207], v[136:139], v[0:3]
	v_mfma_f32_16x16x32_bf16 v[8:11], v[204:207], v[140:143], v[8:11]
	s_waitcnt lgkmcnt(0)
	v_mfma_f32_16x16x32_bf16 v[68:71], v[242:245], v[128:131], v[68:71]
	v_mfma_f32_16x16x32_bf16 v[76:79], v[242:245], v[132:135], v[76:79]
	v_mfma_f32_16x16x32_bf16 v[4:7], v[242:245], v[136:139], v[4:7]
	v_mfma_f32_16x16x32_bf16 v[12:15], v[242:245], v[140:143], v[12:15]
	global_load_dwordx4 v[128:131], v[248:249], off
	global_load_dwordx4 v[132:135], v[248:249], off offset:256
	global_load_dwordx4 v[136:139], v[250:251], off
	global_load_dwordx4 v[140:143], v[250:251], off offset:256
	s_waitcnt vmcnt(10)
	s_barrier
	s_add_i32 s9, s3, 3
	s_lshl_b32 s96, s9, 13
	s_mov_b32 m0, vcc_lo
	v_lshl_add_u64 v[160:161], v[188:189], 0, s[96:97]
	global_load_lds_dwordx4 v[160:161], off
	global_load_lds_dwordx4 v[160:161], off offset:1024
	ds_read_b128 v[196:199], v246 offset:8192
	ds_read_b128 v[200:203], v162 offset:8192
	ds_read_b128 v[204:207], v246 offset:10240
	ds_read_b128 v[242:245], v162 offset:10240
	s_add_i32 s9, s3, 3
	s_lshl_b32 s96, s9, 11
	v_lshl_add_u64 v[248:249], v[184:185], 0, s[96:97]
	v_lshl_add_u64 v[250:251], v[186:187], 0, s[96:97]
	s_waitcnt vmcnt(8) lgkmcnt(3)
	v_mfma_f32_16x16x32_bf16 v[112:115], v[196:199], v[144:147], v[112:115]
	v_mfma_f32_16x16x32_bf16 v[120:123], v[196:199], v[148:151], v[120:123]
	v_mfma_f32_16x16x32_bf16 v[48:51], v[196:199], v[152:155], v[48:51]
	v_mfma_f32_16x16x32_bf16 v[56:59], v[196:199], v[156:159], v[56:59]
	ds_read_b128 v[196:199], v246 offset:12288
	s_waitcnt lgkmcnt(3)
	v_mfma_f32_16x16x32_bf16 v[116:119], v[200:203], v[144:147], v[116:119]
	v_mfma_f32_16x16x32_bf16 v[124:127], v[200:203], v[148:151], v[124:127]
	v_mfma_f32_16x16x32_bf16 v[52:55], v[200:203], v[152:155], v[52:55]
	v_mfma_f32_16x16x32_bf16 v[60:63], v[200:203], v[156:159], v[60:63]
	ds_read_b128 v[200:203], v162 offset:12288
	s_waitcnt lgkmcnt(3)
	v_mfma_f32_16x16x32_bf16 v[96:99], v[204:207], v[144:147], v[96:99]
	v_mfma_f32_16x16x32_bf16 v[104:107], v[204:207], v[148:151], v[104:107]
	v_mfma_f32_16x16x32_bf16 v[32:35], v[204:207], v[152:155], v[32:35]
	v_mfma_f32_16x16x32_bf16 v[40:43], v[204:207], v[156:159], v[40:43]
	ds_read_b128 v[204:207], v246 offset:14336
	s_waitcnt lgkmcnt(3)
	v_mfma_f32_16x16x32_bf16 v[100:103], v[242:245], v[144:147], v[100:103]
	v_mfma_f32_16x16x32_bf16 v[108:111], v[242:245], v[148:151], v[108:111]
	v_mfma_f32_16x16x32_bf16 v[36:39], v[242:245], v[152:155], v[36:39]
	v_mfma_f32_16x16x32_bf16 v[44:47], v[242:245], v[156:159], v[44:47]
	ds_read_b128 v[242:245], v162 offset:14336
	s_waitcnt lgkmcnt(3)
	v_mfma_f32_16x16x32_bf16 v[80:83], v[196:199], v[144:147], v[80:83]
	v_mfma_f32_16x16x32_bf16 v[88:91], v[196:199], v[148:151], v[88:91]
	v_mfma_f32_16x16x32_bf16 v[16:19], v[196:199], v[152:155], v[16:19]
	v_mfma_f32_16x16x32_bf16 v[24:27], v[196:199], v[156:159], v[24:27]
	s_waitcnt lgkmcnt(2)
	v_mfma_f32_16x16x32_bf16 v[84:87], v[200:203], v[144:147], v[84:87]
	v_mfma_f32_16x16x32_bf16 v[92:95], v[200:203], v[148:151], v[92:95]
	v_mfma_f32_16x16x32_bf16 v[20:23], v[200:203], v[152:155], v[20:23]
	v_mfma_f32_16x16x32_bf16 v[28:31], v[200:203], v[156:159], v[28:31]
	s_waitcnt lgkmcnt(1)
	v_mfma_f32_16x16x32_bf16 v[64:67], v[204:207], v[144:147], v[64:67]
	v_mfma_f32_16x16x32_bf16 v[72:75], v[204:207], v[148:151], v[72:75]
	v_mfma_f32_16x16x32_bf16 v[0:3], v[204:207], v[152:155], v[0:3]
	v_mfma_f32_16x16x32_bf16 v[8:11], v[204:207], v[156:159], v[8:11]
	s_waitcnt lgkmcnt(0)
	v_mfma_f32_16x16x32_bf16 v[68:71], v[242:245], v[144:147], v[68:71]
	v_mfma_f32_16x16x32_bf16 v[76:79], v[242:245], v[148:151], v[76:79]
	v_mfma_f32_16x16x32_bf16 v[4:7], v[242:245], v[152:155], v[4:7]
	v_mfma_f32_16x16x32_bf16 v[12:15], v[242:245], v[156:159], v[12:15]
	global_load_dwordx4 v[144:147], v[248:249], off
	global_load_dwordx4 v[148:151], v[248:249], off offset:256
	global_load_dwordx4 v[152:155], v[250:251], off
	global_load_dwordx4 v[156:159], v[250:251], off offset:256
	s_waitcnt vmcnt(10)
	s_barrier
	s_add_i32 s9, s3, 4
	s_lshl_b32 s96, s9, 13
	s_add_i32 m0, vcc_lo, 8192
	v_lshl_add_u64 v[160:161], v[188:189], 0, s[96:97]
	global_load_lds_dwordx4 v[160:161], off
	global_load_lds_dwordx4 v[160:161], off offset:1024
	ds_read_b128 v[196:199], v246 offset:16384
	ds_read_b128 v[200:203], v162 offset:16384
	ds_read_b128 v[204:207], v246 offset:18432
	ds_read_b128 v[242:245], v162 offset:18432
	s_add_i32 s9, s3, 4
	s_lshl_b32 s96, s9, 11
	v_lshl_add_u64 v[248:249], v[184:185], 0, s[96:97]
	v_lshl_add_u64 v[250:251], v[186:187], 0, s[96:97]
	s_waitcnt vmcnt(8) lgkmcnt(3)
	v_mfma_f32_16x16x32_bf16 v[112:115], v[196:199], v[128:131], v[112:115]
	v_mfma_f32_16x16x32_bf16 v[120:123], v[196:199], v[132:135], v[120:123]
	v_mfma_f32_16x16x32_bf16 v[48:51], v[196:199], v[136:139], v[48:51]
	v_mfma_f32_16x16x32_bf16 v[56:59], v[196:199], v[140:143], v[56:59]
	ds_read_b128 v[196:199], v246 offset:20480
	s_waitcnt lgkmcnt(3)
	v_mfma_f32_16x16x32_bf16 v[116:119], v[200:203], v[128:131], v[116:119]
	v_mfma_f32_16x16x32_bf16 v[124:127], v[200:203], v[132:135], v[124:127]
	v_mfma_f32_16x16x32_bf16 v[52:55], v[200:203], v[136:139], v[52:55]
	v_mfma_f32_16x16x32_bf16 v[60:63], v[200:203], v[140:143], v[60:63]
	ds_read_b128 v[200:203], v162 offset:20480
	s_waitcnt lgkmcnt(3)
	v_mfma_f32_16x16x32_bf16 v[96:99], v[204:207], v[128:131], v[96:99]
	v_mfma_f32_16x16x32_bf16 v[104:107], v[204:207], v[132:135], v[104:107]
	v_mfma_f32_16x16x32_bf16 v[32:35], v[204:207], v[136:139], v[32:35]
	v_mfma_f32_16x16x32_bf16 v[40:43], v[204:207], v[140:143], v[40:43]
	ds_read_b128 v[204:207], v246 offset:22528
	s_waitcnt lgkmcnt(3)
	v_mfma_f32_16x16x32_bf16 v[100:103], v[242:245], v[128:131], v[100:103]
	v_mfma_f32_16x16x32_bf16 v[108:111], v[242:245], v[132:135], v[108:111]
	v_mfma_f32_16x16x32_bf16 v[36:39], v[242:245], v[136:139], v[36:39]
	v_mfma_f32_16x16x32_bf16 v[44:47], v[242:245], v[140:143], v[44:47]
	ds_read_b128 v[242:245], v162 offset:22528
	s_waitcnt lgkmcnt(3)
	v_mfma_f32_16x16x32_bf16 v[80:83], v[196:199], v[128:131], v[80:83]
	v_mfma_f32_16x16x32_bf16 v[88:91], v[196:199], v[132:135], v[88:91]
	v_mfma_f32_16x16x32_bf16 v[16:19], v[196:199], v[136:139], v[16:19]
	v_mfma_f32_16x16x32_bf16 v[24:27], v[196:199], v[140:143], v[24:27]
	s_waitcnt lgkmcnt(2)
	v_mfma_f32_16x16x32_bf16 v[84:87], v[200:203], v[128:131], v[84:87]
	v_mfma_f32_16x16x32_bf16 v[92:95], v[200:203], v[132:135], v[92:95]
	v_mfma_f32_16x16x32_bf16 v[20:23], v[200:203], v[136:139], v[20:23]
	v_mfma_f32_16x16x32_bf16 v[28:31], v[200:203], v[140:143], v[28:31]
	s_waitcnt lgkmcnt(1)
	v_mfma_f32_16x16x32_bf16 v[64:67], v[204:207], v[128:131], v[64:67]
	v_mfma_f32_16x16x32_bf16 v[72:75], v[204:207], v[132:135], v[72:75]
	v_mfma_f32_16x16x32_bf16 v[0:3], v[204:207], v[136:139], v[0:3]
	v_mfma_f32_16x16x32_bf16 v[8:11], v[204:207], v[140:143], v[8:11]
	s_waitcnt lgkmcnt(0)
	v_mfma_f32_16x16x32_bf16 v[68:71], v[242:245], v[128:131], v[68:71]
	v_mfma_f32_16x16x32_bf16 v[76:79], v[242:245], v[132:135], v[76:79]
	v_mfma_f32_16x16x32_bf16 v[4:7], v[242:245], v[136:139], v[4:7]
	v_mfma_f32_16x16x32_bf16 v[12:15], v[242:245], v[140:143], v[12:15]
	global_load_dwordx4 v[128:131], v[248:249], off
	global_load_dwordx4 v[132:135], v[248:249], off offset:256
	global_load_dwordx4 v[136:139], v[250:251], off
	global_load_dwordx4 v[140:143], v[250:251], off offset:256
	s_waitcnt vmcnt(10)
	s_barrier
	s_add_i32 s9, s3, 5
	s_lshl_b32 s96, s9, 13
	s_add_i32 m0, vcc_lo, 16384
	v_lshl_add_u64 v[160:161], v[188:189], 0, s[96:97]
	global_load_lds_dwordx4 v[160:161], off
	global_load_lds_dwordx4 v[160:161], off offset:1024
	ds_read_b128 v[196:199], v246 offset:0
	ds_read_b128 v[200:203], v162 offset:0
	ds_read_b128 v[204:207], v246 offset:2048
	ds_read_b128 v[242:245], v162 offset:2048
	s_add_i32 s9, s3, 5
	s_lshl_b32 s96, s9, 11
	v_lshl_add_u64 v[248:249], v[184:185], 0, s[96:97]
	v_lshl_add_u64 v[250:251], v[186:187], 0, s[96:97]
	s_waitcnt vmcnt(8) lgkmcnt(3)
	v_mfma_f32_16x16x32_bf16 v[112:115], v[196:199], v[144:147], v[112:115]
	v_mfma_f32_16x16x32_bf16 v[120:123], v[196:199], v[148:151], v[120:123]
	v_mfma_f32_16x16x32_bf16 v[48:51], v[196:199], v[152:155], v[48:51]
	v_mfma_f32_16x16x32_bf16 v[56:59], v[196:199], v[156:159], v[56:59]
	ds_read_b128 v[196:199], v246 offset:4096
	s_waitcnt lgkmcnt(3)
	v_mfma_f32_16x16x32_bf16 v[116:119], v[200:203], v[144:147], v[116:119]
	v_mfma_f32_16x16x32_bf16 v[124:127], v[200:203], v[148:151], v[124:127]
	v_mfma_f32_16x16x32_bf16 v[52:55], v[200:203], v[152:155], v[52:55]
	v_mfma_f32_16x16x32_bf16 v[60:63], v[200:203], v[156:159], v[60:63]
	ds_read_b128 v[200:203], v162 offset:4096
	s_waitcnt lgkmcnt(3)
	v_mfma_f32_16x16x32_bf16 v[96:99], v[204:207], v[144:147], v[96:99]
	v_mfma_f32_16x16x32_bf16 v[104:107], v[204:207], v[148:151], v[104:107]
	v_mfma_f32_16x16x32_bf16 v[32:35], v[204:207], v[152:155], v[32:35]
	v_mfma_f32_16x16x32_bf16 v[40:43], v[204:207], v[156:159], v[40:43]
	ds_read_b128 v[204:207], v246 offset:6144
	s_waitcnt lgkmcnt(3)
	v_mfma_f32_16x16x32_bf16 v[100:103], v[242:245], v[144:147], v[100:103]
	v_mfma_f32_16x16x32_bf16 v[108:111], v[242:245], v[148:151], v[108:111]
	v_mfma_f32_16x16x32_bf16 v[36:39], v[242:245], v[152:155], v[36:39]
	v_mfma_f32_16x16x32_bf16 v[44:47], v[242:245], v[156:159], v[44:47]
	ds_read_b128 v[242:245], v162 offset:6144
	s_waitcnt lgkmcnt(3)
	v_mfma_f32_16x16x32_bf16 v[80:83], v[196:199], v[144:147], v[80:83]
	v_mfma_f32_16x16x32_bf16 v[88:91], v[196:199], v[148:151], v[88:91]
	v_mfma_f32_16x16x32_bf16 v[16:19], v[196:199], v[152:155], v[16:19]
	v_mfma_f32_16x16x32_bf16 v[24:27], v[196:199], v[156:159], v[24:27]
	s_waitcnt lgkmcnt(2)
	v_mfma_f32_16x16x32_bf16 v[84:87], v[200:203], v[144:147], v[84:87]
	v_mfma_f32_16x16x32_bf16 v[92:95], v[200:203], v[148:151], v[92:95]
	v_mfma_f32_16x16x32_bf16 v[20:23], v[200:203], v[152:155], v[20:23]
	v_mfma_f32_16x16x32_bf16 v[28:31], v[200:203], v[156:159], v[28:31]
	s_waitcnt lgkmcnt(1)
	v_mfma_f32_16x16x32_bf16 v[64:67], v[204:207], v[144:147], v[64:67]
	v_mfma_f32_16x16x32_bf16 v[72:75], v[204:207], v[148:151], v[72:75]
	v_mfma_f32_16x16x32_bf16 v[0:3], v[204:207], v[152:155], v[0:3]
	v_mfma_f32_16x16x32_bf16 v[8:11], v[204:207], v[156:159], v[8:11]
	s_waitcnt lgkmcnt(0)
	v_mfma_f32_16x16x32_bf16 v[68:71], v[242:245], v[144:147], v[68:71]
	v_mfma_f32_16x16x32_bf16 v[76:79], v[242:245], v[148:151], v[76:79]
	v_mfma_f32_16x16x32_bf16 v[4:7], v[242:245], v[152:155], v[4:7]
	v_mfma_f32_16x16x32_bf16 v[12:15], v[242:245], v[156:159], v[12:15]
	global_load_dwordx4 v[144:147], v[248:249], off
	global_load_dwordx4 v[148:151], v[248:249], off offset:256
	global_load_dwordx4 v[152:155], v[250:251], off
	global_load_dwordx4 v[156:159], v[250:251], off offset:256
	s_waitcnt vmcnt(10)
	s_barrier
	s_add_i32 s9, s3, 6
	s_lshl_b32 s96, s9, 13
	s_mov_b32 m0, vcc_lo
	v_lshl_add_u64 v[160:161], v[188:189], 0, s[96:97]
	global_load_lds_dwordx4 v[160:161], off
	global_load_lds_dwordx4 v[160:161], off offset:1024
	ds_read_b128 v[196:199], v246 offset:8192
	ds_read_b128 v[200:203], v162 offset:8192
	ds_read_b128 v[204:207], v246 offset:10240
	ds_read_b128 v[242:245], v162 offset:10240
	s_add_i32 s9, s3, 6
	s_lshl_b32 s96, s9, 11
	v_lshl_add_u64 v[248:249], v[184:185], 0, s[96:97]
	v_lshl_add_u64 v[250:251], v[186:187], 0, s[96:97]
	s_waitcnt vmcnt(8) lgkmcnt(3)
	v_mfma_f32_16x16x32_bf16 v[112:115], v[196:199], v[128:131], v[112:115]
	v_mfma_f32_16x16x32_bf16 v[120:123], v[196:199], v[132:135], v[120:123]
	v_mfma_f32_16x16x32_bf16 v[48:51], v[196:199], v[136:139], v[48:51]
	v_mfma_f32_16x16x32_bf16 v[56:59], v[196:199], v[140:143], v[56:59]
	ds_read_b128 v[196:199], v246 offset:12288
	s_waitcnt lgkmcnt(3)
	v_mfma_f32_16x16x32_bf16 v[116:119], v[200:203], v[128:131], v[116:119]
	v_mfma_f32_16x16x32_bf16 v[124:127], v[200:203], v[132:135], v[124:127]
	v_mfma_f32_16x16x32_bf16 v[52:55], v[200:203], v[136:139], v[52:55]
	v_mfma_f32_16x16x32_bf16 v[60:63], v[200:203], v[140:143], v[60:63]
	ds_read_b128 v[200:203], v162 offset:12288
	s_waitcnt lgkmcnt(3)
	v_mfma_f32_16x16x32_bf16 v[96:99], v[204:207], v[128:131], v[96:99]
	v_mfma_f32_16x16x32_bf16 v[104:107], v[204:207], v[132:135], v[104:107]
	v_mfma_f32_16x16x32_bf16 v[32:35], v[204:207], v[136:139], v[32:35]
	v_mfma_f32_16x16x32_bf16 v[40:43], v[204:207], v[140:143], v[40:43]
	ds_read_b128 v[204:207], v246 offset:14336
	s_waitcnt lgkmcnt(3)
	v_mfma_f32_16x16x32_bf16 v[100:103], v[242:245], v[128:131], v[100:103]
	v_mfma_f32_16x16x32_bf16 v[108:111], v[242:245], v[132:135], v[108:111]
	v_mfma_f32_16x16x32_bf16 v[36:39], v[242:245], v[136:139], v[36:39]
	v_mfma_f32_16x16x32_bf16 v[44:47], v[242:245], v[140:143], v[44:47]
	ds_read_b128 v[242:245], v162 offset:14336
	s_waitcnt lgkmcnt(3)
	v_mfma_f32_16x16x32_bf16 v[80:83], v[196:199], v[128:131], v[80:83]
	v_mfma_f32_16x16x32_bf16 v[88:91], v[196:199], v[132:135], v[88:91]
	v_mfma_f32_16x16x32_bf16 v[16:19], v[196:199], v[136:139], v[16:19]
	v_mfma_f32_16x16x32_bf16 v[24:27], v[196:199], v[140:143], v[24:27]
	s_waitcnt lgkmcnt(2)
	v_mfma_f32_16x16x32_bf16 v[84:87], v[200:203], v[128:131], v[84:87]
	v_mfma_f32_16x16x32_bf16 v[92:95], v[200:203], v[132:135], v[92:95]
	v_mfma_f32_16x16x32_bf16 v[20:23], v[200:203], v[136:139], v[20:23]
	v_mfma_f32_16x16x32_bf16 v[28:31], v[200:203], v[140:143], v[28:31]
	s_waitcnt lgkmcnt(1)
	v_mfma_f32_16x16x32_bf16 v[64:67], v[204:207], v[128:131], v[64:67]
	v_mfma_f32_16x16x32_bf16 v[72:75], v[204:207], v[132:135], v[72:75]
	v_mfma_f32_16x16x32_bf16 v[0:3], v[204:207], v[136:139], v[0:3]
	v_mfma_f32_16x16x32_bf16 v[8:11], v[204:207], v[140:143], v[8:11]
	s_waitcnt lgkmcnt(0)
	v_mfma_f32_16x16x32_bf16 v[68:71], v[242:245], v[128:131], v[68:71]
	v_mfma_f32_16x16x32_bf16 v[76:79], v[242:245], v[132:135], v[76:79]
	v_mfma_f32_16x16x32_bf16 v[4:7], v[242:245], v[136:139], v[4:7]
	v_mfma_f32_16x16x32_bf16 v[12:15], v[242:245], v[140:143], v[12:15]
	global_load_dwordx4 v[128:131], v[248:249], off
	global_load_dwordx4 v[132:135], v[248:249], off offset:256
	global_load_dwordx4 v[136:139], v[250:251], off
	global_load_dwordx4 v[140:143], v[250:251], off offset:256
	s_waitcnt vmcnt(10)
	s_barrier
	s_add_i32 s9, s3, 7
	s_lshl_b32 s96, s9, 13
	s_add_i32 m0, vcc_lo, 8192
	v_lshl_add_u64 v[160:161], v[188:189], 0, s[96:97]
	global_load_lds_dwordx4 v[160:161], off
	global_load_lds_dwordx4 v[160:161], off offset:1024
	ds_read_b128 v[196:199], v246 offset:16384
	ds_read_b128 v[200:203], v162 offset:16384
	ds_read_b128 v[204:207], v246 offset:18432
	ds_read_b128 v[242:245], v162 offset:18432
	s_add_i32 s9, s3, 7
	s_lshl_b32 s96, s9, 11
	v_lshl_add_u64 v[248:249], v[184:185], 0, s[96:97]
	v_lshl_add_u64 v[250:251], v[186:187], 0, s[96:97]
	s_waitcnt vmcnt(8) lgkmcnt(3)
	v_mfma_f32_16x16x32_bf16 v[112:115], v[196:199], v[144:147], v[112:115]
	v_mfma_f32_16x16x32_bf16 v[120:123], v[196:199], v[148:151], v[120:123]
	v_mfma_f32_16x16x32_bf16 v[48:51], v[196:199], v[152:155], v[48:51]
	v_mfma_f32_16x16x32_bf16 v[56:59], v[196:199], v[156:159], v[56:59]
	ds_read_b128 v[196:199], v246 offset:20480
	s_waitcnt lgkmcnt(3)
	v_mfma_f32_16x16x32_bf16 v[116:119], v[200:203], v[144:147], v[116:119]
	v_mfma_f32_16x16x32_bf16 v[124:127], v[200:203], v[148:151], v[124:127]
	v_mfma_f32_16x16x32_bf16 v[52:55], v[200:203], v[152:155], v[52:55]
	v_mfma_f32_16x16x32_bf16 v[60:63], v[200:203], v[156:159], v[60:63]
	ds_read_b128 v[200:203], v162 offset:20480
	s_waitcnt lgkmcnt(3)
	v_mfma_f32_16x16x32_bf16 v[96:99], v[204:207], v[144:147], v[96:99]
	v_mfma_f32_16x16x32_bf16 v[104:107], v[204:207], v[148:151], v[104:107]
	v_mfma_f32_16x16x32_bf16 v[32:35], v[204:207], v[152:155], v[32:35]
	v_mfma_f32_16x16x32_bf16 v[40:43], v[204:207], v[156:159], v[40:43]
	ds_read_b128 v[204:207], v246 offset:22528
	s_waitcnt lgkmcnt(3)
	v_mfma_f32_16x16x32_bf16 v[100:103], v[242:245], v[144:147], v[100:103]
	v_mfma_f32_16x16x32_bf16 v[108:111], v[242:245], v[148:151], v[108:111]
	v_mfma_f32_16x16x32_bf16 v[36:39], v[242:245], v[152:155], v[36:39]
	v_mfma_f32_16x16x32_bf16 v[44:47], v[242:245], v[156:159], v[44:47]
	ds_read_b128 v[242:245], v162 offset:22528
	s_waitcnt lgkmcnt(3)
	v_mfma_f32_16x16x32_bf16 v[80:83], v[196:199], v[144:147], v[80:83]
	v_mfma_f32_16x16x32_bf16 v[88:91], v[196:199], v[148:151], v[88:91]
	v_mfma_f32_16x16x32_bf16 v[16:19], v[196:199], v[152:155], v[16:19]
	v_mfma_f32_16x16x32_bf16 v[24:27], v[196:199], v[156:159], v[24:27]
	s_waitcnt lgkmcnt(2)
	v_mfma_f32_16x16x32_bf16 v[84:87], v[200:203], v[144:147], v[84:87]
	v_mfma_f32_16x16x32_bf16 v[92:95], v[200:203], v[148:151], v[92:95]
	v_mfma_f32_16x16x32_bf16 v[20:23], v[200:203], v[152:155], v[20:23]
	v_mfma_f32_16x16x32_bf16 v[28:31], v[200:203], v[156:159], v[28:31]
	s_waitcnt lgkmcnt(1)
	v_mfma_f32_16x16x32_bf16 v[64:67], v[204:207], v[144:147], v[64:67]
	v_mfma_f32_16x16x32_bf16 v[72:75], v[204:207], v[148:151], v[72:75]
	v_mfma_f32_16x16x32_bf16 v[0:3], v[204:207], v[152:155], v[0:3]
	v_mfma_f32_16x16x32_bf16 v[8:11], v[204:207], v[156:159], v[8:11]
	s_waitcnt lgkmcnt(0)
	v_mfma_f32_16x16x32_bf16 v[68:71], v[242:245], v[144:147], v[68:71]
	v_mfma_f32_16x16x32_bf16 v[76:79], v[242:245], v[148:151], v[76:79]
	v_mfma_f32_16x16x32_bf16 v[4:7], v[242:245], v[152:155], v[4:7]
	v_mfma_f32_16x16x32_bf16 v[12:15], v[242:245], v[156:159], v[12:15]
	global_load_dwordx4 v[144:147], v[248:249], off
	global_load_dwordx4 v[148:151], v[248:249], off offset:256
	global_load_dwordx4 v[152:155], v[250:251], off
	global_load_dwordx4 v[156:159], v[250:251], off offset:256
	s_waitcnt vmcnt(10)
	s_barrier
	s_add_i32 s3, s3, 6
	s_cmp_lt_u32 s3, 30
	s_cbranch_scc1 .Lg16_out_k
	ds_read_b128 v[196:199], v246 offset:0
	ds_read_b128 v[200:203], v162 offset:0
	ds_read_b128 v[204:207], v246 offset:2048
	ds_read_b128 v[242:245], v162 offset:2048
	s_waitcnt vmcnt(6) lgkmcnt(3)
	v_mfma_f32_16x16x32_bf16 v[112:115], v[196:199], v[128:131], v[112:115]
	v_mfma_f32_16x16x32_bf16 v[120:123], v[196:199], v[132:135], v[120:123]
	v_mfma_f32_16x16x32_bf16 v[48:51], v[196:199], v[136:139], v[48:51]
	v_mfma_f32_16x16x32_bf16 v[56:59], v[196:199], v[140:143], v[56:59]
	ds_read_b128 v[196:199], v246 offset:4096
	s_waitcnt lgkmcnt(3)
	v_mfma_f32_16x16x32_bf16 v[116:119], v[200:203], v[128:131], v[116:119]
	v_mfma_f32_16x16x32_bf16 v[124:127], v[200:203], v[132:135], v[124:127]
	v_mfma_f32_16x16x32_bf16 v[52:55], v[200:203], v[136:139], v[52:55]
	v_mfma_f32_16x16x32_bf16 v[60:63], v[200:203], v[140:143], v[60:63]
	ds_read_b128 v[200:203], v162 offset:4096
	s_waitcnt lgkmcnt(3)
	v_mfma_f32_16x16x32_bf16 v[96:99], v[204:207], v[128:131], v[96:99]
	v_mfma_f32_16x16x32_bf16 v[104:107], v[204:207], v[132:135], v[104:107]
	v_mfma_f32_16x16x32_bf16 v[32:35], v[204:207], v[136:139], v[32:35]
	v_mfma_f32_16x16x32_bf16 v[40:43], v[204:207], v[140:143], v[40:43]
	ds_read_b128 v[204:207], v246 offset:6144
	s_waitcnt lgkmcnt(3)
	v_mfma_f32_16x16x32_bf16 v[100:103], v[242:245], v[128:131], v[100:103]
	v_mfma_f32_16x16x32_bf16 v[108:111], v[242:245], v[132:135], v[108:111]
	v_mfma_f32_16x16x32_bf16 v[36:39], v[242:245], v[136:139], v[36:39]
	v_mfma_f32_16x16x32_bf16 v[44:47], v[242:245], v[140:143], v[44:47]
	ds_read_b128 v[242:245], v162 offset:6144
	s_waitcnt lgkmcnt(3)
	v_mfma_f32_16x16x32_bf16 v[80:83], v[196:199], v[128:131], v[80:83]
	v_mfma_f32_16x16x32_bf16 v[88:91], v[196:199], v[132:135], v[88:91]
	v_mfma_f32_16x16x32_bf16 v[16:19], v[196:199], v[136:139], v[16:19]
	v_mfma_f32_16x16x32_bf16 v[24:27], v[196:199], v[140:143], v[24:27]
	s_waitcnt lgkmcnt(2)
	v_mfma_f32_16x16x32_bf16 v[84:87], v[200:203], v[128:131], v[84:87]
	v_mfma_f32_16x16x32_bf16 v[92:95], v[200:203], v[132:135], v[92:95]
	v_mfma_f32_16x16x32_bf16 v[20:23], v[200:203], v[136:139], v[20:23]
	v_mfma_f32_16x16x32_bf16 v[28:31], v[200:203], v[140:143], v[28:31]
	s_waitcnt lgkmcnt(1)
	v_mfma_f32_16x16x32_bf16 v[64:67], v[204:207], v[128:131], v[64:67]
	v_mfma_f32_16x16x32_bf16 v[72:75], v[204:207], v[132:135], v[72:75]
	v_mfma_f32_16x16x32_bf16 v[0:3], v[204:207], v[136:139], v[0:3]
	v_mfma_f32_16x16x32_bf16 v[8:11], v[204:207], v[140:143], v[8:11]
	s_waitcnt lgkmcnt(0)
	v_mfma_f32_16x16x32_bf16 v[68:71], v[242:245], v[128:131], v[68:71]
	v_mfma_f32_16x16x32_bf16 v[76:79], v[242:245], v[132:135], v[76:79]
	v_mfma_f32_16x16x32_bf16 v[4:7], v[242:245], v[136:139], v[4:7]
	v_mfma_f32_16x16x32_bf16 v[12:15], v[242:245], v[140:143], v[12:15]
	s_waitcnt vmcnt(4)
	s_barrier
	ds_read_b128 v[196:199], v246 offset:8192
	ds_read_b128 v[200:203], v162 offset:8192
	ds_read_b128 v[204:207], v246 offset:10240
	ds_read_b128 v[242:245], v162 offset:10240
	s_waitcnt vmcnt(0) lgkmcnt(3)
	v_mfma_f32_16x16x32_bf16 v[112:115], v[196:199], v[144:147], v[112:115]
	v_mfma_f32_16x16x32_bf16 v[120:123], v[196:199], v[148:151], v[120:123]
	v_mfma_f32_16x16x32_bf16 v[48:51], v[196:199], v[152:155], v[48:51]
	v_mfma_f32_16x16x32_bf16 v[56:59], v[196:199], v[156:159], v[56:59]
	ds_read_b128 v[196:199], v246 offset:12288
	s_waitcnt lgkmcnt(3)
	v_mfma_f32_16x16x32_bf16 v[116:119], v[200:203], v[144:147], v[116:119]
	v_mfma_f32_16x16x32_bf16 v[124:127], v[200:203], v[148:151], v[124:127]
	v_mfma_f32_16x16x32_bf16 v[52:55], v[200:203], v[152:155], v[52:55]
	v_mfma_f32_16x16x32_bf16 v[60:63], v[200:203], v[156:159], v[60:63]
	ds_read_b128 v[200:203], v162 offset:12288
	s_waitcnt lgkmcnt(3)
	v_mfma_f32_16x16x32_bf16 v[96:99], v[204:207], v[144:147], v[96:99]
	v_mfma_f32_16x16x32_bf16 v[104:107], v[204:207], v[148:151], v[104:107]
	v_mfma_f32_16x16x32_bf16 v[32:35], v[204:207], v[152:155], v[32:35]
	v_mfma_f32_16x16x32_bf16 v[40:43], v[204:207], v[156:159], v[40:43]
	ds_read_b128 v[204:207], v246 offset:14336
	s_waitcnt lgkmcnt(3)
	v_mfma_f32_16x16x32_bf16 v[100:103], v[242:245], v[144:147], v[100:103]
	v_mfma_f32_16x16x32_bf16 v[108:111], v[242:245], v[148:151], v[108:111]
	v_mfma_f32_16x16x32_bf16 v[36:39], v[242:245], v[152:155], v[36:39]
	v_mfma_f32_16x16x32_bf16 v[44:47], v[242:245], v[156:159], v[44:47]
	ds_read_b128 v[242:245], v162 offset:14336
	s_waitcnt lgkmcnt(3)
	v_mfma_f32_16x16x32_bf16 v[80:83], v[196:199], v[144:147], v[80:83]
	v_mfma_f32_16x16x32_bf16 v[88:91], v[196:199], v[148:151], v[88:91]
	v_mfma_f32_16x16x32_bf16 v[16:19], v[196:199], v[152:155], v[16:19]
	v_mfma_f32_16x16x32_bf16 v[24:27], v[196:199], v[156:159], v[24:27]
	s_waitcnt lgkmcnt(2)
	v_mfma_f32_16x16x32_bf16 v[84:87], v[200:203], v[144:147], v[84:87]
	v_mfma_f32_16x16x32_bf16 v[92:95], v[200:203], v[148:151], v[92:95]
	v_mfma_f32_16x16x32_bf16 v[20:23], v[200:203], v[152:155], v[20:23]
	v_mfma_f32_16x16x32_bf16 v[28:31], v[200:203], v[156:159], v[28:31]
	s_waitcnt lgkmcnt(1)
	v_mfma_f32_16x16x32_bf16 v[64:67], v[204:207], v[144:147], v[64:67]
	v_mfma_f32_16x16x32_bf16 v[72:75], v[204:207], v[148:151], v[72:75]
	v_mfma_f32_16x16x32_bf16 v[0:3], v[204:207], v[152:155], v[0:3]
	v_mfma_f32_16x16x32_bf16 v[8:11], v[204:207], v[156:159], v[8:11]
	s_waitcnt lgkmcnt(0)
	v_mfma_f32_16x16x32_bf16 v[68:71], v[242:245], v[144:147], v[68:71]
	v_mfma_f32_16x16x32_bf16 v[76:79], v[242:245], v[148:151], v[76:79]
	v_mfma_f32_16x16x32_bf16 v[4:7], v[242:245], v[152:155], v[4:7]
	v_mfma_f32_16x16x32_bf16 v[12:15], v[242:245], v[156:159], v[12:15]
	s_barrier
	s_nop 7
	s_nop 1
	s_waitcnt vmcnt(0)
	s_waitcnt vmcnt(0)
	v_and_b32_e32 v188, 63, v179
	v_lshrrev_b32_e32 v189, 6, v179
	v_mul_u32_u24_e32 v249, 0x2400, v189
	v_mov_b32_e32 v250, v249
	v_and_b32_e32 v251, 15, v188
	v_mul_u32_u24_e32 v251, 0x110, v251
	v_add_u32_e32 v249, v249, v251
	v_lshrrev_b32_e32 v251, 4, v188
	v_lshl_add_u32 v249, v251, 5, v249
	v_lshrrev_b32_e32 v237, 4, v188
	v_mul_u32_u24_e32 v251, 0x110, v237
	v_add_u32_e32 v250, v250, v251
	v_and_b32_e32 v251, 15, v188
	v_lshlrev_b32_e32 v251, 4, v251
	v_add_u32_e32 v250, v250, v251
	v_lshl_add_u32 v237, v189, 6, v237
	v_lshl_add_u32 v237, v237, 12, v251
	v_add_u32_e32 v238, 16384, v237
	v_add_u32_e32 v239, 32768, v237
	v_add_u32_e32 v240, 49152, v237
	v_add_u32_e32 v241, 65536, v237
	v_add_u32_e32 v242, 81920, v237
	v_add_u32_e32 v243, 98304, v237
	v_add_u32_e32 v248, 114688, v237
	s_lshl_b32 s16, s8, 8
	s_lshl_b32 s18, s2, 9
	s_lshr_b32 s19, s8, 4
	v_readlane_b32 s12, v254, 38
	v_readlane_b32 s13, v254, 37
	v_readlane_b32 s14, v253, 46
	v_readlane_b32 s15, v253, 47
	v_readlane_b32 s22, v254, 40
	v_readlane_b32 s23, v254, 39
	s_add_i32 s17, s16, 0xffff8000
	s_cmpk_lt_u32 s8, 0x80
	s_cselect_b32 s12, s12, s22
	s_cselect_b32 s13, s13, s23
	s_cselect_b32 s14, s14, s62
	s_cselect_b32 s15, s15, s63
	s_cselect_b32 s19, s19, 8
	s_cselect_b32 s16, s16, s17
	s_mov_b32 s17, 0
	s_lshl_b64 s[16:17], s[16:17], 12
	s_add_u32 s16, s16, s18
	s_addc_u32 s17, s17, 0
	s_add_u32 s12, s12, s16
	s_addc_u32 s13, s13, s17
	s_add_u32 s14, s14, s16
	s_addc_u32 s15, s15, s17
	s_mul_i32 s19, s19, 0x6000
	s_add_u32 s20, s0, s19
	s_addc_u32 s21, s1, 0
	s_add_u32 s20, s20, s18
	s_addc_u32 s21, s21, 0
	global_load_dwordx4 v[244:247], v251, s[20:21]
	global_load_dwordx4 v[160:163], v237, s[12:13]
	global_load_dwordx4 v[164:167], v238, s[12:13]
	global_load_dwordx4 v[168:171], v239, s[12:13]
	global_load_dwordx4 v[172:175], v240, s[12:13]
	global_load_dwordx4 v[196:199], v241, s[12:13]
	global_load_dwordx4 v[200:203], v242, s[12:13]
	global_load_dwordx4 v[204:207], v243, s[12:13]
	global_load_dwordx4 v[184:187], v248, s[12:13]
	ds_write_b128 v249, v[112:115]
	ds_write_b128 v249, v[116:119] offset:16
	ds_write_b128 v249, v[96:99] offset:128
	ds_write_b128 v249, v[100:103] offset:144
	ds_write_b128 v249, v[120:123] offset:4352
	ds_write_b128 v249, v[124:127] offset:4368
	ds_write_b128 v249, v[104:107] offset:4480
	ds_write_b128 v249, v[108:111] offset:4496
	s_waitcnt lgkmcnt(0)
	ds_read_b128 v[128:131], v250
	ds_read_b128 v[132:135], v250 offset:1088
	ds_read_b128 v[136:139], v250 offset:2176
	ds_read_b128 v[140:143], v250 offset:3264
	ds_read_b128 v[144:147], v250 offset:4352
	ds_read_b128 v[148:151], v250 offset:5440
	ds_read_b128 v[152:155], v250 offset:6528
	ds_read_b128 v[156:159], v250 offset:7616
	s_waitcnt vmcnt(7) lgkmcnt(7)
	v_fma_f32 v128, v244, v128, v160
	v_fma_f32 v129, v245, v129, v161
	v_fma_f32 v130, v246, v130, v162
	v_fma_f32 v131, v247, v131, v163
	global_store_dwordx4 v237, v[128:131], s[14:15]
	s_waitcnt vmcnt(7) lgkmcnt(6)
	v_fma_f32 v132, v244, v132, v164
	v_fma_f32 v133, v245, v133, v165
	v_fma_f32 v134, v246, v134, v166
	v_fma_f32 v135, v247, v135, v167
	global_store_dwordx4 v238, v[132:135], s[14:15]
	s_waitcnt vmcnt(7) lgkmcnt(5)
	v_fma_f32 v136, v244, v136, v168
	v_fma_f32 v137, v245, v137, v169
	v_fma_f32 v138, v246, v138, v170
	v_fma_f32 v139, v247, v139, v171
	global_store_dwordx4 v239, v[136:139], s[14:15]
	s_waitcnt vmcnt(7) lgkmcnt(4)
	v_fma_f32 v140, v244, v140, v172
	v_fma_f32 v141, v245, v141, v173
	v_fma_f32 v142, v246, v142, v174
	v_fma_f32 v143, v247, v143, v175
	global_store_dwordx4 v240, v[140:143], s[14:15]
	s_waitcnt vmcnt(7) lgkmcnt(3)
	v_fma_f32 v144, v244, v144, v196
	v_fma_f32 v145, v245, v145, v197
	v_fma_f32 v146, v246, v146, v198
	v_fma_f32 v147, v247, v147, v199
	global_store_dwordx4 v241, v[144:147], s[14:15]
	s_waitcnt vmcnt(7) lgkmcnt(2)
	v_fma_f32 v148, v244, v148, v200
	v_fma_f32 v149, v245, v149, v201
	v_fma_f32 v150, v246, v150, v202
	v_fma_f32 v151, v247, v151, v203
	global_store_dwordx4 v242, v[148:151], s[14:15]
	s_waitcnt vmcnt(7) lgkmcnt(1)
	v_fma_f32 v152, v244, v152, v204
	v_fma_f32 v153, v245, v153, v205
	v_fma_f32 v154, v246, v154, v206
	v_fma_f32 v155, v247, v155, v207
	global_store_dwordx4 v243, v[152:155], s[14:15]
	s_waitcnt vmcnt(7) lgkmcnt(0)
	v_fma_f32 v156, v244, v156, v184
	v_fma_f32 v157, v245, v157, v185
	v_fma_f32 v158, v246, v158, v186
	v_fma_f32 v159, v247, v159, v187
	global_store_dwordx4 v248, v[156:159], s[14:15]
	global_load_dwordx4 v[244:247], v251, s[20:21] offset:256
	global_load_dwordx4 v[160:163], v237, s[12:13] offset:256
	global_load_dwordx4 v[164:167], v238, s[12:13] offset:256
	global_load_dwordx4 v[168:171], v239, s[12:13] offset:256
	global_load_dwordx4 v[172:175], v240, s[12:13] offset:256
	global_load_dwordx4 v[196:199], v241, s[12:13] offset:256
	global_load_dwordx4 v[200:203], v242, s[12:13] offset:256
	global_load_dwordx4 v[204:207], v243, s[12:13] offset:256
	global_load_dwordx4 v[184:187], v248, s[12:13] offset:256
	ds_write_b128 v249, v[80:83]
	ds_write_b128 v249, v[84:87] offset:16
	ds_write_b128 v249, v[64:67] offset:128
	ds_write_b128 v249, v[68:71] offset:144
	ds_write_b128 v249, v[88:91] offset:4352
	ds_write_b128 v249, v[92:95] offset:4368
	ds_write_b128 v249, v[72:75] offset:4480
	ds_write_b128 v249, v[76:79] offset:4496
	s_waitcnt lgkmcnt(0)
	ds_read_b128 v[128:131], v250
	ds_read_b128 v[132:135], v250 offset:1088
	ds_read_b128 v[136:139], v250 offset:2176
	ds_read_b128 v[140:143], v250 offset:3264
	ds_read_b128 v[144:147], v250 offset:4352
	ds_read_b128 v[148:151], v250 offset:5440
	ds_read_b128 v[152:155], v250 offset:6528
	ds_read_b128 v[156:159], v250 offset:7616
	s_waitcnt vmcnt(7) lgkmcnt(7)
	v_fma_f32 v128, v244, v128, v160
	v_fma_f32 v129, v245, v129, v161
	v_fma_f32 v130, v246, v130, v162
	v_fma_f32 v131, v247, v131, v163
	global_store_dwordx4 v237, v[128:131], s[14:15] offset:256
	s_waitcnt vmcnt(7) lgkmcnt(6)
	v_fma_f32 v132, v244, v132, v164
	v_fma_f32 v133, v245, v133, v165
	v_fma_f32 v134, v246, v134, v166
	v_fma_f32 v135, v247, v135, v167
	global_store_dwordx4 v238, v[132:135], s[14:15] offset:256
	s_waitcnt vmcnt(7) lgkmcnt(5)
	v_fma_f32 v136, v244, v136, v168
	v_fma_f32 v137, v245, v137, v169
	v_fma_f32 v138, v246, v138, v170
	v_fma_f32 v139, v247, v139, v171
	global_store_dwordx4 v239, v[136:139], s[14:15] offset:256
	s_waitcnt vmcnt(7) lgkmcnt(4)
	v_fma_f32 v140, v244, v140, v172
	v_fma_f32 v141, v245, v141, v173
	v_fma_f32 v142, v246, v142, v174
	v_fma_f32 v143, v247, v143, v175
	global_store_dwordx4 v240, v[140:143], s[14:15] offset:256
	s_waitcnt vmcnt(7) lgkmcnt(3)
	v_fma_f32 v144, v244, v144, v196
	v_fma_f32 v145, v245, v145, v197
	v_fma_f32 v146, v246, v146, v198
	v_fma_f32 v147, v247, v147, v199
	global_store_dwordx4 v241, v[144:147], s[14:15] offset:256
	s_waitcnt vmcnt(7) lgkmcnt(2)
	v_fma_f32 v148, v244, v148, v200
	v_fma_f32 v149, v245, v149, v201
	v_fma_f32 v150, v246, v150, v202
	v_fma_f32 v151, v247, v151, v203
	global_store_dwordx4 v242, v[148:151], s[14:15] offset:256
	s_waitcnt vmcnt(7) lgkmcnt(1)
	v_fma_f32 v152, v244, v152, v204
	v_fma_f32 v153, v245, v153, v205
	v_fma_f32 v154, v246, v154, v206
	v_fma_f32 v155, v247, v155, v207
	global_store_dwordx4 v243, v[152:155], s[14:15] offset:256
	s_waitcnt vmcnt(7) lgkmcnt(0)
	v_fma_f32 v156, v244, v156, v184
	v_fma_f32 v157, v245, v157, v185
	v_fma_f32 v158, v246, v158, v186
	v_fma_f32 v159, v247, v159, v187
	global_store_dwordx4 v248, v[156:159], s[14:15] offset:256
	s_add_u32 s12, s12, 0x20000
	s_addc_u32 s13, s13, 0
	s_add_u32 s14, s14, 0x20000
	s_addc_u32 s15, s15, 0
	global_load_dwordx4 v[244:247], v251, s[20:21]
	global_load_dwordx4 v[160:163], v237, s[12:13]
	global_load_dwordx4 v[164:167], v238, s[12:13]
	global_load_dwordx4 v[168:171], v239, s[12:13]
	global_load_dwordx4 v[172:175], v240, s[12:13]
	global_load_dwordx4 v[196:199], v241, s[12:13]
	global_load_dwordx4 v[200:203], v242, s[12:13]
	global_load_dwordx4 v[204:207], v243, s[12:13]
	global_load_dwordx4 v[184:187], v248, s[12:13]
	ds_write_b128 v249, v[48:51]
	ds_write_b128 v249, v[52:55] offset:16
	ds_write_b128 v249, v[32:35] offset:128
	ds_write_b128 v249, v[36:39] offset:144
	ds_write_b128 v249, v[56:59] offset:4352
	ds_write_b128 v249, v[60:63] offset:4368
	ds_write_b128 v249, v[40:43] offset:4480
	ds_write_b128 v249, v[44:47] offset:4496
	s_waitcnt lgkmcnt(0)
	ds_read_b128 v[128:131], v250
	ds_read_b128 v[132:135], v250 offset:1088
	ds_read_b128 v[136:139], v250 offset:2176
	ds_read_b128 v[140:143], v250 offset:3264
	ds_read_b128 v[144:147], v250 offset:4352
	ds_read_b128 v[148:151], v250 offset:5440
	ds_read_b128 v[152:155], v250 offset:6528
	ds_read_b128 v[156:159], v250 offset:7616
	s_waitcnt vmcnt(7) lgkmcnt(7)
	v_fma_f32 v128, v244, v128, v160
	v_fma_f32 v129, v245, v129, v161
	v_fma_f32 v130, v246, v130, v162
	v_fma_f32 v131, v247, v131, v163
	global_store_dwordx4 v237, v[128:131], s[14:15]
	s_waitcnt vmcnt(7) lgkmcnt(6)
	v_fma_f32 v132, v244, v132, v164
	v_fma_f32 v133, v245, v133, v165
	v_fma_f32 v134, v246, v134, v166
	v_fma_f32 v135, v247, v135, v167
	global_store_dwordx4 v238, v[132:135], s[14:15]
	s_waitcnt vmcnt(7) lgkmcnt(5)
	v_fma_f32 v136, v244, v136, v168
	v_fma_f32 v137, v245, v137, v169
	v_fma_f32 v138, v246, v138, v170
	v_fma_f32 v139, v247, v139, v171
	global_store_dwordx4 v239, v[136:139], s[14:15]
	s_waitcnt vmcnt(7) lgkmcnt(4)
	v_fma_f32 v140, v244, v140, v172
	v_fma_f32 v141, v245, v141, v173
	v_fma_f32 v142, v246, v142, v174
	v_fma_f32 v143, v247, v143, v175
	global_store_dwordx4 v240, v[140:143], s[14:15]
	s_waitcnt vmcnt(7) lgkmcnt(3)
	v_fma_f32 v144, v244, v144, v196
	v_fma_f32 v145, v245, v145, v197
	v_fma_f32 v146, v246, v146, v198
	v_fma_f32 v147, v247, v147, v199
	global_store_dwordx4 v241, v[144:147], s[14:15]
	s_waitcnt vmcnt(7) lgkmcnt(2)
	v_fma_f32 v148, v244, v148, v200
	v_fma_f32 v149, v245, v149, v201
	v_fma_f32 v150, v246, v150, v202
	v_fma_f32 v151, v247, v151, v203
	global_store_dwordx4 v242, v[148:151], s[14:15]
	s_waitcnt vmcnt(7) lgkmcnt(1)
	v_fma_f32 v152, v244, v152, v204
	v_fma_f32 v153, v245, v153, v205
	v_fma_f32 v154, v246, v154, v206
	v_fma_f32 v155, v247, v155, v207
	global_store_dwordx4 v243, v[152:155], s[14:15]
	s_waitcnt vmcnt(7) lgkmcnt(0)
	v_fma_f32 v156, v244, v156, v184
	v_fma_f32 v157, v245, v157, v185
	v_fma_f32 v158, v246, v158, v186
	v_fma_f32 v159, v247, v159, v187
	global_store_dwordx4 v248, v[156:159], s[14:15]
	global_load_dwordx4 v[244:247], v251, s[20:21] offset:256
	global_load_dwordx4 v[160:163], v237, s[12:13] offset:256
	global_load_dwordx4 v[164:167], v238, s[12:13] offset:256
	global_load_dwordx4 v[168:171], v239, s[12:13] offset:256
	global_load_dwordx4 v[172:175], v240, s[12:13] offset:256
	global_load_dwordx4 v[196:199], v241, s[12:13] offset:256
	global_load_dwordx4 v[200:203], v242, s[12:13] offset:256
	global_load_dwordx4 v[204:207], v243, s[12:13] offset:256
	global_load_dwordx4 v[184:187], v248, s[12:13] offset:256
	ds_write_b128 v249, v[16:19]
	ds_write_b128 v249, v[20:23] offset:16
	ds_write_b128 v249, v[0:3] offset:128
	ds_write_b128 v249, v[4:7] offset:144
	ds_write_b128 v249, v[24:27] offset:4352
	ds_write_b128 v249, v[28:31] offset:4368
	ds_write_b128 v249, v[8:11] offset:4480
	ds_write_b128 v249, v[12:15] offset:4496
	s_waitcnt lgkmcnt(0)
	ds_read_b128 v[128:131], v250
	ds_read_b128 v[132:135], v250 offset:1088
	ds_read_b128 v[136:139], v250 offset:2176
	ds_read_b128 v[140:143], v250 offset:3264
	ds_read_b128 v[144:147], v250 offset:4352
	ds_read_b128 v[148:151], v250 offset:5440
	ds_read_b128 v[152:155], v250 offset:6528
	ds_read_b128 v[156:159], v250 offset:7616
	s_waitcnt vmcnt(7) lgkmcnt(7)
	v_fma_f32 v128, v244, v128, v160
	v_fma_f32 v129, v245, v129, v161
	v_fma_f32 v130, v246, v130, v162
	v_fma_f32 v131, v247, v131, v163
	global_store_dwordx4 v237, v[128:131], s[14:15] offset:256
	s_waitcnt vmcnt(7) lgkmcnt(6)
	v_fma_f32 v132, v244, v132, v164
	v_fma_f32 v133, v245, v133, v165
	v_fma_f32 v134, v246, v134, v166
	v_fma_f32 v135, v247, v135, v167
	global_store_dwordx4 v238, v[132:135], s[14:15] offset:256
	s_waitcnt vmcnt(7) lgkmcnt(5)
	v_fma_f32 v136, v244, v136, v168
	v_fma_f32 v137, v245, v137, v169
	v_fma_f32 v138, v246, v138, v170
	v_fma_f32 v139, v247, v139, v171
	global_store_dwordx4 v239, v[136:139], s[14:15] offset:256
	s_waitcnt vmcnt(7) lgkmcnt(4)
	v_fma_f32 v140, v244, v140, v172
	v_fma_f32 v141, v245, v141, v173
	v_fma_f32 v142, v246, v142, v174
	v_fma_f32 v143, v247, v143, v175
	global_store_dwordx4 v240, v[140:143], s[14:15] offset:256
	s_waitcnt vmcnt(7) lgkmcnt(3)
	v_fma_f32 v144, v244, v144, v196
	v_fma_f32 v145, v245, v145, v197
	v_fma_f32 v146, v246, v146, v198
	v_fma_f32 v147, v247, v147, v199
	global_store_dwordx4 v241, v[144:147], s[14:15] offset:256
	s_waitcnt vmcnt(7) lgkmcnt(2)
	v_fma_f32 v148, v244, v148, v200
	v_fma_f32 v149, v245, v149, v201
	v_fma_f32 v150, v246, v150, v202
	v_fma_f32 v151, v247, v151, v203
	global_store_dwordx4 v242, v[148:151], s[14:15] offset:256
	s_waitcnt vmcnt(7) lgkmcnt(1)
	v_fma_f32 v152, v244, v152, v204
	v_fma_f32 v153, v245, v153, v205
	v_fma_f32 v154, v246, v154, v206
	v_fma_f32 v155, v247, v155, v207
	global_store_dwordx4 v243, v[152:155], s[14:15] offset:256
	s_waitcnt vmcnt(7) lgkmcnt(0)
	v_fma_f32 v156, v244, v156, v184
	v_fma_f32 v157, v245, v157, v185
	v_fma_f32 v158, v246, v158, v186
	v_fma_f32 v159, v247, v159, v187
	global_store_dwordx4 v248, v[156:159], s[14:15] offset:256
	s_waitcnt lgkmcnt(0)
	v_readlane_b32 s16, v254, 11
	s_andn2_b32 s17, s26, 63
	s_add_i32 s4, s4, s16
	s_cmp_lt_i32 s4, s17
	s_cbranch_scc0 .Lhx_out_left
	s_barrier
	s_branch .LBB0_923

.Lhx_out_half:
	v_bfe_u32 v247, v181, 4, 2
	v_lshlrev_b32_e32 v247, 1, v247
	v_mov_b32_e32 v176, 0x78
	v_lshrrev_b32_e32 v247, v247, v176
	v_and_b32_e32 v247, 3, v247
	v_and_b32_e32 v246, 3, v181
	v_xor_b32_e32 v247, v247, v246
	v_lshlrev_b32_e32 v247, 4, v247
	v_and_b32_e32 v188, 0xffffffcf, v186
	v_or_b32_e32 v188, v188, v247
	v_mov_b32_e32 v189, v187
	v_lshrrev_b32_e32 v176, 6, v181
	v_lshlrev_b32_e32 v247, 11, v176
	v_lshlrev_b32_e32 v176, 10, v176
	v_lshl_add_u64 v[188:189], v[188:189], 0, v[176:177]
	v_readfirstlane_b32 vcc_lo, v247
	v_bfe_u32 v247, v181, 4, 1
	v_lshlrev_b32_e32 v176, 9, v183
	v_lshl_add_u32 v176, v247, 8, v176
	v_lshl_add_u64 v[184:185], v[184:185], 0, v[176:177]
	v_mov_b32_e32 v176, s41
	v_lshl_add_u64 v[186:187], v[184:185], 0, v[176:177]
	v_mov_b32_e32 v176, 0x78
	v_bfe_u32 v247, v181, 2, 1
	v_lshlrev_b32_e32 v247, 2, v247
	v_lshrrev_b32_e32 v247, v247, v176
	v_and_b32_e32 v247, 3, v247
	v_bfe_u32 v246, v181, 4, 2
	v_xor_b32_e32 v247, v247, v246
	v_lshlrev_b32_e32 v247, 4, v247
	v_bfe_u32 v246, v181, 2, 2
	v_lshlrev_b32_e32 v246, 3, v246
	v_and_b32_e32 v162, 3, v181
	v_add_u32_e32 v246, v246, v162
	v_lshl_add_u32 v246, v246, 6, v247
	v_bfe_u32 v247, v181, 2, 1
	v_lshlrev_b32_e32 v247, 2, v247
	v_add_u32_e32 v247, 2, v247
	v_lshrrev_b32_e32 v247, v247, v176
	v_and_b32_e32 v247, 3, v247
	v_bfe_u32 v162, v181, 4, 2
	v_xor_b32_e32 v247, v247, v162
	v_lshlrev_b32_e32 v247, 4, v247
	v_and_b32_e32 v162, 0xffffffcf, v246
	v_add_u32_e32 v162, 0x100, v162
	v_or_b32_e32 v162, v162, v247
	s_cmp_eq_u32 s101, 1
	s_cbranch_scc0 .Lg16_outh_a0
	v_mov_b32_e32 v184, v186
	v_mov_b32_e32 v185, v187

.Lg16_outh_k:
	s_add_i32 s9, s3, 2
	s_lshl_b32 s96, s9, 13
	s_add_i32 m0, vcc_lo, 16384
	v_lshl_add_u64 v[160:161], v[188:189], 0, s[96:97]
	global_load_lds_dwordx4 v[160:161], off
	global_load_lds_dwordx4 v[160:161], off offset:1024
	ds_read_b128 v[196:199], v246 offset:0
	ds_read_b128 v[200:203], v162 offset:0
	ds_read_b128 v[204:207], v246 offset:2048
	ds_read_b128 v[242:245], v162 offset:2048
	s_add_i32 s9, s3, 2
	s_lshl_b32 s96, s9, 11
	v_lshl_add_u64 v[248:249], v[184:185], 0, s[96:97]
	v_lshl_add_u64 v[250:251], v[186:187], 0, s[96:97]
	s_waitcnt vmcnt(6) lgkmcnt(3)
	v_mfma_f32_16x16x32_bf16 v[112:115], v[196:199], v[128:131], v[112:115]
	v_mfma_f32_16x16x32_bf16 v[120:123], v[196:199], v[132:135], v[120:123]
	ds_read_b128 v[196:199], v246 offset:4096
	s_waitcnt lgkmcnt(3)
	v_mfma_f32_16x16x32_bf16 v[116:119], v[200:203], v[128:131], v[116:119]
	v_mfma_f32_16x16x32_bf16 v[124:127], v[200:203], v[132:135], v[124:127]
	ds_read_b128 v[200:203], v162 offset:4096
	s_waitcnt lgkmcnt(3)
	v_mfma_f32_16x16x32_bf16 v[96:99], v[204:207], v[128:131], v[96:99]
	v_mfma_f32_16x16x32_bf16 v[104:107], v[204:207], v[132:135], v[104:107]
	ds_read_b128 v[204:207], v246 offset:6144
	s_waitcnt lgkmcnt(3)
	v_mfma_f32_16x16x32_bf16 v[100:103], v[242:245], v[128:131], v[100:103]
	v_mfma_f32_16x16x32_bf16 v[108:111], v[242:245], v[132:135], v[108:111]
	ds_read_b128 v[242:245], v162 offset:6144
	s_waitcnt lgkmcnt(3)
	v_mfma_f32_16x16x32_bf16 v[80:83], v[196:199], v[128:131], v[80:83]
	v_mfma_f32_16x16x32_bf16 v[88:91], v[196:199], v[132:135], v[88:91]
	s_waitcnt lgkmcnt(2)
	v_mfma_f32_16x16x32_bf16 v[84:87], v[200:203], v[128:131], v[84:87]
	v_mfma_f32_16x16x32_bf16 v[92:95], v[200:203], v[132:135], v[92:95]
	s_waitcnt lgkmcnt(1)
	v_mfma_f32_16x16x32_bf16 v[64:67], v[204:207], v[128:131], v[64:67]
	v_mfma_f32_16x16x32_bf16 v[72:75], v[204:207], v[132:135], v[72:75]
	s_waitcnt lgkmcnt(0)
	v_mfma_f32_16x16x32_bf16 v[68:71], v[242:245], v[128:131], v[68:71]
	v_mfma_f32_16x16x32_bf16 v[76:79], v[242:245], v[132:135], v[76:79]
	global_load_dwordx4 v[128:131], v[248:249], off
	global_load_dwordx4 v[132:135], v[248:249], off offset:256
	s_waitcnt vmcnt(6)
	s_barrier
	s_add_i32 s9, s3, 3
	s_lshl_b32 s96, s9, 13
	s_mov_b32 m0, vcc_lo
	v_lshl_add_u64 v[160:161], v[188:189], 0, s[96:97]
	global_load_lds_dwordx4 v[160:161], off
	global_load_lds_dwordx4 v[160:161], off offset:1024
	ds_read_b128 v[196:199], v246 offset:8192
	ds_read_b128 v[200:203], v162 offset:8192
	ds_read_b128 v[204:207], v246 offset:10240
	ds_read_b128 v[242:245], v162 offset:10240
	s_add_i32 s9, s3, 3
	s_lshl_b32 s96, s9, 11
	v_lshl_add_u64 v[248:249], v[184:185], 0, s[96:97]
	v_lshl_add_u64 v[250:251], v[186:187], 0, s[96:97]
	s_waitcnt vmcnt(6) lgkmcnt(3)
	v_mfma_f32_16x16x32_bf16 v[112:115], v[196:199], v[144:147], v[112:115]
	v_mfma_f32_16x16x32_bf16 v[120:123], v[196:199], v[148:151], v[120:123]
	ds_read_b128 v[196:199], v246 offset:12288
	s_waitcnt lgkmcnt(3)
	v_mfma_f32_16x16x32_bf16 v[116:119], v[200:203], v[144:147], v[116:119]
	v_mfma_f32_16x16x32_bf16 v[124:127], v[200:203], v[148:151], v[124:127]
	ds_read_b128 v[200:203], v162 offset:12288
	s_waitcnt lgkmcnt(3)
	v_mfma_f32_16x16x32_bf16 v[96:99], v[204:207], v[144:147], v[96:99]
	v_mfma_f32_16x16x32_bf16 v[104:107], v[204:207], v[148:151], v[104:107]
	ds_read_b128 v[204:207], v246 offset:14336
	s_waitcnt lgkmcnt(3)
	v_mfma_f32_16x16x32_bf16 v[100:103], v[242:245], v[144:147], v[100:103]
	v_mfma_f32_16x16x32_bf16 v[108:111], v[242:245], v[148:151], v[108:111]
	ds_read_b128 v[242:245], v162 offset:14336
	s_waitcnt lgkmcnt(3)
	v_mfma_f32_16x16x32_bf16 v[80:83], v[196:199], v[144:147], v[80:83]
	v_mfma_f32_16x16x32_bf16 v[88:91], v[196:199], v[148:151], v[88:91]
	s_waitcnt lgkmcnt(2)
	v_mfma_f32_16x16x32_bf16 v[84:87], v[200:203], v[144:147], v[84:87]
	v_mfma_f32_16x16x32_bf16 v[92:95], v[200:203], v[148:151], v[92:95]
	s_waitcnt lgkmcnt(1)
	v_mfma_f32_16x16x32_bf16 v[64:67], v[204:207], v[144:147], v[64:67]
	v_mfma_f32_16x16x32_bf16 v[72:75], v[204:207], v[148:151], v[72:75]
	s_waitcnt lgkmcnt(0)
	v_mfma_f32_16x16x32_bf16 v[68:71], v[242:245], v[144:147], v[68:71]
	v_mfma_f32_16x16x32_bf16 v[76:79], v[242:245], v[148:151], v[76:79]
	global_load_dwordx4 v[144:147], v[248:249], off
	global_load_dwordx4 v[148:151], v[248:249], off offset:256
	s_waitcnt vmcnt(6)
	s_barrier
	s_add_i32 s9, s3, 4
	s_lshl_b32 s96, s9, 13
	s_add_i32 m0, vcc_lo, 8192
	v_lshl_add_u64 v[160:161], v[188:189], 0, s[96:97]
	global_load_lds_dwordx4 v[160:161], off
	global_load_lds_dwordx4 v[160:161], off offset:1024
	ds_read_b128 v[196:199], v246 offset:16384
	ds_read_b128 v[200:203], v162 offset:16384
	ds_read_b128 v[204:207], v246 offset:18432
	ds_read_b128 v[242:245], v162 offset:18432
	s_add_i32 s9, s3, 4
	s_lshl_b32 s96, s9, 11
	v_lshl_add_u64 v[248:249], v[184:185], 0, s[96:97]
	v_lshl_add_u64 v[250:251], v[186:187], 0, s[96:97]
	s_waitcnt vmcnt(6) lgkmcnt(3)
	v_mfma_f32_16x16x32_bf16 v[112:115], v[196:199], v[128:131], v[112:115]
	v_mfma_f32_16x16x32_bf16 v[120:123], v[196:199], v[132:135], v[120:123]
	ds_read_b128 v[196:199], v246 offset:20480
	s_waitcnt lgkmcnt(3)
	v_mfma_f32_16x16x32_bf16 v[116:119], v[200:203], v[128:131], v[116:119]
	v_mfma_f32_16x16x32_bf16 v[124:127], v[200:203], v[132:135], v[124:127]
	ds_read_b128 v[200:203], v162 offset:20480
	s_waitcnt lgkmcnt(3)
	v_mfma_f32_16x16x32_bf16 v[96:99], v[204:207], v[128:131], v[96:99]
	v_mfma_f32_16x16x32_bf16 v[104:107], v[204:207], v[132:135], v[104:107]
	ds_read_b128 v[204:207], v246 offset:22528
	s_waitcnt lgkmcnt(3)
	v_mfma_f32_16x16x32_bf16 v[100:103], v[242:245], v[128:131], v[100:103]
	v_mfma_f32_16x16x32_bf16 v[108:111], v[242:245], v[132:135], v[108:111]
	ds_read_b128 v[242:245], v162 offset:22528
	s_waitcnt lgkmcnt(3)
	v_mfma_f32_16x16x32_bf16 v[80:83], v[196:199], v[128:131], v[80:83]
	v_mfma_f32_16x16x32_bf16 v[88:91], v[196:199], v[132:135], v[88:91]
	s_waitcnt lgkmcnt(2)
	v_mfma_f32_16x16x32_bf16 v[84:87], v[200:203], v[128:131], v[84:87]
	v_mfma_f32_16x16x32_bf16 v[92:95], v[200:203], v[132:135], v[92:95]
	s_waitcnt lgkmcnt(1)
	v_mfma_f32_16x16x32_bf16 v[64:67], v[204:207], v[128:131], v[64:67]
	v_mfma_f32_16x16x32_bf16 v[72:75], v[204:207], v[132:135], v[72:75]
	s_waitcnt lgkmcnt(0)
	v_mfma_f32_16x16x32_bf16 v[68:71], v[242:245], v[128:131], v[68:71]
	v_mfma_f32_16x16x32_bf16 v[76:79], v[242:245], v[132:135], v[76:79]
	global_load_dwordx4 v[128:131], v[248:249], off
	global_load_dwordx4 v[132:135], v[248:249], off offset:256
	s_waitcnt vmcnt(6)
	s_barrier
	s_add_i32 s9, s3, 5
	s_lshl_b32 s96, s9, 13
	s_add_i32 m0, vcc_lo, 16384
	v_lshl_add_u64 v[160:161], v[188:189], 0, s[96:97]
	global_load_lds_dwordx4 v[160:161], off
	global_load_lds_dwordx4 v[160:161], off offset:1024
	ds_read_b128 v[196:199], v246 offset:0
	ds_read_b128 v[200:203], v162 offset:0
	ds_read_b128 v[204:207], v246 offset:2048
	ds_read_b128 v[242:245], v162 offset:2048
	s_add_i32 s9, s3, 5
	s_lshl_b32 s96, s9, 11
	v_lshl_add_u64 v[248:249], v[184:185], 0, s[96:97]
	v_lshl_add_u64 v[250:251], v[186:187], 0, s[96:97]
	s_waitcnt vmcnt(6) lgkmcnt(3)
	v_mfma_f32_16x16x32_bf16 v[112:115], v[196:199], v[144:147], v[112:115]
	v_mfma_f32_16x16x32_bf16 v[120:123], v[196:199], v[148:151], v[120:123]
	ds_read_b128 v[196:199], v246 offset:4096
	s_waitcnt lgkmcnt(3)
	v_mfma_f32_16x16x32_bf16 v[116:119], v[200:203], v[144:147], v[116:119]
	v_mfma_f32_16x16x32_bf16 v[124:127], v[200:203], v[148:151], v[124:127]
	ds_read_b128 v[200:203], v162 offset:4096
	s_waitcnt lgkmcnt(3)
	v_mfma_f32_16x16x32_bf16 v[96:99], v[204:207], v[144:147], v[96:99]
	v_mfma_f32_16x16x32_bf16 v[104:107], v[204:207], v[148:151], v[104:107]
	ds_read_b128 v[204:207], v246 offset:6144
	s_waitcnt lgkmcnt(3)
	v_mfma_f32_16x16x32_bf16 v[100:103], v[242:245], v[144:147], v[100:103]
	v_mfma_f32_16x16x32_bf16 v[108:111], v[242:245], v[148:151], v[108:111]
	ds_read_b128 v[242:245], v162 offset:6144
	s_waitcnt lgkmcnt(3)
	v_mfma_f32_16x16x32_bf16 v[80:83], v[196:199], v[144:147], v[80:83]
	v_mfma_f32_16x16x32_bf16 v[88:91], v[196:199], v[148:151], v[88:91]
	s_waitcnt lgkmcnt(2)
	v_mfma_f32_16x16x32_bf16 v[84:87], v[200:203], v[144:147], v[84:87]
	v_mfma_f32_16x16x32_bf16 v[92:95], v[200:203], v[148:151], v[92:95]
	s_waitcnt lgkmcnt(1)
	v_mfma_f32_16x16x32_bf16 v[64:67], v[204:207], v[144:147], v[64:67]
	v_mfma_f32_16x16x32_bf16 v[72:75], v[204:207], v[148:151], v[72:75]
	s_waitcnt lgkmcnt(0)
	v_mfma_f32_16x16x32_bf16 v[68:71], v[242:245], v[144:147], v[68:71]
	v_mfma_f32_16x16x32_bf16 v[76:79], v[242:245], v[148:151], v[76:79]
	global_load_dwordx4 v[144:147], v[248:249], off
	global_load_dwordx4 v[148:151], v[248:249], off offset:256
	s_waitcnt vmcnt(6)
	s_barrier
	s_add_i32 s9, s3, 6
	s_lshl_b32 s96, s9, 13
	s_mov_b32 m0, vcc_lo
	v_lshl_add_u64 v[160:161], v[188:189], 0, s[96:97]
	global_load_lds_dwordx4 v[160:161], off
	global_load_lds_dwordx4 v[160:161], off offset:1024
	ds_read_b128 v[196:199], v246 offset:8192
	ds_read_b128 v[200:203], v162 offset:8192
	ds_read_b128 v[204:207], v246 offset:10240
	ds_read_b128 v[242:245], v162 offset:10240
	s_add_i32 s9, s3, 6
	s_lshl_b32 s96, s9, 11
	v_lshl_add_u64 v[248:249], v[184:185], 0, s[96:97]
	v_lshl_add_u64 v[250:251], v[186:187], 0, s[96:97]
	s_waitcnt vmcnt(6) lgkmcnt(3)
	v_mfma_f32_16x16x32_bf16 v[112:115], v[196:199], v[128:131], v[112:115]
	v_mfma_f32_16x16x32_bf16 v[120:123], v[196:199], v[132:135], v[120:123]
	ds_read_b128 v[196:199], v246 offset:12288
	s_waitcnt lgkmcnt(3)
	v_mfma_f32_16x16x32_bf16 v[116:119], v[200:203], v[128:131], v[116:119]
	v_mfma_f32_16x16x32_bf16 v[124:127], v[200:203], v[132:135], v[124:127]
	ds_read_b128 v[200:203], v162 offset:12288
	s_waitcnt lgkmcnt(3)
	v_mfma_f32_16x16x32_bf16 v[96:99], v[204:207], v[128:131], v[96:99]
	v_mfma_f32_16x16x32_bf16 v[104:107], v[204:207], v[132:135], v[104:107]
	ds_read_b128 v[204:207], v246 offset:14336
	s_waitcnt lgkmcnt(3)
	v_mfma_f32_16x16x32_bf16 v[100:103], v[242:245], v[128:131], v[100:103]
	v_mfma_f32_16x16x32_bf16 v[108:111], v[242:245], v[132:135], v[108:111]
	ds_read_b128 v[242:245], v162 offset:14336
	s_waitcnt lgkmcnt(3)
	v_mfma_f32_16x16x32_bf16 v[80:83], v[196:199], v[128:131], v[80:83]
	v_mfma_f32_16x16x32_bf16 v[88:91], v[196:199], v[132:135], v[88:91]
	s_waitcnt lgkmcnt(2)
	v_mfma_f32_16x16x32_bf16 v[84:87], v[200:203], v[128:131], v[84:87]
	v_mfma_f32_16x16x32_bf16 v[92:95], v[200:203], v[132:135], v[92:95]
	s_waitcnt lgkmcnt(1)
	v_mfma_f32_16x16x32_bf16 v[64:67], v[204:207], v[128:131], v[64:67]
	v_mfma_f32_16x16x32_bf16 v[72:75], v[204:207], v[132:135], v[72:75]
	s_waitcnt lgkmcnt(0)
	v_mfma_f32_16x16x32_bf16 v[68:71], v[242:245], v[128:131], v[68:71]
	v_mfma_f32_16x16x32_bf16 v[76:79], v[242:245], v[132:135], v[76:79]
	global_load_dwordx4 v[128:131], v[248:249], off
	global_load_dwordx4 v[132:135], v[248:249], off offset:256
	s_waitcnt vmcnt(6)
	s_barrier
	s_add_i32 s9, s3, 7
	s_lshl_b32 s96, s9, 13
	s_add_i32 m0, vcc_lo, 8192
	v_lshl_add_u64 v[160:161], v[188:189], 0, s[96:97]
	global_load_lds_dwordx4 v[160:161], off
	global_load_lds_dwordx4 v[160:161], off offset:1024
	ds_read_b128 v[196:199], v246 offset:16384
	ds_read_b128 v[200:203], v162 offset:16384
	ds_read_b128 v[204:207], v246 offset:18432
	ds_read_b128 v[242:245], v162 offset:18432
	s_add_i32 s9, s3, 7
	s_lshl_b32 s96, s9, 11
	v_lshl_add_u64 v[248:249], v[184:185], 0, s[96:97]
	v_lshl_add_u64 v[250:251], v[186:187], 0, s[96:97]
	s_waitcnt vmcnt(6) lgkmcnt(3)
	v_mfma_f32_16x16x32_bf16 v[112:115], v[196:199], v[144:147], v[112:115]
	v_mfma_f32_16x16x32_bf16 v[120:123], v[196:199], v[148:151], v[120:123]
	ds_read_b128 v[196:199], v246 offset:20480
	s_waitcnt lgkmcnt(3)
	v_mfma_f32_16x16x32_bf16 v[116:119], v[200:203], v[144:147], v[116:119]
	v_mfma_f32_16x16x32_bf16 v[124:127], v[200:203], v[148:151], v[124:127]
	ds_read_b128 v[200:203], v162 offset:20480
	s_waitcnt lgkmcnt(3)
	v_mfma_f32_16x16x32_bf16 v[96:99], v[204:207], v[144:147], v[96:99]
	v_mfma_f32_16x16x32_bf16 v[104:107], v[204:207], v[148:151], v[104:107]
	ds_read_b128 v[204:207], v246 offset:22528
	s_waitcnt lgkmcnt(3)
	v_mfma_f32_16x16x32_bf16 v[100:103], v[242:245], v[144:147], v[100:103]
	v_mfma_f32_16x16x32_bf16 v[108:111], v[242:245], v[148:151], v[108:111]
	ds_read_b128 v[242:245], v162 offset:22528
	s_waitcnt lgkmcnt(3)
	v_mfma_f32_16x16x32_bf16 v[80:83], v[196:199], v[144:147], v[80:83]
	v_mfma_f32_16x16x32_bf16 v[88:91], v[196:199], v[148:151], v[88:91]
	s_waitcnt lgkmcnt(2)
	v_mfma_f32_16x16x32_bf16 v[84:87], v[200:203], v[144:147], v[84:87]
	v_mfma_f32_16x16x32_bf16 v[92:95], v[200:203], v[148:151], v[92:95]
	s_waitcnt lgkmcnt(1)
	v_mfma_f32_16x16x32_bf16 v[64:67], v[204:207], v[144:147], v[64:67]
	v_mfma_f32_16x16x32_bf16 v[72:75], v[204:207], v[148:151], v[72:75]
	s_waitcnt lgkmcnt(0)
	v_mfma_f32_16x16x32_bf16 v[68:71], v[242:245], v[144:147], v[68:71]
	v_mfma_f32_16x16x32_bf16 v[76:79], v[242:245], v[148:151], v[76:79]
	global_load_dwordx4 v[144:147], v[248:249], off
	global_load_dwordx4 v[148:151], v[248:249], off offset:256
	s_waitcnt vmcnt(6)
	s_barrier
	s_add_i32 s3, s3, 6
	s_cmp_lt_u32 s3, 30
	s_cbranch_scc1 .Lg16_outh_k
	ds_read_b128 v[196:199], v246 offset:0
	ds_read_b128 v[200:203], v162 offset:0
	ds_read_b128 v[204:207], v246 offset:2048
	ds_read_b128 v[242:245], v162 offset:2048
	s_waitcnt vmcnt(4) lgkmcnt(3)
	v_mfma_f32_16x16x32_bf16 v[112:115], v[196:199], v[128:131], v[112:115]
	v_mfma_f32_16x16x32_bf16 v[120:123], v[196:199], v[132:135], v[120:123]
	ds_read_b128 v[196:199], v246 offset:4096
	s_waitcnt lgkmcnt(3)
	v_mfma_f32_16x16x32_bf16 v[116:119], v[200:203], v[128:131], v[116:119]
	v_mfma_f32_16x16x32_bf16 v[124:127], v[200:203], v[132:135], v[124:127]
	ds_read_b128 v[200:203], v162 offset:4096
	s_waitcnt lgkmcnt(3)
	v_mfma_f32_16x16x32_bf16 v[96:99], v[204:207], v[128:131], v[96:99]
	v_mfma_f32_16x16x32_bf16 v[104:107], v[204:207], v[132:135], v[104:107]
	ds_read_b128 v[204:207], v246 offset:6144
	s_waitcnt lgkmcnt(3)
	v_mfma_f32_16x16x32_bf16 v[100:103], v[242:245], v[128:131], v[100:103]
	v_mfma_f32_16x16x32_bf16 v[108:111], v[242:245], v[132:135], v[108:111]
	ds_read_b128 v[242:245], v162 offset:6144
	s_waitcnt lgkmcnt(3)
	v_mfma_f32_16x16x32_bf16 v[80:83], v[196:199], v[128:131], v[80:83]
	v_mfma_f32_16x16x32_bf16 v[88:91], v[196:199], v[132:135], v[88:91]
	s_waitcnt lgkmcnt(2)
	v_mfma_f32_16x16x32_bf16 v[84:87], v[200:203], v[128:131], v[84:87]
	v_mfma_f32_16x16x32_bf16 v[92:95], v[200:203], v[132:135], v[92:95]
	s_waitcnt lgkmcnt(1)
	v_mfma_f32_16x16x32_bf16 v[64:67], v[204:207], v[128:131], v[64:67]
	v_mfma_f32_16x16x32_bf16 v[72:75], v[204:207], v[132:135], v[72:75]
	s_waitcnt lgkmcnt(0)
	v_mfma_f32_16x16x32_bf16 v[68:71], v[242:245], v[128:131], v[68:71]
	v_mfma_f32_16x16x32_bf16 v[76:79], v[242:245], v[132:135], v[76:79]
	s_waitcnt vmcnt(2)
	s_barrier
	ds_read_b128 v[196:199], v246 offset:8192
	ds_read_b128 v[200:203], v162 offset:8192
	ds_read_b128 v[204:207], v246 offset:10240
	ds_read_b128 v[242:245], v162 offset:10240
	s_waitcnt vmcnt(0) lgkmcnt(3)
	v_mfma_f32_16x16x32_bf16 v[112:115], v[196:199], v[144:147], v[112:115]
	v_mfma_f32_16x16x32_bf16 v[120:123], v[196:199], v[148:151], v[120:123]
	ds_read_b128 v[196:199], v246 offset:12288
	s_waitcnt lgkmcnt(3)
	v_mfma_f32_16x16x32_bf16 v[116:119], v[200:203], v[144:147], v[116:119]
	v_mfma_f32_16x16x32_bf16 v[124:127], v[200:203], v[148:151], v[124:127]
	ds_read_b128 v[200:203], v162 offset:12288
	s_waitcnt lgkmcnt(3)
	v_mfma_f32_16x16x32_bf16 v[96:99], v[204:207], v[144:147], v[96:99]
	v_mfma_f32_16x16x32_bf16 v[104:107], v[204:207], v[148:151], v[104:107]
	ds_read_b128 v[204:207], v246 offset:14336
	s_waitcnt lgkmcnt(3)
	v_mfma_f32_16x16x32_bf16 v[100:103], v[242:245], v[144:147], v[100:103]
	v_mfma_f32_16x16x32_bf16 v[108:111], v[242:245], v[148:151], v[108:111]
	ds_read_b128 v[242:245], v162 offset:14336
	s_waitcnt lgkmcnt(3)
	v_mfma_f32_16x16x32_bf16 v[80:83], v[196:199], v[144:147], v[80:83]
	v_mfma_f32_16x16x32_bf16 v[88:91], v[196:199], v[148:151], v[88:91]
	s_waitcnt lgkmcnt(2)
	v_mfma_f32_16x16x32_bf16 v[84:87], v[200:203], v[144:147], v[84:87]
	v_mfma_f32_16x16x32_bf16 v[92:95], v[200:203], v[148:151], v[92:95]
	s_waitcnt lgkmcnt(1)
	v_mfma_f32_16x16x32_bf16 v[64:67], v[204:207], v[144:147], v[64:67]
	v_mfma_f32_16x16x32_bf16 v[72:75], v[204:207], v[148:151], v[72:75]
	s_waitcnt lgkmcnt(0)
	v_mfma_f32_16x16x32_bf16 v[68:71], v[242:245], v[144:147], v[68:71]
	v_mfma_f32_16x16x32_bf16 v[76:79], v[242:245], v[148:151], v[76:79]
	s_barrier
	s_nop 7
	s_nop 1
	s_waitcnt vmcnt(0)
	s_waitcnt vmcnt(0)
	v_and_b32_e32 v188, 63, v179
	v_lshrrev_b32_e32 v189, 6, v179
	v_mul_u32_u24_e32 v249, 0x2400, v189
	v_mov_b32_e32 v250, v249
	v_and_b32_e32 v251, 15, v188
	v_mul_u32_u24_e32 v251, 0x110, v251
	v_add_u32_e32 v249, v249, v251
	v_lshrrev_b32_e32 v251, 4, v188
	v_lshl_add_u32 v249, v251, 5, v249
	v_lshrrev_b32_e32 v237, 4, v188
	v_mul_u32_u24_e32 v251, 0x110, v237
	v_add_u32_e32 v250, v250, v251
	v_and_b32_e32 v251, 15, v188
	v_lshlrev_b32_e32 v251, 4, v251
	v_add_u32_e32 v250, v250, v251
	v_lshl_add_u32 v237, v189, 6, v237
	v_lshl_add_u32 v237, v237, 12, v251
	v_add_u32_e32 v238, 16384, v237
	v_add_u32_e32 v239, 32768, v237
	v_add_u32_e32 v240, 49152, v237
	v_add_u32_e32 v241, 65536, v237
	v_add_u32_e32 v242, 81920, v237
	v_add_u32_e32 v243, 98304, v237
	v_add_u32_e32 v248, 114688, v237
	s_lshl_b32 s16, s8, 8
	s_lshl_b32 s18, s2, 9
	s_lshr_b32 s19, s8, 4
	v_readlane_b32 s12, v254, 38
	v_readlane_b32 s13, v254, 37
	v_readlane_b32 s14, v253, 46
	v_readlane_b32 s15, v253, 47
	v_readlane_b32 s22, v254, 40
	v_readlane_b32 s23, v254, 39
	s_add_i32 s17, s16, 0xffff8000
	s_cmpk_lt_u32 s8, 0x80
	s_cselect_b32 s12, s12, s22
	s_cselect_b32 s13, s13, s23
	s_cselect_b32 s14, s14, s62
	s_cselect_b32 s15, s15, s63
	s_cselect_b32 s19, s19, 8
	s_cselect_b32 s16, s16, s17
	s_mov_b32 s17, 0
	s_lshl_b64 s[16:17], s[16:17], 12
	s_add_u32 s16, s16, s18
	s_addc_u32 s17, s17, 0
	s_add_u32 s12, s12, s16
	s_addc_u32 s13, s13, s17
	s_add_u32 s14, s14, s16
	s_addc_u32 s15, s15, s17
	s_mul_i32 s19, s19, 0x6000
	s_add_u32 s20, s0, s19
	s_addc_u32 s21, s1, 0
	s_add_u32 s20, s20, s18
	s_addc_u32 s21, s21, 0
	s_cmp_eq_u32 s101, 1
	s_cbranch_scc0 .Lre_outh_h0
	s_add_u32 s12, s12, 0x20000
	s_addc_u32 s13, s13, 0
	s_add_u32 s14, s14, 0x20000
	s_addc_u32 s15, s15, 0
.Lre_outh_h0:
	global_load_dwordx4 v[244:247], v251, s[20:21]
	global_load_dwordx4 v[160:163], v237, s[12:13]
	global_load_dwordx4 v[164:167], v238, s[12:13]
	global_load_dwordx4 v[168:171], v239, s[12:13]
	global_load_dwordx4 v[172:175], v240, s[12:13]
	global_load_dwordx4 v[196:199], v241, s[12:13]
	global_load_dwordx4 v[200:203], v242, s[12:13]
	global_load_dwordx4 v[204:207], v243, s[12:13]
	global_load_dwordx4 v[184:187], v248, s[12:13]
	ds_write_b128 v249, v[112:115]
	ds_write_b128 v249, v[116:119] offset:16
	ds_write_b128 v249, v[96:99] offset:128
	ds_write_b128 v249, v[100:103] offset:144
	ds_write_b128 v249, v[120:123] offset:4352
	ds_write_b128 v249, v[124:127] offset:4368
	ds_write_b128 v249, v[104:107] offset:4480
	ds_write_b128 v249, v[108:111] offset:4496
	s_waitcnt lgkmcnt(0)
	ds_read_b128 v[128:131], v250
	ds_read_b128 v[132:135], v250 offset:1088
	ds_read_b128 v[136:139], v250 offset:2176
	ds_read_b128 v[140:143], v250 offset:3264
	ds_read_b128 v[144:147], v250 offset:4352
	ds_read_b128 v[148:151], v250 offset:5440
	ds_read_b128 v[152:155], v250 offset:6528
	ds_read_b128 v[156:159], v250 offset:7616
	s_waitcnt vmcnt(7) lgkmcnt(7)
	v_fma_f32 v128, v244, v128, v160
	v_fma_f32 v129, v245, v129, v161
	v_fma_f32 v130, v246, v130, v162
	v_fma_f32 v131, v247, v131, v163
	global_store_dwordx4 v237, v[128:131], s[14:15]
	s_waitcnt vmcnt(7) lgkmcnt(6)
	v_fma_f32 v132, v244, v132, v164
	v_fma_f32 v133, v245, v133, v165
	v_fma_f32 v134, v246, v134, v166
	v_fma_f32 v135, v247, v135, v167
	global_store_dwordx4 v238, v[132:135], s[14:15]
	s_waitcnt vmcnt(7) lgkmcnt(5)
	v_fma_f32 v136, v244, v136, v168
	v_fma_f32 v137, v245, v137, v169
	v_fma_f32 v138, v246, v138, v170
	v_fma_f32 v139, v247, v139, v171
	global_store_dwordx4 v239, v[136:139], s[14:15]
	s_waitcnt vmcnt(7) lgkmcnt(4)
	v_fma_f32 v140, v244, v140, v172
	v_fma_f32 v141, v245, v141, v173
	v_fma_f32 v142, v246, v142, v174
	v_fma_f32 v143, v247, v143, v175
	global_store_dwordx4 v240, v[140:143], s[14:15]
	s_waitcnt vmcnt(7) lgkmcnt(3)
	v_fma_f32 v144, v244, v144, v196
	v_fma_f32 v145, v245, v145, v197
	v_fma_f32 v146, v246, v146, v198
	v_fma_f32 v147, v247, v147, v199
	global_store_dwordx4 v241, v[144:147], s[14:15]
	s_waitcnt vmcnt(7) lgkmcnt(2)
	v_fma_f32 v148, v244, v148, v200
	v_fma_f32 v149, v245, v149, v201
	v_fma_f32 v150, v246, v150, v202
	v_fma_f32 v151, v247, v151, v203
	global_store_dwordx4 v242, v[148:151], s[14:15]
	s_waitcnt vmcnt(7) lgkmcnt(1)
	v_fma_f32 v152, v244, v152, v204
	v_fma_f32 v153, v245, v153, v205
	v_fma_f32 v154, v246, v154, v206
	v_fma_f32 v155, v247, v155, v207
	global_store_dwordx4 v243, v[152:155], s[14:15]
	s_waitcnt vmcnt(7) lgkmcnt(0)
	v_fma_f32 v156, v244, v156, v184
	v_fma_f32 v157, v245, v157, v185
	v_fma_f32 v158, v246, v158, v186
	v_fma_f32 v159, v247, v159, v187
	global_store_dwordx4 v248, v[156:159], s[14:15]
	global_load_dwordx4 v[244:247], v251, s[20:21] offset:256
	global_load_dwordx4 v[160:163], v237, s[12:13] offset:256
	global_load_dwordx4 v[164:167], v238, s[12:13] offset:256
	global_load_dwordx4 v[168:171], v239, s[12:13] offset:256
	global_load_dwordx4 v[172:175], v240, s[12:13] offset:256
	global_load_dwordx4 v[196:199], v241, s[12:13] offset:256
	global_load_dwordx4 v[200:203], v242, s[12:13] offset:256
	global_load_dwordx4 v[204:207], v243, s[12:13] offset:256
	global_load_dwordx4 v[184:187], v248, s[12:13] offset:256
	ds_write_b128 v249, v[80:83]
	ds_write_b128 v249, v[84:87] offset:16
	ds_write_b128 v249, v[64:67] offset:128
	ds_write_b128 v249, v[68:71] offset:144
	ds_write_b128 v249, v[88:91] offset:4352
	ds_write_b128 v249, v[92:95] offset:4368
	ds_write_b128 v249, v[72:75] offset:4480
	ds_write_b128 v249, v[76:79] offset:4496
	s_waitcnt lgkmcnt(0)
	ds_read_b128 v[128:131], v250
	ds_read_b128 v[132:135], v250 offset:1088
	ds_read_b128 v[136:139], v250 offset:2176
	ds_read_b128 v[140:143], v250 offset:3264
	ds_read_b128 v[144:147], v250 offset:4352
	ds_read_b128 v[148:151], v250 offset:5440
	ds_read_b128 v[152:155], v250 offset:6528
	ds_read_b128 v[156:159], v250 offset:7616
	s_waitcnt vmcnt(7) lgkmcnt(7)
	v_fma_f32 v128, v244, v128, v160
	v_fma_f32 v129, v245, v129, v161
	v_fma_f32 v130, v246, v130, v162
	v_fma_f32 v131, v247, v131, v163
	global_store_dwordx4 v237, v[128:131], s[14:15] offset:256
	s_waitcnt vmcnt(7) lgkmcnt(6)
	v_fma_f32 v132, v244, v132, v164
	v_fma_f32 v133, v245, v133, v165
	v_fma_f32 v134, v246, v134, v166
	v_fma_f32 v135, v247, v135, v167
	global_store_dwordx4 v238, v[132:135], s[14:15] offset:256
	s_waitcnt vmcnt(7) lgkmcnt(5)
	v_fma_f32 v136, v244, v136, v168
	v_fma_f32 v137, v245, v137, v169
	v_fma_f32 v138, v246, v138, v170
	v_fma_f32 v139, v247, v139, v171
	global_store_dwordx4 v239, v[136:139], s[14:15] offset:256
	s_waitcnt vmcnt(7) lgkmcnt(4)
	v_fma_f32 v140, v244, v140, v172
	v_fma_f32 v141, v245, v141, v173
	v_fma_f32 v142, v246, v142, v174
	v_fma_f32 v143, v247, v143, v175
	global_store_dwordx4 v240, v[140:143], s[14:15] offset:256
	s_waitcnt vmcnt(7) lgkmcnt(3)
	v_fma_f32 v144, v244, v144, v196
	v_fma_f32 v145, v245, v145, v197
	v_fma_f32 v146, v246, v146, v198
	v_fma_f32 v147, v247, v147, v199
	global_store_dwordx4 v241, v[144:147], s[14:15] offset:256
	s_waitcnt vmcnt(7) lgkmcnt(2)
	v_fma_f32 v148, v244, v148, v200
	v_fma_f32 v149, v245, v149, v201
	v_fma_f32 v150, v246, v150, v202
	v_fma_f32 v151, v247, v151, v203
	global_store_dwordx4 v242, v[148:151], s[14:15] offset:256
	s_waitcnt vmcnt(7) lgkmcnt(1)
	v_fma_f32 v152, v244, v152, v204
	v_fma_f32 v153, v245, v153, v205
	v_fma_f32 v154, v246, v154, v206
	v_fma_f32 v155, v247, v155, v207
	global_store_dwordx4 v243, v[152:155], s[14:15] offset:256
	s_waitcnt vmcnt(7) lgkmcnt(0)
	v_fma_f32 v156, v244, v156, v184
	v_fma_f32 v157, v245, v157, v185
	v_fma_f32 v158, v246, v158, v186
	v_fma_f32 v159, v247, v159, v187
	global_store_dwordx4 v248, v[156:159], s[14:15] offset:256
	s_waitcnt lgkmcnt(0)
	s_mov_b32 s100, 0
	s_barrier
	s_branch .LBB0_926

.LBB0_1086:
	s_ashr_i32 s6, s2, 31
	s_lshr_b32 s6, s6, 26
	s_add_i32 s6, s2, s6
	s_ashr_i32 s7, s6, 6
	s_lshl_b32 s7, s7, 3
	s_sub_i32 s8, s25, s7
	s_min_i32 s8, s8, 8
	s_abs_i32 s9, s8
	v_cvt_f32_u32_e32 v0, s9
	s_sub_i32 s12, 0, s9
	s_andn2_b32 s6, s6, 63
	s_sub_i32 s10, s2, s6
	v_rcp_iflag_f32_e32 v0, v0
	s_abs_i32 s6, s10
	s_xor_b32 s11, s10, s8
	s_ashr_i32 s11, s11, 31
	v_mul_f32_e32 v0, 0x4f7ffffe, v0
	v_cvt_u32_f32_e32 v0, v0
	v_mov_b32_e32 v181, v179
	v_readfirstlane_b32 s13, v0
	s_mul_i32 s12, s12, s13
	s_mul_hi_u32 s12, s13, s12
	s_add_i32 s13, s13, s12
	s_mul_hi_u32 s12, s6, s13
	s_mul_i32 s13, s12, s9
	s_sub_i32 s6, s6, s13
	s_add_i32 s14, s12, 1
	s_sub_i32 s13, s6, s9
	s_cmp_ge_u32 s6, s9
	s_cselect_b32 s12, s14, s12
	s_cselect_b32 s6, s13, s6
	s_add_i32 s13, s12, 1
	s_cmp_ge_u32 s6, s9
	s_cselect_b32 s6, s13, s12
	s_xor_b32 s6, s6, s11
	s_sub_i32 s6, s6, s11
	s_mul_i32 s8, s8, s6
	s_add_i32 s7, s7, s5
	s_sub_i32 s8, s10, s8
	v_ashrrev_i32_e32 v237, 6, v181
	s_add_i32 s7, s7, s8
	v_lshlrev_b32_e32 v0, 1, v237
	v_bfe_u32 v183, v181, 5, 1
	v_lshl_add_u32 v2, s7, 3, v0
	v_mov_b64_e32 v[0:1], s[66:67]
	v_and_b32_e32 v238, 31, v181
	v_mad_i64_i32 v[0:1], s[8:9], v2, s24, v[0:1]
	v_lshlrev_b32_e32 v176, 9, v183
	v_lshl_add_u64 v[0:1], v[0:1], 0, v[176:177]
	v_lshlrev_b32_e32 v176, 4, v238
	v_ashrrev_i32_e32 v38, 2, v181
	s_mul_i32 s8, s6, 0xb0000
	v_lshl_add_u64 v[184:185], v[0:1], 0, v[176:177]
	s_mul_hi_i32 s9, s6, 0xb0000
	s_add_u32 s8, s3, s8
	v_lshlrev_b32_e32 v0, 5, v38
	s_addc_u32 s9, s4, s9
	v_ashrrev_i32_e32 v1, 31, v0
	v_lshlrev_b32_e32 v2, 4, v181
	v_lshl_add_u64 v[0:1], v[0:1], 1, s[8:9]
	v_and_b32_e32 v176, 48, v2
	v_lshl_add_u64 v[186:187], v[0:1], 0, v[176:177]
	s_movk_i32 s8, 0x2000
	v_add_co_u32_e32 v34, vcc, s8, v186
	v_mul_u32_u24_e32 v36, 40, v238
	s_nop 0
	v_addc_co_u32_e32 v35, vcc, 0, v187, vcc
	v_lshlrev_b32_e32 v37, 4, v183
	v_lshl_add_u32 v240, v36, 1, v37
	v_add_co_u32_e32 v36, vcc, s24, v184
	s_movk_i32 s9, 0x50
	s_nop 0
	v_addc_co_u32_e32 v37, vcc, 0, v185, vcc
	v_and_b32_e32 v239, 63, v181
	s_cmp_eq_u32 s100, 1
	s_cbranch_scc1 .Lhx_down_half
	v_bfe_u32 v247, v181, 4, 2
	v_lshlrev_b32_e32 v247, 1, v247
	v_mov_b32_e32 v176, 0x78
	v_lshrrev_b32_e32 v247, v247, v176
	v_and_b32_e32 v247, 3, v247
	v_and_b32_e32 v246, 3, v181
	v_xor_b32_e32 v247, v247, v246
	v_lshlrev_b32_e32 v247, 4, v247
	v_and_b32_e32 v188, 0xffffffcf, v186
	v_or_b32_e32 v188, v188, v247
	v_mov_b32_e32 v189, v187
	v_lshrrev_b32_e32 v176, 6, v181
	v_lshlrev_b32_e32 v247, 11, v176
	v_lshlrev_b32_e32 v176, 10, v176
	v_lshl_add_u64 v[188:189], v[188:189], 0, v[176:177]
	v_readfirstlane_b32 vcc_lo, v247
	v_bfe_u32 v247, v181, 4, 1
	v_lshlrev_b32_e32 v176, 9, v183
	v_lshl_add_u32 v176, v247, 8, v176
	v_lshl_add_u64 v[184:185], v[184:185], 0, v[176:177]
	v_mov_b32_e32 v176, s24
	v_lshl_add_u64 v[186:187], v[184:185], 0, v[176:177]
	v_mov_b32_e32 v176, 0x78
	v_bfe_u32 v247, v181, 2, 1
	v_lshlrev_b32_e32 v247, 2, v247
	v_lshrrev_b32_e32 v247, v247, v176
	v_and_b32_e32 v247, 3, v247
	v_bfe_u32 v246, v181, 4, 2
	v_xor_b32_e32 v247, v247, v246
	v_lshlrev_b32_e32 v247, 4, v247
	v_bfe_u32 v246, v181, 2, 2
	v_lshlrev_b32_e32 v246, 3, v246
	v_and_b32_e32 v162, 3, v181
	v_add_u32_e32 v246, v246, v162
	v_lshl_add_u32 v246, v246, 6, v247
	v_bfe_u32 v247, v181, 2, 1
	v_lshlrev_b32_e32 v247, 2, v247
	v_add_u32_e32 v247, 2, v247
	v_lshrrev_b32_e32 v247, v247, v176
	v_and_b32_e32 v247, 3, v247
	v_bfe_u32 v162, v181, 4, 2
	v_xor_b32_e32 v247, v247, v162
	v_lshlrev_b32_e32 v247, 4, v247
	v_and_b32_e32 v162, 0xffffffcf, v246
	v_add_u32_e32 v162, 0x100, v162
	v_or_b32_e32 v162, v162, v247
	s_mov_b32 s96, 0
	s_mov_b32 m0, vcc_lo
	v_lshl_add_u64 v[160:161], v[188:189], 0, s[96:97]
	global_load_lds_dwordx4 v[160:161], off
	global_load_lds_dwordx4 v[160:161], off offset:1024
	s_mov_b32 s96, 0
	v_lshl_add_u64 v[248:249], v[184:185], 0, s[96:97]
	v_lshl_add_u64 v[250:251], v[186:187], 0, s[96:97]
	global_load_dwordx4 v[128:131], v[248:249], off
	global_load_dwordx4 v[132:135], v[248:249], off offset:256
	global_load_dwordx4 v[136:139], v[250:251], off
	global_load_dwordx4 v[140:143], v[250:251], off offset:256
	s_movk_i32 s96, 0x2000
	s_add_i32 m0, vcc_lo, 8192
	v_lshl_add_u64 v[160:161], v[188:189], 0, s[96:97]
	global_load_lds_dwordx4 v[160:161], off
	global_load_lds_dwordx4 v[160:161], off offset:1024
	s_movk_i32 s96, 0x800
	v_lshl_add_u64 v[248:249], v[184:185], 0, s[96:97]
	v_lshl_add_u64 v[250:251], v[186:187], 0, s[96:97]
	global_load_dwordx4 v[144:147], v[248:249], off
	global_load_dwordx4 v[148:151], v[248:249], off offset:256
	global_load_dwordx4 v[152:155], v[250:251], off
	global_load_dwordx4 v[156:159], v[250:251], off offset:256
	v_mov_b32_e32 v0, 0
	v_mov_b32_e32 v1, 0
	v_mov_b32_e32 v2, 0
	v_mov_b32_e32 v3, 0
	v_mov_b32_e32 v4, 0
	v_mov_b32_e32 v5, 0
	v_mov_b32_e32 v6, 0
	v_mov_b32_e32 v7, 0
	v_mov_b32_e32 v8, 0
	v_mov_b32_e32 v9, 0
	v_mov_b32_e32 v10, 0
	v_mov_b32_e32 v11, 0
	v_mov_b32_e32 v12, 0
	v_mov_b32_e32 v13, 0
	v_mov_b32_e32 v14, 0
	v_mov_b32_e32 v15, 0
	v_mov_b32_e32 v16, 0
	v_mov_b32_e32 v17, 0
	v_mov_b32_e32 v18, 0
	v_mov_b32_e32 v19, 0
	v_mov_b32_e32 v20, 0
	v_mov_b32_e32 v21, 0
	v_mov_b32_e32 v22, 0
	v_mov_b32_e32 v23, 0
	v_mov_b32_e32 v24, 0
	v_mov_b32_e32 v25, 0
	v_mov_b32_e32 v26, 0
	v_mov_b32_e32 v27, 0
	v_mov_b32_e32 v28, 0
	v_mov_b32_e32 v29, 0
	v_mov_b32_e32 v30, 0
	v_mov_b32_e32 v31, 0
	v_mov_b32_e32 v32, 0
	v_mov_b32_e32 v33, 0
	v_mov_b32_e32 v34, 0
	v_mov_b32_e32 v35, 0
	v_mov_b32_e32 v36, 0
	v_mov_b32_e32 v37, 0
	v_mov_b32_e32 v38, 0
	v_mov_b32_e32 v39, 0
	v_mov_b32_e32 v40, 0
	v_mov_b32_e32 v41, 0
	v_mov_b32_e32 v42, 0
	v_mov_b32_e32 v43, 0
	v_mov_b32_e32 v44, 0
	v_mov_b32_e32 v45, 0
	v_mov_b32_e32 v46, 0
	v_mov_b32_e32 v47, 0
	v_mov_b32_e32 v48, 0
	v_mov_b32_e32 v49, 0
	v_mov_b32_e32 v50, 0
	v_mov_b32_e32 v51, 0
	v_mov_b32_e32 v52, 0
	v_mov_b32_e32 v53, 0
	v_mov_b32_e32 v54, 0
	v_mov_b32_e32 v55, 0
	v_mov_b32_e32 v56, 0
	v_mov_b32_e32 v57, 0
	v_mov_b32_e32 v58, 0
	v_mov_b32_e32 v59, 0
	v_mov_b32_e32 v60, 0
	v_mov_b32_e32 v61, 0
	v_mov_b32_e32 v62, 0
	v_mov_b32_e32 v63, 0
	v_mov_b32_e32 v64, 0
	v_mov_b32_e32 v65, 0
	v_mov_b32_e32 v66, 0
	v_mov_b32_e32 v67, 0
	v_mov_b32_e32 v68, 0
	v_mov_b32_e32 v69, 0
	v_mov_b32_e32 v70, 0
	v_mov_b32_e32 v71, 0
	v_mov_b32_e32 v72, 0
	v_mov_b32_e32 v73, 0
	v_mov_b32_e32 v74, 0
	v_mov_b32_e32 v75, 0
	v_mov_b32_e32 v76, 0
	v_mov_b32_e32 v77, 0
	v_mov_b32_e32 v78, 0
	v_mov_b32_e32 v79, 0
	v_mov_b32_e32 v80, 0
	v_mov_b32_e32 v81, 0
	v_mov_b32_e32 v82, 0
	v_mov_b32_e32 v83, 0
	v_mov_b32_e32 v84, 0
	v_mov_b32_e32 v85, 0
	v_mov_b32_e32 v86, 0
	v_mov_b32_e32 v87, 0
	v_mov_b32_e32 v88, 0
	v_mov_b32_e32 v89, 0
	v_mov_b32_e32 v90, 0
	v_mov_b32_e32 v91, 0
	v_mov_b32_e32 v92, 0
	v_mov_b32_e32 v93, 0
	v_mov_b32_e32 v94, 0
	v_mov_b32_e32 v95, 0
	v_mov_b32_e32 v96, 0
	v_mov_b32_e32 v97, 0
	v_mov_b32_e32 v98, 0
	v_mov_b32_e32 v99, 0
	v_mov_b32_e32 v100, 0
	v_mov_b32_e32 v101, 0
	v_mov_b32_e32 v102, 0
	v_mov_b32_e32 v103, 0
	v_mov_b32_e32 v104, 0
	v_mov_b32_e32 v105, 0
	v_mov_b32_e32 v106, 0
	v_mov_b32_e32 v107, 0
	v_mov_b32_e32 v108, 0
	v_mov_b32_e32 v109, 0
	v_mov_b32_e32 v110, 0
	v_mov_b32_e32 v111, 0
	v_mov_b32_e32 v112, 0
	v_mov_b32_e32 v113, 0
	v_mov_b32_e32 v114, 0
	v_mov_b32_e32 v115, 0
	v_mov_b32_e32 v116, 0
	v_mov_b32_e32 v117, 0
	v_mov_b32_e32 v118, 0
	v_mov_b32_e32 v119, 0
	v_mov_b32_e32 v120, 0
	v_mov_b32_e32 v121, 0
	v_mov_b32_e32 v122, 0
	v_mov_b32_e32 v123, 0
	v_mov_b32_e32 v124, 0
	v_mov_b32_e32 v125, 0
	v_mov_b32_e32 v126, 0
	v_mov_b32_e32 v127, 0
	s_mov_b32 s8, 0
	s_waitcnt vmcnt(4)
	s_barrier
.Lg16_down_k:
	s_add_i32 s9, s8, 2
	s_lshl_b32 s96, s9, 13
	s_add_i32 m0, vcc_lo, 16384
	v_lshl_add_u64 v[160:161], v[188:189], 0, s[96:97]
	global_load_lds_dwordx4 v[160:161], off
	global_load_lds_dwordx4 v[160:161], off offset:1024
	ds_read_b128 v[196:199], v246 offset:0
	ds_read_b128 v[200:203], v162 offset:0
	ds_read_b128 v[204:207], v246 offset:2048
	ds_read_b128 v[242:245], v162 offset:2048
	s_add_i32 s9, s8, 2
	s_lshl_b32 s96, s9, 11
	v_lshl_add_u64 v[248:249], v[184:185], 0, s[96:97]
	v_lshl_add_u64 v[250:251], v[186:187], 0, s[96:97]
	s_waitcnt vmcnt(8) lgkmcnt(3)
	v_mfma_f32_16x16x32_bf16 v[112:115], v[196:199], v[128:131], v[112:115]
	v_mfma_f32_16x16x32_bf16 v[120:123], v[196:199], v[132:135], v[120:123]
	v_mfma_f32_16x16x32_bf16 v[48:51], v[196:199], v[136:139], v[48:51]
	v_mfma_f32_16x16x32_bf16 v[56:59], v[196:199], v[140:143], v[56:59]
	ds_read_b128 v[196:199], v246 offset:4096
	s_waitcnt lgkmcnt(3)
	v_mfma_f32_16x16x32_bf16 v[116:119], v[200:203], v[128:131], v[116:119]
	v_mfma_f32_16x16x32_bf16 v[124:127], v[200:203], v[132:135], v[124:127]
	v_mfma_f32_16x16x32_bf16 v[52:55], v[200:203], v[136:139], v[52:55]
	v_mfma_f32_16x16x32_bf16 v[60:63], v[200:203], v[140:143], v[60:63]
	ds_read_b128 v[200:203], v162 offset:4096
	s_waitcnt lgkmcnt(3)
	v_mfma_f32_16x16x32_bf16 v[96:99], v[204:207], v[128:131], v[96:99]
	v_mfma_f32_16x16x32_bf16 v[104:107], v[204:207], v[132:135], v[104:107]
	v_mfma_f32_16x16x32_bf16 v[32:35], v[204:207], v[136:139], v[32:35]
	v_mfma_f32_16x16x32_bf16 v[40:43], v[204:207], v[140:143], v[40:43]
	ds_read_b128 v[204:207], v246 offset:6144
	s_waitcnt lgkmcnt(3)
	v_mfma_f32_16x16x32_bf16 v[100:103], v[242:245], v[128:131], v[100:103]
	v_mfma_f32_16x16x32_bf16 v[108:111], v[242:245], v[132:135], v[108:111]
	v_mfma_f32_16x16x32_bf16 v[36:39], v[242:245], v[136:139], v[36:39]
	v_mfma_f32_16x16x32_bf16 v[44:47], v[242:245], v[140:143], v[44:47]
	ds_read_b128 v[242:245], v162 offset:6144
	s_waitcnt lgkmcnt(3)
	v_mfma_f32_16x16x32_bf16 v[80:83], v[196:199], v[128:131], v[80:83]
	v_mfma_f32_16x16x32_bf16 v[88:91], v[196:199], v[132:135], v[88:91]
	v_mfma_f32_16x16x32_bf16 v[16:19], v[196:199], v[136:139], v[16:19]
	v_mfma_f32_16x16x32_bf16 v[24:27], v[196:199], v[140:143], v[24:27]
	s_waitcnt lgkmcnt(2)
	v_mfma_f32_16x16x32_bf16 v[84:87], v[200:203], v[128:131], v[84:87]
	v_mfma_f32_16x16x32_bf16 v[92:95], v[200:203], v[132:135], v[92:95]
	v_mfma_f32_16x16x32_bf16 v[20:23], v[200:203], v[136:139], v[20:23]
	v_mfma_f32_16x16x32_bf16 v[28:31], v[200:203], v[140:143], v[28:31]
	s_waitcnt lgkmcnt(1)
	v_mfma_f32_16x16x32_bf16 v[64:67], v[204:207], v[128:131], v[64:67]
	v_mfma_f32_16x16x32_bf16 v[72:75], v[204:207], v[132:135], v[72:75]
	v_mfma_f32_16x16x32_bf16 v[0:3], v[204:207], v[136:139], v[0:3]
	v_mfma_f32_16x16x32_bf16 v[8:11], v[204:207], v[140:143], v[8:11]
	s_waitcnt lgkmcnt(0)
	v_mfma_f32_16x16x32_bf16 v[68:71], v[242:245], v[128:131], v[68:71]
	v_mfma_f32_16x16x32_bf16 v[76:79], v[242:245], v[132:135], v[76:79]
	v_mfma_f32_16x16x32_bf16 v[4:7], v[242:245], v[136:139], v[4:7]
	v_mfma_f32_16x16x32_bf16 v[12:15], v[242:245], v[140:143], v[12:15]
	global_load_dwordx4 v[128:131], v[248:249], off
	global_load_dwordx4 v[132:135], v[248:249], off offset:256
	global_load_dwordx4 v[136:139], v[250:251], off
	global_load_dwordx4 v[140:143], v[250:251], off offset:256
	s_waitcnt vmcnt(10)
	s_barrier
	s_add_i32 s9, s8, 3
	s_lshl_b32 s96, s9, 13
	s_mov_b32 m0, vcc_lo
	v_lshl_add_u64 v[160:161], v[188:189], 0, s[96:97]
	global_load_lds_dwordx4 v[160:161], off
	global_load_lds_dwordx4 v[160:161], off offset:1024
	ds_read_b128 v[196:199], v246 offset:8192
	ds_read_b128 v[200:203], v162 offset:8192
	ds_read_b128 v[204:207], v246 offset:10240
	ds_read_b128 v[242:245], v162 offset:10240
	s_add_i32 s9, s8, 3
	s_lshl_b32 s96, s9, 11
	v_lshl_add_u64 v[248:249], v[184:185], 0, s[96:97]
	v_lshl_add_u64 v[250:251], v[186:187], 0, s[96:97]
	s_waitcnt vmcnt(8) lgkmcnt(3)
	v_mfma_f32_16x16x32_bf16 v[112:115], v[196:199], v[144:147], v[112:115]
	v_mfma_f32_16x16x32_bf16 v[120:123], v[196:199], v[148:151], v[120:123]
	v_mfma_f32_16x16x32_bf16 v[48:51], v[196:199], v[152:155], v[48:51]
	v_mfma_f32_16x16x32_bf16 v[56:59], v[196:199], v[156:159], v[56:59]
	ds_read_b128 v[196:199], v246 offset:12288
	s_waitcnt lgkmcnt(3)
	v_mfma_f32_16x16x32_bf16 v[116:119], v[200:203], v[144:147], v[116:119]
	v_mfma_f32_16x16x32_bf16 v[124:127], v[200:203], v[148:151], v[124:127]
	v_mfma_f32_16x16x32_bf16 v[52:55], v[200:203], v[152:155], v[52:55]
	v_mfma_f32_16x16x32_bf16 v[60:63], v[200:203], v[156:159], v[60:63]
	ds_read_b128 v[200:203], v162 offset:12288
	s_waitcnt lgkmcnt(3)
	v_mfma_f32_16x16x32_bf16 v[96:99], v[204:207], v[144:147], v[96:99]
	v_mfma_f32_16x16x32_bf16 v[104:107], v[204:207], v[148:151], v[104:107]
	v_mfma_f32_16x16x32_bf16 v[32:35], v[204:207], v[152:155], v[32:35]
	v_mfma_f32_16x16x32_bf16 v[40:43], v[204:207], v[156:159], v[40:43]
	ds_read_b128 v[204:207], v246 offset:14336
	s_waitcnt lgkmcnt(3)
	v_mfma_f32_16x16x32_bf16 v[100:103], v[242:245], v[144:147], v[100:103]
	v_mfma_f32_16x16x32_bf16 v[108:111], v[242:245], v[148:151], v[108:111]
	v_mfma_f32_16x16x32_bf16 v[36:39], v[242:245], v[152:155], v[36:39]
	v_mfma_f32_16x16x32_bf16 v[44:47], v[242:245], v[156:159], v[44:47]
	ds_read_b128 v[242:245], v162 offset:14336
	s_waitcnt lgkmcnt(3)
	v_mfma_f32_16x16x32_bf16 v[80:83], v[196:199], v[144:147], v[80:83]
	v_mfma_f32_16x16x32_bf16 v[88:91], v[196:199], v[148:151], v[88:91]
	v_mfma_f32_16x16x32_bf16 v[16:19], v[196:199], v[152:155], v[16:19]
	v_mfma_f32_16x16x32_bf16 v[24:27], v[196:199], v[156:159], v[24:27]
	s_waitcnt lgkmcnt(2)
	v_mfma_f32_16x16x32_bf16 v[84:87], v[200:203], v[144:147], v[84:87]
	v_mfma_f32_16x16x32_bf16 v[92:95], v[200:203], v[148:151], v[92:95]
	v_mfma_f32_16x16x32_bf16 v[20:23], v[200:203], v[152:155], v[20:23]
	v_mfma_f32_16x16x32_bf16 v[28:31], v[200:203], v[156:159], v[28:31]
	s_waitcnt lgkmcnt(1)
	v_mfma_f32_16x16x32_bf16 v[64:67], v[204:207], v[144:147], v[64:67]
	v_mfma_f32_16x16x32_bf16 v[72:75], v[204:207], v[148:151], v[72:75]
	v_mfma_f32_16x16x32_bf16 v[0:3], v[204:207], v[152:155], v[0:3]
	v_mfma_f32_16x16x32_bf16 v[8:11], v[204:207], v[156:159], v[8:11]
	s_waitcnt lgkmcnt(0)
	v_mfma_f32_16x16x32_bf16 v[68:71], v[242:245], v[144:147], v[68:71]
	v_mfma_f32_16x16x32_bf16 v[76:79], v[242:245], v[148:151], v[76:79]
	v_mfma_f32_16x16x32_bf16 v[4:7], v[242:245], v[152:155], v[4:7]
	v_mfma_f32_16x16x32_bf16 v[12:15], v[242:245], v[156:159], v[12:15]
	global_load_dwordx4 v[144:147], v[248:249], off
	global_load_dwordx4 v[148:151], v[248:249], off offset:256
	global_load_dwordx4 v[152:155], v[250:251], off
	global_load_dwordx4 v[156:159], v[250:251], off offset:256
	s_waitcnt vmcnt(10)
	s_barrier
	s_add_i32 s9, s8, 4
	s_lshl_b32 s96, s9, 13
	s_add_i32 m0, vcc_lo, 8192
	v_lshl_add_u64 v[160:161], v[188:189], 0, s[96:97]
	global_load_lds_dwordx4 v[160:161], off
	global_load_lds_dwordx4 v[160:161], off offset:1024
	ds_read_b128 v[196:199], v246 offset:16384
	ds_read_b128 v[200:203], v162 offset:16384
	ds_read_b128 v[204:207], v246 offset:18432
	ds_read_b128 v[242:245], v162 offset:18432
	s_add_i32 s9, s8, 4
	s_lshl_b32 s96, s9, 11
	v_lshl_add_u64 v[248:249], v[184:185], 0, s[96:97]
	v_lshl_add_u64 v[250:251], v[186:187], 0, s[96:97]
	s_waitcnt vmcnt(8) lgkmcnt(3)
	v_mfma_f32_16x16x32_bf16 v[112:115], v[196:199], v[128:131], v[112:115]
	v_mfma_f32_16x16x32_bf16 v[120:123], v[196:199], v[132:135], v[120:123]
	v_mfma_f32_16x16x32_bf16 v[48:51], v[196:199], v[136:139], v[48:51]
	v_mfma_f32_16x16x32_bf16 v[56:59], v[196:199], v[140:143], v[56:59]
	ds_read_b128 v[196:199], v246 offset:20480
	s_waitcnt lgkmcnt(3)
	v_mfma_f32_16x16x32_bf16 v[116:119], v[200:203], v[128:131], v[116:119]
	v_mfma_f32_16x16x32_bf16 v[124:127], v[200:203], v[132:135], v[124:127]
	v_mfma_f32_16x16x32_bf16 v[52:55], v[200:203], v[136:139], v[52:55]
	v_mfma_f32_16x16x32_bf16 v[60:63], v[200:203], v[140:143], v[60:63]
	ds_read_b128 v[200:203], v162 offset:20480
	s_waitcnt lgkmcnt(3)
	v_mfma_f32_16x16x32_bf16 v[96:99], v[204:207], v[128:131], v[96:99]
	v_mfma_f32_16x16x32_bf16 v[104:107], v[204:207], v[132:135], v[104:107]
	v_mfma_f32_16x16x32_bf16 v[32:35], v[204:207], v[136:139], v[32:35]
	v_mfma_f32_16x16x32_bf16 v[40:43], v[204:207], v[140:143], v[40:43]
	ds_read_b128 v[204:207], v246 offset:22528
	s_waitcnt lgkmcnt(3)
	v_mfma_f32_16x16x32_bf16 v[100:103], v[242:245], v[128:131], v[100:103]
	v_mfma_f32_16x16x32_bf16 v[108:111], v[242:245], v[132:135], v[108:111]
	v_mfma_f32_16x16x32_bf16 v[36:39], v[242:245], v[136:139], v[36:39]
	v_mfma_f32_16x16x32_bf16 v[44:47], v[242:245], v[140:143], v[44:47]
	ds_read_b128 v[242:245], v162 offset:22528
	s_waitcnt lgkmcnt(3)
	v_mfma_f32_16x16x32_bf16 v[80:83], v[196:199], v[128:131], v[80:83]
	v_mfma_f32_16x16x32_bf16 v[88:91], v[196:199], v[132:135], v[88:91]
	v_mfma_f32_16x16x32_bf16 v[16:19], v[196:199], v[136:139], v[16:19]
	v_mfma_f32_16x16x32_bf16 v[24:27], v[196:199], v[140:143], v[24:27]
	s_waitcnt lgkmcnt(2)
	v_mfma_f32_16x16x32_bf16 v[84:87], v[200:203], v[128:131], v[84:87]
	v_mfma_f32_16x16x32_bf16 v[92:95], v[200:203], v[132:135], v[92:95]
	v_mfma_f32_16x16x32_bf16 v[20:23], v[200:203], v[136:139], v[20:23]
	v_mfma_f32_16x16x32_bf16 v[28:31], v[200:203], v[140:143], v[28:31]
	s_waitcnt lgkmcnt(1)
	v_mfma_f32_16x16x32_bf16 v[64:67], v[204:207], v[128:131], v[64:67]
	v_mfma_f32_16x16x32_bf16 v[72:75], v[204:207], v[132:135], v[72:75]
	v_mfma_f32_16x16x32_bf16 v[0:3], v[204:207], v[136:139], v[0:3]
	v_mfma_f32_16x16x32_bf16 v[8:11], v[204:207], v[140:143], v[8:11]
	s_waitcnt lgkmcnt(0)
	v_mfma_f32_16x16x32_bf16 v[68:71], v[242:245], v[128:131], v[68:71]
	v_mfma_f32_16x16x32_bf16 v[76:79], v[242:245], v[132:135], v[76:79]
	v_mfma_f32_16x16x32_bf16 v[4:7], v[242:245], v[136:139], v[4:7]
	v_mfma_f32_16x16x32_bf16 v[12:15], v[242:245], v[140:143], v[12:15]
	global_load_dwordx4 v[128:131], v[248:249], off
	global_load_dwordx4 v[132:135], v[248:249], off offset:256
	global_load_dwordx4 v[136:139], v[250:251], off
	global_load_dwordx4 v[140:143], v[250:251], off offset:256
	s_waitcnt vmcnt(10)
	s_barrier
	s_add_i32 s9, s8, 5
	s_lshl_b32 s96, s9, 13
	s_add_i32 m0, vcc_lo, 16384
	v_lshl_add_u64 v[160:161], v[188:189], 0, s[96:97]
	global_load_lds_dwordx4 v[160:161], off
	global_load_lds_dwordx4 v[160:161], off offset:1024
	ds_read_b128 v[196:199], v246 offset:0
	ds_read_b128 v[200:203], v162 offset:0
	ds_read_b128 v[204:207], v246 offset:2048
	ds_read_b128 v[242:245], v162 offset:2048
	s_add_i32 s9, s8, 5
	s_lshl_b32 s96, s9, 11
	v_lshl_add_u64 v[248:249], v[184:185], 0, s[96:97]
	v_lshl_add_u64 v[250:251], v[186:187], 0, s[96:97]
	s_waitcnt vmcnt(8) lgkmcnt(3)
	v_mfma_f32_16x16x32_bf16 v[112:115], v[196:199], v[144:147], v[112:115]
	v_mfma_f32_16x16x32_bf16 v[120:123], v[196:199], v[148:151], v[120:123]
	v_mfma_f32_16x16x32_bf16 v[48:51], v[196:199], v[152:155], v[48:51]
	v_mfma_f32_16x16x32_bf16 v[56:59], v[196:199], v[156:159], v[56:59]
	ds_read_b128 v[196:199], v246 offset:4096
	s_waitcnt lgkmcnt(3)
	v_mfma_f32_16x16x32_bf16 v[116:119], v[200:203], v[144:147], v[116:119]
	v_mfma_f32_16x16x32_bf16 v[124:127], v[200:203], v[148:151], v[124:127]
	v_mfma_f32_16x16x32_bf16 v[52:55], v[200:203], v[152:155], v[52:55]
	v_mfma_f32_16x16x32_bf16 v[60:63], v[200:203], v[156:159], v[60:63]
	ds_read_b128 v[200:203], v162 offset:4096
	s_waitcnt lgkmcnt(3)
	v_mfma_f32_16x16x32_bf16 v[96:99], v[204:207], v[144:147], v[96:99]
	v_mfma_f32_16x16x32_bf16 v[104:107], v[204:207], v[148:151], v[104:107]
	v_mfma_f32_16x16x32_bf16 v[32:35], v[204:207], v[152:155], v[32:35]
	v_mfma_f32_16x16x32_bf16 v[40:43], v[204:207], v[156:159], v[40:43]
	ds_read_b128 v[204:207], v246 offset:6144
	s_waitcnt lgkmcnt(3)
	v_mfma_f32_16x16x32_bf16 v[100:103], v[242:245], v[144:147], v[100:103]
	v_mfma_f32_16x16x32_bf16 v[108:111], v[242:245], v[148:151], v[108:111]
	v_mfma_f32_16x16x32_bf16 v[36:39], v[242:245], v[152:155], v[36:39]
	v_mfma_f32_16x16x32_bf16 v[44:47], v[242:245], v[156:159], v[44:47]
	ds_read_b128 v[242:245], v162 offset:6144
	s_waitcnt lgkmcnt(3)
	v_mfma_f32_16x16x32_bf16 v[80:83], v[196:199], v[144:147], v[80:83]
	v_mfma_f32_16x16x32_bf16 v[88:91], v[196:199], v[148:151], v[88:91]
	v_mfma_f32_16x16x32_bf16 v[16:19], v[196:199], v[152:155], v[16:19]
	v_mfma_f32_16x16x32_bf16 v[24:27], v[196:199], v[156:159], v[24:27]
	s_waitcnt lgkmcnt(2)
	v_mfma_f32_16x16x32_bf16 v[84:87], v[200:203], v[144:147], v[84:87]
	v_mfma_f32_16x16x32_bf16 v[92:95], v[200:203], v[148:151], v[92:95]
	v_mfma_f32_16x16x32_bf16 v[20:23], v[200:203], v[152:155], v[20:23]
	v_mfma_f32_16x16x32_bf16 v[28:31], v[200:203], v[156:159], v[28:31]
	s_waitcnt lgkmcnt(1)
	v_mfma_f32_16x16x32_bf16 v[64:67], v[204:207], v[144:147], v[64:67]
	v_mfma_f32_16x16x32_bf16 v[72:75], v[204:207], v[148:151], v[72:75]
	v_mfma_f32_16x16x32_bf16 v[0:3], v[204:207], v[152:155], v[0:3]
	v_mfma_f32_16x16x32_bf16 v[8:11], v[204:207], v[156:159], v[8:11]
	s_waitcnt lgkmcnt(0)
	v_mfma_f32_16x16x32_bf16 v[68:71], v[242:245], v[144:147], v[68:71]
	v_mfma_f32_16x16x32_bf16 v[76:79], v[242:245], v[148:151], v[76:79]
	v_mfma_f32_16x16x32_bf16 v[4:7], v[242:245], v[152:155], v[4:7]
	v_mfma_f32_16x16x32_bf16 v[12:15], v[242:245], v[156:159], v[12:15]
	global_load_dwordx4 v[144:147], v[248:249], off
	global_load_dwordx4 v[148:151], v[248:249], off offset:256
	global_load_dwordx4 v[152:155], v[250:251], off
	global_load_dwordx4 v[156:159], v[250:251], off offset:256
	s_waitcnt vmcnt(10)
	s_barrier
	s_add_i32 s9, s8, 6
	s_lshl_b32 s96, s9, 13
	s_mov_b32 m0, vcc_lo
	v_lshl_add_u64 v[160:161], v[188:189], 0, s[96:97]
	global_load_lds_dwordx4 v[160:161], off
	global_load_lds_dwordx4 v[160:161], off offset:1024
	ds_read_b128 v[196:199], v246 offset:8192
	ds_read_b128 v[200:203], v162 offset:8192
	ds_read_b128 v[204:207], v246 offset:10240
	ds_read_b128 v[242:245], v162 offset:10240
	s_add_i32 s9, s8, 6
	s_lshl_b32 s96, s9, 11
	v_lshl_add_u64 v[248:249], v[184:185], 0, s[96:97]
	v_lshl_add_u64 v[250:251], v[186:187], 0, s[96:97]
	s_waitcnt vmcnt(8) lgkmcnt(3)
	v_mfma_f32_16x16x32_bf16 v[112:115], v[196:199], v[128:131], v[112:115]
	v_mfma_f32_16x16x32_bf16 v[120:123], v[196:199], v[132:135], v[120:123]
	v_mfma_f32_16x16x32_bf16 v[48:51], v[196:199], v[136:139], v[48:51]
	v_mfma_f32_16x16x32_bf16 v[56:59], v[196:199], v[140:143], v[56:59]
	ds_read_b128 v[196:199], v246 offset:12288
	s_waitcnt lgkmcnt(3)
	v_mfma_f32_16x16x32_bf16 v[116:119], v[200:203], v[128:131], v[116:119]
	v_mfma_f32_16x16x32_bf16 v[124:127], v[200:203], v[132:135], v[124:127]
	v_mfma_f32_16x16x32_bf16 v[52:55], v[200:203], v[136:139], v[52:55]
	v_mfma_f32_16x16x32_bf16 v[60:63], v[200:203], v[140:143], v[60:63]
	ds_read_b128 v[200:203], v162 offset:12288
	s_waitcnt lgkmcnt(3)
	v_mfma_f32_16x16x32_bf16 v[96:99], v[204:207], v[128:131], v[96:99]
	v_mfma_f32_16x16x32_bf16 v[104:107], v[204:207], v[132:135], v[104:107]
	v_mfma_f32_16x16x32_bf16 v[32:35], v[204:207], v[136:139], v[32:35]
	v_mfma_f32_16x16x32_bf16 v[40:43], v[204:207], v[140:143], v[40:43]
	ds_read_b128 v[204:207], v246 offset:14336
	s_waitcnt lgkmcnt(3)
	v_mfma_f32_16x16x32_bf16 v[100:103], v[242:245], v[128:131], v[100:103]
	v_mfma_f32_16x16x32_bf16 v[108:111], v[242:245], v[132:135], v[108:111]
	v_mfma_f32_16x16x32_bf16 v[36:39], v[242:245], v[136:139], v[36:39]
	v_mfma_f32_16x16x32_bf16 v[44:47], v[242:245], v[140:143], v[44:47]
	ds_read_b128 v[242:245], v162 offset:14336
	s_waitcnt lgkmcnt(3)
	v_mfma_f32_16x16x32_bf16 v[80:83], v[196:199], v[128:131], v[80:83]
	v_mfma_f32_16x16x32_bf16 v[88:91], v[196:199], v[132:135], v[88:91]
	v_mfma_f32_16x16x32_bf16 v[16:19], v[196:199], v[136:139], v[16:19]
	v_mfma_f32_16x16x32_bf16 v[24:27], v[196:199], v[140:143], v[24:27]
	s_waitcnt lgkmcnt(2)
	v_mfma_f32_16x16x32_bf16 v[84:87], v[200:203], v[128:131], v[84:87]
	v_mfma_f32_16x16x32_bf16 v[92:95], v[200:203], v[132:135], v[92:95]
	v_mfma_f32_16x16x32_bf16 v[20:23], v[200:203], v[136:139], v[20:23]
	v_mfma_f32_16x16x32_bf16 v[28:31], v[200:203], v[140:143], v[28:31]
	s_waitcnt lgkmcnt(1)
	v_mfma_f32_16x16x32_bf16 v[64:67], v[204:207], v[128:131], v[64:67]
	v_mfma_f32_16x16x32_bf16 v[72:75], v[204:207], v[132:135], v[72:75]
	v_mfma_f32_16x16x32_bf16 v[0:3], v[204:207], v[136:139], v[0:3]
	v_mfma_f32_16x16x32_bf16 v[8:11], v[204:207], v[140:143], v[8:11]
	s_waitcnt lgkmcnt(0)
	v_mfma_f32_16x16x32_bf16 v[68:71], v[242:245], v[128:131], v[68:71]
	v_mfma_f32_16x16x32_bf16 v[76:79], v[242:245], v[132:135], v[76:79]
	v_mfma_f32_16x16x32_bf16 v[4:7], v[242:245], v[136:139], v[4:7]
	v_mfma_f32_16x16x32_bf16 v[12:15], v[242:245], v[140:143], v[12:15]
	global_load_dwordx4 v[128:131], v[248:249], off
	global_load_dwordx4 v[132:135], v[248:249], off offset:256
	global_load_dwordx4 v[136:139], v[250:251], off
	global_load_dwordx4 v[140:143], v[250:251], off offset:256
	s_waitcnt vmcnt(10)
	s_barrier
	s_add_i32 s9, s8, 7
	s_lshl_b32 s96, s9, 13
	s_add_i32 m0, vcc_lo, 8192
	v_lshl_add_u64 v[160:161], v[188:189], 0, s[96:97]
	global_load_lds_dwordx4 v[160:161], off
	global_load_lds_dwordx4 v[160:161], off offset:1024
	ds_read_b128 v[196:199], v246 offset:16384
	ds_read_b128 v[200:203], v162 offset:16384
	ds_read_b128 v[204:207], v246 offset:18432
	ds_read_b128 v[242:245], v162 offset:18432
	s_add_i32 s9, s8, 7
	s_lshl_b32 s96, s9, 11
	v_lshl_add_u64 v[248:249], v[184:185], 0, s[96:97]
	v_lshl_add_u64 v[250:251], v[186:187], 0, s[96:97]
	s_waitcnt vmcnt(8) lgkmcnt(3)
	v_mfma_f32_16x16x32_bf16 v[112:115], v[196:199], v[144:147], v[112:115]
	v_mfma_f32_16x16x32_bf16 v[120:123], v[196:199], v[148:151], v[120:123]
	v_mfma_f32_16x16x32_bf16 v[48:51], v[196:199], v[152:155], v[48:51]
	v_mfma_f32_16x16x32_bf16 v[56:59], v[196:199], v[156:159], v[56:59]
	ds_read_b128 v[196:199], v246 offset:20480
	s_waitcnt lgkmcnt(3)
	v_mfma_f32_16x16x32_bf16 v[116:119], v[200:203], v[144:147], v[116:119]
	v_mfma_f32_16x16x32_bf16 v[124:127], v[200:203], v[148:151], v[124:127]
	v_mfma_f32_16x16x32_bf16 v[52:55], v[200:203], v[152:155], v[52:55]
	v_mfma_f32_16x16x32_bf16 v[60:63], v[200:203], v[156:159], v[60:63]
	ds_read_b128 v[200:203], v162 offset:20480
	s_waitcnt lgkmcnt(3)
	v_mfma_f32_16x16x32_bf16 v[96:99], v[204:207], v[144:147], v[96:99]
	v_mfma_f32_16x16x32_bf16 v[104:107], v[204:207], v[148:151], v[104:107]
	v_mfma_f32_16x16x32_bf16 v[32:35], v[204:207], v[152:155], v[32:35]
	v_mfma_f32_16x16x32_bf16 v[40:43], v[204:207], v[156:159], v[40:43]
	ds_read_b128 v[204:207], v246 offset:22528
	s_waitcnt lgkmcnt(3)
	v_mfma_f32_16x16x32_bf16 v[100:103], v[242:245], v[144:147], v[100:103]
	v_mfma_f32_16x16x32_bf16 v[108:111], v[242:245], v[148:151], v[108:111]
	v_mfma_f32_16x16x32_bf16 v[36:39], v[242:245], v[152:155], v[36:39]
	v_mfma_f32_16x16x32_bf16 v[44:47], v[242:245], v[156:159], v[44:47]
	ds_read_b128 v[242:245], v162 offset:22528
	s_waitcnt lgkmcnt(3)
	v_mfma_f32_16x16x32_bf16 v[80:83], v[196:199], v[144:147], v[80:83]
	v_mfma_f32_16x16x32_bf16 v[88:91], v[196:199], v[148:151], v[88:91]
	v_mfma_f32_16x16x32_bf16 v[16:19], v[196:199], v[152:155], v[16:19]
	v_mfma_f32_16x16x32_bf16 v[24:27], v[196:199], v[156:159], v[24:27]
	s_waitcnt lgkmcnt(2)
	v_mfma_f32_16x16x32_bf16 v[84:87], v[200:203], v[144:147], v[84:87]
	v_mfma_f32_16x16x32_bf16 v[92:95], v[200:203], v[148:151], v[92:95]
	v_mfma_f32_16x16x32_bf16 v[20:23], v[200:203], v[152:155], v[20:23]
	v_mfma_f32_16x16x32_bf16 v[28:31], v[200:203], v[156:159], v[28:31]
	s_waitcnt lgkmcnt(1)
	v_mfma_f32_16x16x32_bf16 v[64:67], v[204:207], v[144:147], v[64:67]
	v_mfma_f32_16x16x32_bf16 v[72:75], v[204:207], v[148:151], v[72:75]
	v_mfma_f32_16x16x32_bf16 v[0:3], v[204:207], v[152:155], v[0:3]
	v_mfma_f32_16x16x32_bf16 v[8:11], v[204:207], v[156:159], v[8:11]
	s_waitcnt lgkmcnt(0)
	v_mfma_f32_16x16x32_bf16 v[68:71], v[242:245], v[144:147], v[68:71]
	v_mfma_f32_16x16x32_bf16 v[76:79], v[242:245], v[148:151], v[76:79]
	v_mfma_f32_16x16x32_bf16 v[4:7], v[242:245], v[152:155], v[4:7]
	v_mfma_f32_16x16x32_bf16 v[12:15], v[242:245], v[156:159], v[12:15]
	global_load_dwordx4 v[144:147], v[248:249], off
	global_load_dwordx4 v[148:151], v[248:249], off offset:256
	global_load_dwordx4 v[152:155], v[250:251], off
	global_load_dwordx4 v[156:159], v[250:251], off offset:256
	s_waitcnt vmcnt(10)
	s_barrier
	s_add_i32 s8, s8, 6
	s_cmp_lt_u32 s8, 84
	s_cbranch_scc1 .Lg16_down_k
	s_mov_b32 s96, 0xac000
	s_add_i32 m0, vcc_lo, 16384
	v_lshl_add_u64 v[160:161], v[188:189], 0, s[96:97]
	global_load_lds_dwordx4 v[160:161], off
	global_load_lds_dwordx4 v[160:161], off offset:1024
	ds_read_b128 v[196:199], v246 offset:0
	ds_read_b128 v[200:203], v162 offset:0
	ds_read_b128 v[204:207], v246 offset:2048
	ds_read_b128 v[242:245], v162 offset:2048
	s_mov_b32 s96, 0x2b000
	v_lshl_add_u64 v[248:249], v[184:185], 0, s[96:97]
	v_lshl_add_u64 v[250:251], v[186:187], 0, s[96:97]
	s_waitcnt vmcnt(8) lgkmcnt(3)
	v_mfma_f32_16x16x32_bf16 v[112:115], v[196:199], v[128:131], v[112:115]
	v_mfma_f32_16x16x32_bf16 v[120:123], v[196:199], v[132:135], v[120:123]
	v_mfma_f32_16x16x32_bf16 v[48:51], v[196:199], v[136:139], v[48:51]
	v_mfma_f32_16x16x32_bf16 v[56:59], v[196:199], v[140:143], v[56:59]
	ds_read_b128 v[196:199], v246 offset:4096
	s_waitcnt lgkmcnt(3)
	v_mfma_f32_16x16x32_bf16 v[116:119], v[200:203], v[128:131], v[116:119]
	v_mfma_f32_16x16x32_bf16 v[124:127], v[200:203], v[132:135], v[124:127]
	v_mfma_f32_16x16x32_bf16 v[52:55], v[200:203], v[136:139], v[52:55]
	v_mfma_f32_16x16x32_bf16 v[60:63], v[200:203], v[140:143], v[60:63]
	ds_read_b128 v[200:203], v162 offset:4096
	s_waitcnt lgkmcnt(3)
	v_mfma_f32_16x16x32_bf16 v[96:99], v[204:207], v[128:131], v[96:99]
	v_mfma_f32_16x16x32_bf16 v[104:107], v[204:207], v[132:135], v[104:107]
	v_mfma_f32_16x16x32_bf16 v[32:35], v[204:207], v[136:139], v[32:35]
	v_mfma_f32_16x16x32_bf16 v[40:43], v[204:207], v[140:143], v[40:43]
	ds_read_b128 v[204:207], v246 offset:6144
	s_waitcnt lgkmcnt(3)
	v_mfma_f32_16x16x32_bf16 v[100:103], v[242:245], v[128:131], v[100:103]
	v_mfma_f32_16x16x32_bf16 v[108:111], v[242:245], v[132:135], v[108:111]
	v_mfma_f32_16x16x32_bf16 v[36:39], v[242:245], v[136:139], v[36:39]
	v_mfma_f32_16x16x32_bf16 v[44:47], v[242:245], v[140:143], v[44:47]
	ds_read_b128 v[242:245], v162 offset:6144
	s_waitcnt lgkmcnt(3)
	v_mfma_f32_16x16x32_bf16 v[80:83], v[196:199], v[128:131], v[80:83]
	v_mfma_f32_16x16x32_bf16 v[88:91], v[196:199], v[132:135], v[88:91]
	v_mfma_f32_16x16x32_bf16 v[16:19], v[196:199], v[136:139], v[16:19]
	v_mfma_f32_16x16x32_bf16 v[24:27], v[196:199], v[140:143], v[24:27]
	s_waitcnt lgkmcnt(2)
	v_mfma_f32_16x16x32_bf16 v[84:87], v[200:203], v[128:131], v[84:87]
	v_mfma_f32_16x16x32_bf16 v[92:95], v[200:203], v[132:135], v[92:95]
	v_mfma_f32_16x16x32_bf16 v[20:23], v[200:203], v[136:139], v[20:23]
	v_mfma_f32_16x16x32_bf16 v[28:31], v[200:203], v[140:143], v[28:31]
	s_waitcnt lgkmcnt(1)
	v_mfma_f32_16x16x32_bf16 v[64:67], v[204:207], v[128:131], v[64:67]
	v_mfma_f32_16x16x32_bf16 v[72:75], v[204:207], v[132:135], v[72:75]
	v_mfma_f32_16x16x32_bf16 v[0:3], v[204:207], v[136:139], v[0:3]
	v_mfma_f32_16x16x32_bf16 v[8:11], v[204:207], v[140:143], v[8:11]
	s_waitcnt lgkmcnt(0)
	v_mfma_f32_16x16x32_bf16 v[68:71], v[242:245], v[128:131], v[68:71]
	v_mfma_f32_16x16x32_bf16 v[76:79], v[242:245], v[132:135], v[76:79]
	v_mfma_f32_16x16x32_bf16 v[4:7], v[242:245], v[136:139], v[4:7]
	v_mfma_f32_16x16x32_bf16 v[12:15], v[242:245], v[140:143], v[12:15]
	global_load_dwordx4 v[128:131], v[248:249], off
	global_load_dwordx4 v[132:135], v[248:249], off offset:256
	global_load_dwordx4 v[136:139], v[250:251], off
	global_load_dwordx4 v[140:143], v[250:251], off offset:256
	s_waitcnt vmcnt(10)
	s_barrier
	s_mov_b32 s96, 0xae000
	s_mov_b32 m0, vcc_lo
	v_lshl_add_u64 v[160:161], v[188:189], 0, s[96:97]
	global_load_lds_dwordx4 v[160:161], off
	global_load_lds_dwordx4 v[160:161], off offset:1024
	ds_read_b128 v[196:199], v246 offset:8192
	ds_read_b128 v[200:203], v162 offset:8192
	ds_read_b128 v[204:207], v246 offset:10240
	ds_read_b128 v[242:245], v162 offset:10240
	s_mov_b32 s96, 0x2b800
	v_lshl_add_u64 v[248:249], v[184:185], 0, s[96:97]
	v_lshl_add_u64 v[250:251], v[186:187], 0, s[96:97]
	s_waitcnt vmcnt(8) lgkmcnt(3)
	v_mfma_f32_16x16x32_bf16 v[112:115], v[196:199], v[144:147], v[112:115]
	v_mfma_f32_16x16x32_bf16 v[120:123], v[196:199], v[148:151], v[120:123]
	v_mfma_f32_16x16x32_bf16 v[48:51], v[196:199], v[152:155], v[48:51]
	v_mfma_f32_16x16x32_bf16 v[56:59], v[196:199], v[156:159], v[56:59]
	ds_read_b128 v[196:199], v246 offset:12288
	s_waitcnt lgkmcnt(3)
	v_mfma_f32_16x16x32_bf16 v[116:119], v[200:203], v[144:147], v[116:119]
	v_mfma_f32_16x16x32_bf16 v[124:127], v[200:203], v[148:151], v[124:127]
	v_mfma_f32_16x16x32_bf16 v[52:55], v[200:203], v[152:155], v[52:55]
	v_mfma_f32_16x16x32_bf16 v[60:63], v[200:203], v[156:159], v[60:63]
	ds_read_b128 v[200:203], v162 offset:12288
	s_waitcnt lgkmcnt(3)
	v_mfma_f32_16x16x32_bf16 v[96:99], v[204:207], v[144:147], v[96:99]
	v_mfma_f32_16x16x32_bf16 v[104:107], v[204:207], v[148:151], v[104:107]
	v_mfma_f32_16x16x32_bf16 v[32:35], v[204:207], v[152:155], v[32:35]
	v_mfma_f32_16x16x32_bf16 v[40:43], v[204:207], v[156:159], v[40:43]
	ds_read_b128 v[204:207], v246 offset:14336
	s_waitcnt lgkmcnt(3)
	v_mfma_f32_16x16x32_bf16 v[100:103], v[242:245], v[144:147], v[100:103]
	v_mfma_f32_16x16x32_bf16 v[108:111], v[242:245], v[148:151], v[108:111]
	v_mfma_f32_16x16x32_bf16 v[36:39], v[242:245], v[152:155], v[36:39]
	v_mfma_f32_16x16x32_bf16 v[44:47], v[242:245], v[156:159], v[44:47]
	ds_read_b128 v[242:245], v162 offset:14336
	s_waitcnt lgkmcnt(3)
	v_mfma_f32_16x16x32_bf16 v[80:83], v[196:199], v[144:147], v[80:83]
	v_mfma_f32_16x16x32_bf16 v[88:91], v[196:199], v[148:151], v[88:91]
	v_mfma_f32_16x16x32_bf16 v[16:19], v[196:199], v[152:155], v[16:19]
	v_mfma_f32_16x16x32_bf16 v[24:27], v[196:199], v[156:159], v[24:27]
	s_waitcnt lgkmcnt(2)
	v_mfma_f32_16x16x32_bf16 v[84:87], v[200:203], v[144:147], v[84:87]
	v_mfma_f32_16x16x32_bf16 v[92:95], v[200:203], v[148:151], v[92:95]
	v_mfma_f32_16x16x32_bf16 v[20:23], v[200:203], v[152:155], v[20:23]
	v_mfma_f32_16x16x32_bf16 v[28:31], v[200:203], v[156:159], v[28:31]
	s_waitcnt lgkmcnt(1)
	v_mfma_f32_16x16x32_bf16 v[64:67], v[204:207], v[144:147], v[64:67]
	v_mfma_f32_16x16x32_bf16 v[72:75], v[204:207], v[148:151], v[72:75]
	v_mfma_f32_16x16x32_bf16 v[0:3], v[204:207], v[152:155], v[0:3]
	v_mfma_f32_16x16x32_bf16 v[8:11], v[204:207], v[156:159], v[8:11]
	s_waitcnt lgkmcnt(0)
	v_mfma_f32_16x16x32_bf16 v[68:71], v[242:245], v[144:147], v[68:71]
	v_mfma_f32_16x16x32_bf16 v[76:79], v[242:245], v[148:151], v[76:79]
	v_mfma_f32_16x16x32_bf16 v[4:7], v[242:245], v[152:155], v[4:7]
	v_mfma_f32_16x16x32_bf16 v[12:15], v[242:245], v[156:159], v[12:15]
	global_load_dwordx4 v[144:147], v[248:249], off
	global_load_dwordx4 v[148:151], v[248:249], off offset:256
	global_load_dwordx4 v[152:155], v[250:251], off
	global_load_dwordx4 v[156:159], v[250:251], off offset:256
	s_waitcnt vmcnt(10)
	s_barrier
	ds_read_b128 v[196:199], v246 offset:16384
	ds_read_b128 v[200:203], v162 offset:16384
	ds_read_b128 v[204:207], v246 offset:18432
	ds_read_b128 v[242:245], v162 offset:18432
	s_waitcnt vmcnt(6) lgkmcnt(3)
	v_mfma_f32_16x16x32_bf16 v[112:115], v[196:199], v[128:131], v[112:115]
	v_mfma_f32_16x16x32_bf16 v[120:123], v[196:199], v[132:135], v[120:123]
	v_mfma_f32_16x16x32_bf16 v[48:51], v[196:199], v[136:139], v[48:51]
	v_mfma_f32_16x16x32_bf16 v[56:59], v[196:199], v[140:143], v[56:59]
	ds_read_b128 v[196:199], v246 offset:20480
	s_waitcnt lgkmcnt(3)
	v_mfma_f32_16x16x32_bf16 v[116:119], v[200:203], v[128:131], v[116:119]
	v_mfma_f32_16x16x32_bf16 v[124:127], v[200:203], v[132:135], v[124:127]
	v_mfma_f32_16x16x32_bf16 v[52:55], v[200:203], v[136:139], v[52:55]
	v_mfma_f32_16x16x32_bf16 v[60:63], v[200:203], v[140:143], v[60:63]
	ds_read_b128 v[200:203], v162 offset:20480
	s_waitcnt lgkmcnt(3)
	v_mfma_f32_16x16x32_bf16 v[96:99], v[204:207], v[128:131], v[96:99]
	v_mfma_f32_16x16x32_bf16 v[104:107], v[204:207], v[132:135], v[104:107]
	v_mfma_f32_16x16x32_bf16 v[32:35], v[204:207], v[136:139], v[32:35]
	v_mfma_f32_16x16x32_bf16 v[40:43], v[204:207], v[140:143], v[40:43]
	ds_read_b128 v[204:207], v246 offset:22528
	s_waitcnt lgkmcnt(3)
	v_mfma_f32_16x16x32_bf16 v[100:103], v[242:245], v[128:131], v[100:103]
	v_mfma_f32_16x16x32_bf16 v[108:111], v[242:245], v[132:135], v[108:111]
	v_mfma_f32_16x16x32_bf16 v[36:39], v[242:245], v[136:139], v[36:39]
	v_mfma_f32_16x16x32_bf16 v[44:47], v[242:245], v[140:143], v[44:47]
	ds_read_b128 v[242:245], v162 offset:22528
	s_waitcnt lgkmcnt(3)
	v_mfma_f32_16x16x32_bf16 v[80:83], v[196:199], v[128:131], v[80:83]
	v_mfma_f32_16x16x32_bf16 v[88:91], v[196:199], v[132:135], v[88:91]
	v_mfma_f32_16x16x32_bf16 v[16:19], v[196:199], v[136:139], v[16:19]
	v_mfma_f32_16x16x32_bf16 v[24:27], v[196:199], v[140:143], v[24:27]
	s_waitcnt lgkmcnt(2)
	v_mfma_f32_16x16x32_bf16 v[84:87], v[200:203], v[128:131], v[84:87]
	v_mfma_f32_16x16x32_bf16 v[92:95], v[200:203], v[132:135], v[92:95]
	v_mfma_f32_16x16x32_bf16 v[20:23], v[200:203], v[136:139], v[20:23]
	v_mfma_f32_16x16x32_bf16 v[28:31], v[200:203], v[140:143], v[28:31]
	s_waitcnt lgkmcnt(1)
	v_mfma_f32_16x16x32_bf16 v[64:67], v[204:207], v[128:131], v[64:67]
	v_mfma_f32_16x16x32_bf16 v[72:75], v[204:207], v[132:135], v[72:75]
	v_mfma_f32_16x16x32_bf16 v[0:3], v[204:207], v[136:139], v[0:3]
	v_mfma_f32_16x16x32_bf16 v[8:11], v[204:207], v[140:143], v[8:11]
	s_waitcnt lgkmcnt(0)
	v_mfma_f32_16x16x32_bf16 v[68:71], v[242:245], v[128:131], v[68:71]
	v_mfma_f32_16x16x32_bf16 v[76:79], v[242:245], v[132:135], v[76:79]
	v_mfma_f32_16x16x32_bf16 v[4:7], v[242:245], v[136:139], v[4:7]
	v_mfma_f32_16x16x32_bf16 v[12:15], v[242:245], v[140:143], v[12:15]
	s_waitcnt vmcnt(4)
	s_barrier
	ds_read_b128 v[196:199], v246 offset:0
	ds_read_b128 v[200:203], v162 offset:0
	ds_read_b128 v[204:207], v246 offset:2048
	ds_read_b128 v[242:245], v162 offset:2048
	s_waitcnt vmcnt(0) lgkmcnt(3)
	v_mfma_f32_16x16x32_bf16 v[112:115], v[196:199], v[144:147], v[112:115]
	v_mfma_f32_16x16x32_bf16 v[120:123], v[196:199], v[148:151], v[120:123]
	v_mfma_f32_16x16x32_bf16 v[48:51], v[196:199], v[152:155], v[48:51]
	v_mfma_f32_16x16x32_bf16 v[56:59], v[196:199], v[156:159], v[56:59]
	ds_read_b128 v[196:199], v246 offset:4096
	s_waitcnt lgkmcnt(3)
	v_mfma_f32_16x16x32_bf16 v[116:119], v[200:203], v[144:147], v[116:119]
	v_mfma_f32_16x16x32_bf16 v[124:127], v[200:203], v[148:151], v[124:127]
	v_mfma_f32_16x16x32_bf16 v[52:55], v[200:203], v[152:155], v[52:55]
	v_mfma_f32_16x16x32_bf16 v[60:63], v[200:203], v[156:159], v[60:63]
	ds_read_b128 v[200:203], v162 offset:4096
	s_waitcnt lgkmcnt(3)
	v_mfma_f32_16x16x32_bf16 v[96:99], v[204:207], v[144:147], v[96:99]
	v_mfma_f32_16x16x32_bf16 v[104:107], v[204:207], v[148:151], v[104:107]
	v_mfma_f32_16x16x32_bf16 v[32:35], v[204:207], v[152:155], v[32:35]
	v_mfma_f32_16x16x32_bf16 v[40:43], v[204:207], v[156:159], v[40:43]
	ds_read_b128 v[204:207], v246 offset:6144
	s_waitcnt lgkmcnt(3)
	v_mfma_f32_16x16x32_bf16 v[100:103], v[242:245], v[144:147], v[100:103]
	v_mfma_f32_16x16x32_bf16 v[108:111], v[242:245], v[148:151], v[108:111]
	v_mfma_f32_16x16x32_bf16 v[36:39], v[242:245], v[152:155], v[36:39]
	v_mfma_f32_16x16x32_bf16 v[44:47], v[242:245], v[156:159], v[44:47]
	ds_read_b128 v[242:245], v162 offset:6144
	s_waitcnt lgkmcnt(3)
	v_mfma_f32_16x16x32_bf16 v[80:83], v[196:199], v[144:147], v[80:83]
	v_mfma_f32_16x16x32_bf16 v[88:91], v[196:199], v[148:151], v[88:91]
	v_mfma_f32_16x16x32_bf16 v[16:19], v[196:199], v[152:155], v[16:19]
	v_mfma_f32_16x16x32_bf16 v[24:27], v[196:199], v[156:159], v[24:27]
	s_waitcnt lgkmcnt(2)
	v_mfma_f32_16x16x32_bf16 v[84:87], v[200:203], v[144:147], v[84:87]
	v_mfma_f32_16x16x32_bf16 v[92:95], v[200:203], v[148:151], v[92:95]
	v_mfma_f32_16x16x32_bf16 v[20:23], v[200:203], v[152:155], v[20:23]
	v_mfma_f32_16x16x32_bf16 v[28:31], v[200:203], v[156:159], v[28:31]
	s_waitcnt lgkmcnt(1)
	v_mfma_f32_16x16x32_bf16 v[64:67], v[204:207], v[144:147], v[64:67]
	v_mfma_f32_16x16x32_bf16 v[72:75], v[204:207], v[148:151], v[72:75]
	v_mfma_f32_16x16x32_bf16 v[0:3], v[204:207], v[152:155], v[0:3]
	v_mfma_f32_16x16x32_bf16 v[8:11], v[204:207], v[156:159], v[8:11]
	s_waitcnt lgkmcnt(0)
	v_mfma_f32_16x16x32_bf16 v[68:71], v[242:245], v[144:147], v[68:71]
	v_mfma_f32_16x16x32_bf16 v[76:79], v[242:245], v[148:151], v[76:79]
	v_mfma_f32_16x16x32_bf16 v[4:7], v[242:245], v[152:155], v[4:7]
	v_mfma_f32_16x16x32_bf16 v[12:15], v[242:245], v[156:159], v[12:15]
	s_barrier
	s_nop 7
	s_nop 1
	s_waitcnt vmcnt(0)
	s_waitcnt vmcnt(0)
	v_and_b32_e32 v188, 63, v179
	v_lshrrev_b32_e32 v189, 6, v179
	v_mul_u32_u24_e32 v249, 0x2400, v189
	v_mov_b32_e32 v250, v249
	v_and_b32_e32 v251, 15, v188
	v_mul_u32_u24_e32 v251, 0x110, v251
	v_add_u32_e32 v249, v249, v251
	v_lshrrev_b32_e32 v251, 4, v188
	v_lshl_add_u32 v249, v251, 5, v249
	v_lshrrev_b32_e32 v237, 4, v188
	v_mul_u32_u24_e32 v251, 0x110, v237
	v_add_u32_e32 v250, v250, v251
	v_and_b32_e32 v251, 15, v188
	v_lshlrev_b32_e32 v251, 4, v251
	v_add_u32_e32 v250, v250, v251
	v_lshl_add_u32 v237, v189, 6, v237
	v_lshl_add_u32 v237, v237, 12, v251
	v_add_u32_e32 v238, 16384, v237
	v_add_u32_e32 v239, 32768, v237
	v_add_u32_e32 v240, 49152, v237
	v_add_u32_e32 v241, 65536, v237
	v_add_u32_e32 v242, 81920, v237
	v_add_u32_e32 v243, 98304, v237
	v_add_u32_e32 v248, 114688, v237
	s_lshl_b32 s16, s7, 8
	s_lshl_b32 s18, s6, 9
	s_lshr_b32 s19, s7, 4
	v_readlane_b32 s12, v253, 46
	v_readlane_b32 s13, v253, 47
	v_readlane_b32 s14, v253, 46
	v_readlane_b32 s15, v253, 47
	s_add_i32 s17, s16, 0xffff8000
	s_cmpk_lt_u32 s7, 0x80
	s_cselect_b32 s12, s12, s62
	s_cselect_b32 s13, s13, s63
	s_cselect_b32 s14, s14, s62
	s_cselect_b32 s15, s15, s63
	s_cselect_b32 s19, s19, 8
	s_cselect_b32 s16, s16, s17
	s_mov_b32 s17, 0
	s_lshl_b64 s[16:17], s[16:17], 12
	s_add_u32 s16, s16, s18
	s_addc_u32 s17, s17, 0
	s_add_u32 s12, s12, s16
	s_addc_u32 s13, s13, s17
	s_add_u32 s14, s14, s16
	s_addc_u32 s15, s15, s17
	s_mul_i32 s19, s19, 0x6000
	s_add_u32 s20, s0, s19
	s_addc_u32 s21, s1, 0
	s_add_u32 s20, s20, s18
	s_addc_u32 s21, s21, 0
	global_load_dwordx4 v[244:247], v251, s[20:21]
	global_load_dwordx4 v[160:163], v237, s[12:13]
	global_load_dwordx4 v[164:167], v238, s[12:13]
	global_load_dwordx4 v[168:171], v239, s[12:13]
	global_load_dwordx4 v[172:175], v240, s[12:13]
	global_load_dwordx4 v[196:199], v241, s[12:13]
	global_load_dwordx4 v[200:203], v242, s[12:13]
	global_load_dwordx4 v[204:207], v243, s[12:13]
	global_load_dwordx4 v[184:187], v248, s[12:13]
	ds_write_b128 v249, v[112:115]
	ds_write_b128 v249, v[116:119] offset:16
	ds_write_b128 v249, v[96:99] offset:128
	ds_write_b128 v249, v[100:103] offset:144
	ds_write_b128 v249, v[120:123] offset:4352
	ds_write_b128 v249, v[124:127] offset:4368
	ds_write_b128 v249, v[104:107] offset:4480
	ds_write_b128 v249, v[108:111] offset:4496
	s_waitcnt lgkmcnt(0)
	ds_read_b128 v[128:131], v250
	ds_read_b128 v[132:135], v250 offset:1088
	ds_read_b128 v[136:139], v250 offset:2176
	ds_read_b128 v[140:143], v250 offset:3264
	ds_read_b128 v[144:147], v250 offset:4352
	ds_read_b128 v[148:151], v250 offset:5440
	ds_read_b128 v[152:155], v250 offset:6528
	ds_read_b128 v[156:159], v250 offset:7616
	s_waitcnt vmcnt(7) lgkmcnt(7)
	v_fma_f32 v128, v244, v128, v160
	v_fma_f32 v129, v245, v129, v161
	v_fma_f32 v130, v246, v130, v162
	v_fma_f32 v131, v247, v131, v163
	global_store_dwordx4 v237, v[128:131], s[14:15]
	s_waitcnt vmcnt(7) lgkmcnt(6)
	v_fma_f32 v132, v244, v132, v164
	v_fma_f32 v133, v245, v133, v165
	v_fma_f32 v134, v246, v134, v166
	v_fma_f32 v135, v247, v135, v167
	global_store_dwordx4 v238, v[132:135], s[14:15]
	s_waitcnt vmcnt(7) lgkmcnt(5)
	v_fma_f32 v136, v244, v136, v168
	v_fma_f32 v137, v245, v137, v169
	v_fma_f32 v138, v246, v138, v170
	v_fma_f32 v139, v247, v139, v171
	global_store_dwordx4 v239, v[136:139], s[14:15]
	s_waitcnt vmcnt(7) lgkmcnt(4)
	v_fma_f32 v140, v244, v140, v172
	v_fma_f32 v141, v245, v141, v173
	v_fma_f32 v142, v246, v142, v174
	v_fma_f32 v143, v247, v143, v175
	global_store_dwordx4 v240, v[140:143], s[14:15]
	s_waitcnt vmcnt(7) lgkmcnt(3)
	v_fma_f32 v144, v244, v144, v196
	v_fma_f32 v145, v245, v145, v197
	v_fma_f32 v146, v246, v146, v198
	v_fma_f32 v147, v247, v147, v199
	global_store_dwordx4 v241, v[144:147], s[14:15]
	s_waitcnt vmcnt(7) lgkmcnt(2)
	v_fma_f32 v148, v244, v148, v200
	v_fma_f32 v149, v245, v149, v201
	v_fma_f32 v150, v246, v150, v202
	v_fma_f32 v151, v247, v151, v203
	global_store_dwordx4 v242, v[148:151], s[14:15]
	s_waitcnt vmcnt(7) lgkmcnt(1)
	v_fma_f32 v152, v244, v152, v204
	v_fma_f32 v153, v245, v153, v205
	v_fma_f32 v154, v246, v154, v206
	v_fma_f32 v155, v247, v155, v207
	global_store_dwordx4 v243, v[152:155], s[14:15]
	s_waitcnt vmcnt(7) lgkmcnt(0)
	v_fma_f32 v156, v244, v156, v184
	v_fma_f32 v157, v245, v157, v185
	v_fma_f32 v158, v246, v158, v186
	v_fma_f32 v159, v247, v159, v187
	global_store_dwordx4 v248, v[156:159], s[14:15]
	global_load_dwordx4 v[244:247], v251, s[20:21] offset:256
	global_load_dwordx4 v[160:163], v237, s[12:13] offset:256
	global_load_dwordx4 v[164:167], v238, s[12:13] offset:256
	global_load_dwordx4 v[168:171], v239, s[12:13] offset:256
	global_load_dwordx4 v[172:175], v240, s[12:13] offset:256
	global_load_dwordx4 v[196:199], v241, s[12:13] offset:256
	global_load_dwordx4 v[200:203], v242, s[12:13] offset:256
	global_load_dwordx4 v[204:207], v243, s[12:13] offset:256
	global_load_dwordx4 v[184:187], v248, s[12:13] offset:256
	ds_write_b128 v249, v[80:83]
	ds_write_b128 v249, v[84:87] offset:16
	ds_write_b128 v249, v[64:67] offset:128
	ds_write_b128 v249, v[68:71] offset:144
	ds_write_b128 v249, v[88:91] offset:4352
	ds_write_b128 v249, v[92:95] offset:4368
	ds_write_b128 v249, v[72:75] offset:4480
	ds_write_b128 v249, v[76:79] offset:4496
	s_waitcnt lgkmcnt(0)
	ds_read_b128 v[128:131], v250
	ds_read_b128 v[132:135], v250 offset:1088
	ds_read_b128 v[136:139], v250 offset:2176
	ds_read_b128 v[140:143], v250 offset:3264
	ds_read_b128 v[144:147], v250 offset:4352
	ds_read_b128 v[148:151], v250 offset:5440
	ds_read_b128 v[152:155], v250 offset:6528
	ds_read_b128 v[156:159], v250 offset:7616
	s_waitcnt vmcnt(7) lgkmcnt(7)
	v_fma_f32 v128, v244, v128, v160
	v_fma_f32 v129, v245, v129, v161
	v_fma_f32 v130, v246, v130, v162
	v_fma_f32 v131, v247, v131, v163
	global_store_dwordx4 v237, v[128:131], s[14:15] offset:256
	s_waitcnt vmcnt(7) lgkmcnt(6)
	v_fma_f32 v132, v244, v132, v164
	v_fma_f32 v133, v245, v133, v165
	v_fma_f32 v134, v246, v134, v166
	v_fma_f32 v135, v247, v135, v167
	global_store_dwordx4 v238, v[132:135], s[14:15] offset:256
	s_waitcnt vmcnt(7) lgkmcnt(5)
	v_fma_f32 v136, v244, v136, v168
	v_fma_f32 v137, v245, v137, v169
	v_fma_f32 v138, v246, v138, v170
	v_fma_f32 v139, v247, v139, v171
	global_store_dwordx4 v239, v[136:139], s[14:15] offset:256
	s_waitcnt vmcnt(7) lgkmcnt(4)
	v_fma_f32 v140, v244, v140, v172
	v_fma_f32 v141, v245, v141, v173
	v_fma_f32 v142, v246, v142, v174
	v_fma_f32 v143, v247, v143, v175
	global_store_dwordx4 v240, v[140:143], s[14:15] offset:256
	s_waitcnt vmcnt(7) lgkmcnt(3)
	v_fma_f32 v144, v244, v144, v196
	v_fma_f32 v145, v245, v145, v197
	v_fma_f32 v146, v246, v146, v198
	v_fma_f32 v147, v247, v147, v199
	global_store_dwordx4 v241, v[144:147], s[14:15] offset:256
	s_waitcnt vmcnt(7) lgkmcnt(2)
	v_fma_f32 v148, v244, v148, v200
	v_fma_f32 v149, v245, v149, v201
	v_fma_f32 v150, v246, v150, v202
	v_fma_f32 v151, v247, v151, v203
	global_store_dwordx4 v242, v[148:151], s[14:15] offset:256
	s_waitcnt vmcnt(7) lgkmcnt(1)
	v_fma_f32 v152, v244, v152, v204
	v_fma_f32 v153, v245, v153, v205
	v_fma_f32 v154, v246, v154, v206
	v_fma_f32 v155, v247, v155, v207
	global_store_dwordx4 v243, v[152:155], s[14:15] offset:256
	s_waitcnt vmcnt(7) lgkmcnt(0)
	v_fma_f32 v156, v244, v156, v184
	v_fma_f32 v157, v245, v157, v185
	v_fma_f32 v158, v246, v158, v186
	v_fma_f32 v159, v247, v159, v187
	global_store_dwordx4 v248, v[156:159], s[14:15] offset:256
	s_add_u32 s12, s12, 0x20000
	s_addc_u32 s13, s13, 0
	s_add_u32 s14, s14, 0x20000
	s_addc_u32 s15, s15, 0
	global_load_dwordx4 v[244:247], v251, s[20:21]
	global_load_dwordx4 v[160:163], v237, s[12:13]
	global_load_dwordx4 v[164:167], v238, s[12:13]
	global_load_dwordx4 v[168:171], v239, s[12:13]
	global_load_dwordx4 v[172:175], v240, s[12:13]
	global_load_dwordx4 v[196:199], v241, s[12:13]
	global_load_dwordx4 v[200:203], v242, s[12:13]
	global_load_dwordx4 v[204:207], v243, s[12:13]
	global_load_dwordx4 v[184:187], v248, s[12:13]
	ds_write_b128 v249, v[48:51]
	ds_write_b128 v249, v[52:55] offset:16
	ds_write_b128 v249, v[32:35] offset:128
	ds_write_b128 v249, v[36:39] offset:144
	ds_write_b128 v249, v[56:59] offset:4352
	ds_write_b128 v249, v[60:63] offset:4368
	ds_write_b128 v249, v[40:43] offset:4480
	ds_write_b128 v249, v[44:47] offset:4496
	s_waitcnt lgkmcnt(0)
	ds_read_b128 v[128:131], v250
	ds_read_b128 v[132:135], v250 offset:1088
	ds_read_b128 v[136:139], v250 offset:2176
	ds_read_b128 v[140:143], v250 offset:3264
	ds_read_b128 v[144:147], v250 offset:4352
	ds_read_b128 v[148:151], v250 offset:5440
	ds_read_b128 v[152:155], v250 offset:6528
	ds_read_b128 v[156:159], v250 offset:7616
	s_waitcnt vmcnt(7) lgkmcnt(7)
	v_fma_f32 v128, v244, v128, v160
	v_fma_f32 v129, v245, v129, v161
	v_fma_f32 v130, v246, v130, v162
	v_fma_f32 v131, v247, v131, v163
	global_store_dwordx4 v237, v[128:131], s[14:15]
	s_waitcnt vmcnt(7) lgkmcnt(6)
	v_fma_f32 v132, v244, v132, v164
	v_fma_f32 v133, v245, v133, v165
	v_fma_f32 v134, v246, v134, v166
	v_fma_f32 v135, v247, v135, v167
	global_store_dwordx4 v238, v[132:135], s[14:15]
	s_waitcnt vmcnt(7) lgkmcnt(5)
	v_fma_f32 v136, v244, v136, v168
	v_fma_f32 v137, v245, v137, v169
	v_fma_f32 v138, v246, v138, v170
	v_fma_f32 v139, v247, v139, v171
	global_store_dwordx4 v239, v[136:139], s[14:15]
	s_waitcnt vmcnt(7) lgkmcnt(4)
	v_fma_f32 v140, v244, v140, v172
	v_fma_f32 v141, v245, v141, v173
	v_fma_f32 v142, v246, v142, v174
	v_fma_f32 v143, v247, v143, v175
	global_store_dwordx4 v240, v[140:143], s[14:15]
	s_waitcnt vmcnt(7) lgkmcnt(3)
	v_fma_f32 v144, v244, v144, v196
	v_fma_f32 v145, v245, v145, v197
	v_fma_f32 v146, v246, v146, v198
	v_fma_f32 v147, v247, v147, v199
	global_store_dwordx4 v241, v[144:147], s[14:15]
	s_waitcnt vmcnt(7) lgkmcnt(2)
	v_fma_f32 v148, v244, v148, v200
	v_fma_f32 v149, v245, v149, v201
	v_fma_f32 v150, v246, v150, v202
	v_fma_f32 v151, v247, v151, v203
	global_store_dwordx4 v242, v[148:151], s[14:15]
	s_waitcnt vmcnt(7) lgkmcnt(1)
	v_fma_f32 v152, v244, v152, v204
	v_fma_f32 v153, v245, v153, v205
	v_fma_f32 v154, v246, v154, v206
	v_fma_f32 v155, v247, v155, v207
	global_store_dwordx4 v243, v[152:155], s[14:15]
	s_waitcnt vmcnt(7) lgkmcnt(0)
	v_fma_f32 v156, v244, v156, v184
	v_fma_f32 v157, v245, v157, v185
	v_fma_f32 v158, v246, v158, v186
	v_fma_f32 v159, v247, v159, v187
	global_store_dwordx4 v248, v[156:159], s[14:15]
	global_load_dwordx4 v[244:247], v251, s[20:21] offset:256
	global_load_dwordx4 v[160:163], v237, s[12:13] offset:256
	global_load_dwordx4 v[164:167], v238, s[12:13] offset:256
	global_load_dwordx4 v[168:171], v239, s[12:13] offset:256
	global_load_dwordx4 v[172:175], v240, s[12:13] offset:256
	global_load_dwordx4 v[196:199], v241, s[12:13] offset:256
	global_load_dwordx4 v[200:203], v242, s[12:13] offset:256
	global_load_dwordx4 v[204:207], v243, s[12:13] offset:256
	global_load_dwordx4 v[184:187], v248, s[12:13] offset:256
	ds_write_b128 v249, v[16:19]
	ds_write_b128 v249, v[20:23] offset:16
	ds_write_b128 v249, v[0:3] offset:128
	ds_write_b128 v249, v[4:7] offset:144
	ds_write_b128 v249, v[24:27] offset:4352
	ds_write_b128 v249, v[28:31] offset:4368
	ds_write_b128 v249, v[8:11] offset:4480
	ds_write_b128 v249, v[12:15] offset:4496
	s_waitcnt lgkmcnt(0)
	ds_read_b128 v[128:131], v250
	ds_read_b128 v[132:135], v250 offset:1088
	ds_read_b128 v[136:139], v250 offset:2176
	ds_read_b128 v[140:143], v250 offset:3264
	ds_read_b128 v[144:147], v250 offset:4352
	ds_read_b128 v[148:151], v250 offset:5440
	ds_read_b128 v[152:155], v250 offset:6528
	ds_read_b128 v[156:159], v250 offset:7616
	s_waitcnt vmcnt(7) lgkmcnt(7)
	v_fma_f32 v128, v244, v128, v160
	v_fma_f32 v129, v245, v129, v161
	v_fma_f32 v130, v246, v130, v162
	v_fma_f32 v131, v247, v131, v163
	global_store_dwordx4 v237, v[128:131], s[14:15] offset:256
	s_waitcnt vmcnt(7) lgkmcnt(6)
	v_fma_f32 v132, v244, v132, v164
	v_fma_f32 v133, v245, v133, v165
	v_fma_f32 v134, v246, v134, v166
	v_fma_f32 v135, v247, v135, v167
	global_store_dwordx4 v238, v[132:135], s[14:15] offset:256
	s_waitcnt vmcnt(7) lgkmcnt(5)
	v_fma_f32 v136, v244, v136, v168
	v_fma_f32 v137, v245, v137, v169
	v_fma_f32 v138, v246, v138, v170
	v_fma_f32 v139, v247, v139, v171
	global_store_dwordx4 v239, v[136:139], s[14:15] offset:256
	s_waitcnt vmcnt(7) lgkmcnt(4)
	v_fma_f32 v140, v244, v140, v172
	v_fma_f32 v141, v245, v141, v173
	v_fma_f32 v142, v246, v142, v174
	v_fma_f32 v143, v247, v143, v175
	global_store_dwordx4 v240, v[140:143], s[14:15] offset:256
	s_waitcnt vmcnt(7) lgkmcnt(3)
	v_fma_f32 v144, v244, v144, v196
	v_fma_f32 v145, v245, v145, v197
	v_fma_f32 v146, v246, v146, v198
	v_fma_f32 v147, v247, v147, v199
	global_store_dwordx4 v241, v[144:147], s[14:15] offset:256
	s_waitcnt vmcnt(7) lgkmcnt(2)
	v_fma_f32 v148, v244, v148, v200
	v_fma_f32 v149, v245, v149, v201
	v_fma_f32 v150, v246, v150, v202
	v_fma_f32 v151, v247, v151, v203
	global_store_dwordx4 v242, v[148:151], s[14:15] offset:256
	s_waitcnt vmcnt(7) lgkmcnt(1)
	v_fma_f32 v152, v244, v152, v204
	v_fma_f32 v153, v245, v153, v205
	v_fma_f32 v154, v246, v154, v206
	v_fma_f32 v155, v247, v155, v207
	global_store_dwordx4 v243, v[152:155], s[14:15] offset:256
	s_waitcnt vmcnt(7) lgkmcnt(0)
	v_fma_f32 v156, v244, v156, v184
	v_fma_f32 v157, v245, v157, v185
	v_fma_f32 v158, v246, v158, v186
	v_fma_f32 v159, v247, v159, v187
	global_store_dwordx4 v248, v[156:159], s[14:15] offset:256
	s_waitcnt lgkmcnt(0)
	v_readlane_b32 s16, v254, 11
	s_andn2_b32 s17, s26, 63
	s_add_i32 s2, s2, s16
	s_cmp_lt_i32 s2, s17
	s_cbranch_scc0 .Lhx_down_left
	s_barrier
	s_branch .LBB0_1086

.Lhx_down_half:
	v_bfe_u32 v247, v181, 4, 2
	v_lshlrev_b32_e32 v247, 1, v247
	v_mov_b32_e32 v176, 0x78
	v_lshrrev_b32_e32 v247, v247, v176
	v_and_b32_e32 v247, 3, v247
	v_and_b32_e32 v246, 3, v181
	v_xor_b32_e32 v247, v247, v246
	v_lshlrev_b32_e32 v247, 4, v247
	v_and_b32_e32 v188, 0xffffffcf, v186
	v_or_b32_e32 v188, v188, v247
	v_mov_b32_e32 v189, v187
	v_lshrrev_b32_e32 v176, 6, v181
	v_lshlrev_b32_e32 v247, 11, v176
	v_lshlrev_b32_e32 v176, 10, v176
	v_lshl_add_u64 v[188:189], v[188:189], 0, v[176:177]
	v_readfirstlane_b32 vcc_lo, v247
	v_bfe_u32 v247, v181, 4, 1
	v_lshlrev_b32_e32 v176, 9, v183
	v_lshl_add_u32 v176, v247, 8, v176
	v_lshl_add_u64 v[184:185], v[184:185], 0, v[176:177]
	v_mov_b32_e32 v176, s24
	v_lshl_add_u64 v[186:187], v[184:185], 0, v[176:177]
	v_mov_b32_e32 v176, 0x78
	v_bfe_u32 v247, v181, 2, 1
	v_lshlrev_b32_e32 v247, 2, v247
	v_lshrrev_b32_e32 v247, v247, v176
	v_and_b32_e32 v247, 3, v247
	v_bfe_u32 v246, v181, 4, 2
	v_xor_b32_e32 v247, v247, v246
	v_lshlrev_b32_e32 v247, 4, v247
	v_bfe_u32 v246, v181, 2, 2
	v_lshlrev_b32_e32 v246, 3, v246
	v_and_b32_e32 v162, 3, v181
	v_add_u32_e32 v246, v246, v162
	v_lshl_add_u32 v246, v246, 6, v247
	v_bfe_u32 v247, v181, 2, 1
	v_lshlrev_b32_e32 v247, 2, v247
	v_add_u32_e32 v247, 2, v247
	v_lshrrev_b32_e32 v247, v247, v176
	v_and_b32_e32 v247, 3, v247
	v_bfe_u32 v162, v181, 4, 2
	v_xor_b32_e32 v247, v247, v162
	v_lshlrev_b32_e32 v247, 4, v247
	v_and_b32_e32 v162, 0xffffffcf, v246
	v_add_u32_e32 v162, 0x100, v162
	v_or_b32_e32 v162, v162, v247
	s_cmp_eq_u32 s101, 1
	s_cbranch_scc0 .Lg16_downh_a0
	v_mov_b32_e32 v184, v186
	v_mov_b32_e32 v185, v187

.Lg16_downh_k:
	s_add_i32 s9, s8, 2
	s_lshl_b32 s96, s9, 13
	s_add_i32 m0, vcc_lo, 16384
	v_lshl_add_u64 v[160:161], v[188:189], 0, s[96:97]
	global_load_lds_dwordx4 v[160:161], off
	global_load_lds_dwordx4 v[160:161], off offset:1024
	ds_read_b128 v[196:199], v246 offset:0
	ds_read_b128 v[200:203], v162 offset:0
	ds_read_b128 v[204:207], v246 offset:2048
	ds_read_b128 v[242:245], v162 offset:2048
	s_add_i32 s9, s8, 2
	s_lshl_b32 s96, s9, 11
	v_lshl_add_u64 v[248:249], v[184:185], 0, s[96:97]
	v_lshl_add_u64 v[250:251], v[186:187], 0, s[96:97]
	s_waitcnt vmcnt(6) lgkmcnt(3)
	v_mfma_f32_16x16x32_bf16 v[112:115], v[196:199], v[128:131], v[112:115]
	v_mfma_f32_16x16x32_bf16 v[120:123], v[196:199], v[132:135], v[120:123]
	ds_read_b128 v[196:199], v246 offset:4096
	s_waitcnt lgkmcnt(3)
	v_mfma_f32_16x16x32_bf16 v[116:119], v[200:203], v[128:131], v[116:119]
	v_mfma_f32_16x16x32_bf16 v[124:127], v[200:203], v[132:135], v[124:127]
	ds_read_b128 v[200:203], v162 offset:4096
	s_waitcnt lgkmcnt(3)
	v_mfma_f32_16x16x32_bf16 v[96:99], v[204:207], v[128:131], v[96:99]
	v_mfma_f32_16x16x32_bf16 v[104:107], v[204:207], v[132:135], v[104:107]
	ds_read_b128 v[204:207], v246 offset:6144
	s_waitcnt lgkmcnt(3)
	v_mfma_f32_16x16x32_bf16 v[100:103], v[242:245], v[128:131], v[100:103]
	v_mfma_f32_16x16x32_bf16 v[108:111], v[242:245], v[132:135], v[108:111]
	ds_read_b128 v[242:245], v162 offset:6144
	s_waitcnt lgkmcnt(3)
	v_mfma_f32_16x16x32_bf16 v[80:83], v[196:199], v[128:131], v[80:83]
	v_mfma_f32_16x16x32_bf16 v[88:91], v[196:199], v[132:135], v[88:91]
	s_waitcnt lgkmcnt(2)
	v_mfma_f32_16x16x32_bf16 v[84:87], v[200:203], v[128:131], v[84:87]
	v_mfma_f32_16x16x32_bf16 v[92:95], v[200:203], v[132:135], v[92:95]
	s_waitcnt lgkmcnt(1)
	v_mfma_f32_16x16x32_bf16 v[64:67], v[204:207], v[128:131], v[64:67]
	v_mfma_f32_16x16x32_bf16 v[72:75], v[204:207], v[132:135], v[72:75]
	s_waitcnt lgkmcnt(0)
	v_mfma_f32_16x16x32_bf16 v[68:71], v[242:245], v[128:131], v[68:71]
	v_mfma_f32_16x16x32_bf16 v[76:79], v[242:245], v[132:135], v[76:79]
	global_load_dwordx4 v[128:131], v[248:249], off
	global_load_dwordx4 v[132:135], v[248:249], off offset:256
	s_waitcnt vmcnt(6)
	s_barrier
	s_add_i32 s9, s8, 3
	s_lshl_b32 s96, s9, 13
	s_mov_b32 m0, vcc_lo
	v_lshl_add_u64 v[160:161], v[188:189], 0, s[96:97]
	global_load_lds_dwordx4 v[160:161], off
	global_load_lds_dwordx4 v[160:161], off offset:1024
	ds_read_b128 v[196:199], v246 offset:8192
	ds_read_b128 v[200:203], v162 offset:8192
	ds_read_b128 v[204:207], v246 offset:10240
	ds_read_b128 v[242:245], v162 offset:10240
	s_add_i32 s9, s8, 3
	s_lshl_b32 s96, s9, 11
	v_lshl_add_u64 v[248:249], v[184:185], 0, s[96:97]
	v_lshl_add_u64 v[250:251], v[186:187], 0, s[96:97]
	s_waitcnt vmcnt(6) lgkmcnt(3)
	v_mfma_f32_16x16x32_bf16 v[112:115], v[196:199], v[144:147], v[112:115]
	v_mfma_f32_16x16x32_bf16 v[120:123], v[196:199], v[148:151], v[120:123]
	ds_read_b128 v[196:199], v246 offset:12288
	s_waitcnt lgkmcnt(3)
	v_mfma_f32_16x16x32_bf16 v[116:119], v[200:203], v[144:147], v[116:119]
	v_mfma_f32_16x16x32_bf16 v[124:127], v[200:203], v[148:151], v[124:127]
	ds_read_b128 v[200:203], v162 offset:12288
	s_waitcnt lgkmcnt(3)
	v_mfma_f32_16x16x32_bf16 v[96:99], v[204:207], v[144:147], v[96:99]
	v_mfma_f32_16x16x32_bf16 v[104:107], v[204:207], v[148:151], v[104:107]
	ds_read_b128 v[204:207], v246 offset:14336
	s_waitcnt lgkmcnt(3)
	v_mfma_f32_16x16x32_bf16 v[100:103], v[242:245], v[144:147], v[100:103]
	v_mfma_f32_16x16x32_bf16 v[108:111], v[242:245], v[148:151], v[108:111]
	ds_read_b128 v[242:245], v162 offset:14336
	s_waitcnt lgkmcnt(3)
	v_mfma_f32_16x16x32_bf16 v[80:83], v[196:199], v[144:147], v[80:83]
	v_mfma_f32_16x16x32_bf16 v[88:91], v[196:199], v[148:151], v[88:91]
	s_waitcnt lgkmcnt(2)
	v_mfma_f32_16x16x32_bf16 v[84:87], v[200:203], v[144:147], v[84:87]
	v_mfma_f32_16x16x32_bf16 v[92:95], v[200:203], v[148:151], v[92:95]
	s_waitcnt lgkmcnt(1)
	v_mfma_f32_16x16x32_bf16 v[64:67], v[204:207], v[144:147], v[64:67]
	v_mfma_f32_16x16x32_bf16 v[72:75], v[204:207], v[148:151], v[72:75]
	s_waitcnt lgkmcnt(0)
	v_mfma_f32_16x16x32_bf16 v[68:71], v[242:245], v[144:147], v[68:71]
	v_mfma_f32_16x16x32_bf16 v[76:79], v[242:245], v[148:151], v[76:79]
	global_load_dwordx4 v[144:147], v[248:249], off
	global_load_dwordx4 v[148:151], v[248:249], off offset:256
	s_waitcnt vmcnt(6)
	s_barrier
	s_add_i32 s9, s8, 4
	s_lshl_b32 s96, s9, 13
	s_add_i32 m0, vcc_lo, 8192
	v_lshl_add_u64 v[160:161], v[188:189], 0, s[96:97]
	global_load_lds_dwordx4 v[160:161], off
	global_load_lds_dwordx4 v[160:161], off offset:1024
	ds_read_b128 v[196:199], v246 offset:16384
	ds_read_b128 v[200:203], v162 offset:16384
	ds_read_b128 v[204:207], v246 offset:18432
	ds_read_b128 v[242:245], v162 offset:18432
	s_add_i32 s9, s8, 4
	s_lshl_b32 s96, s9, 11
	v_lshl_add_u64 v[248:249], v[184:185], 0, s[96:97]
	v_lshl_add_u64 v[250:251], v[186:187], 0, s[96:97]
	s_waitcnt vmcnt(6) lgkmcnt(3)
	v_mfma_f32_16x16x32_bf16 v[112:115], v[196:199], v[128:131], v[112:115]
	v_mfma_f32_16x16x32_bf16 v[120:123], v[196:199], v[132:135], v[120:123]
	ds_read_b128 v[196:199], v246 offset:20480
	s_waitcnt lgkmcnt(3)
	v_mfma_f32_16x16x32_bf16 v[116:119], v[200:203], v[128:131], v[116:119]
	v_mfma_f32_16x16x32_bf16 v[124:127], v[200:203], v[132:135], v[124:127]
	ds_read_b128 v[200:203], v162 offset:20480
	s_waitcnt lgkmcnt(3)
	v_mfma_f32_16x16x32_bf16 v[96:99], v[204:207], v[128:131], v[96:99]
	v_mfma_f32_16x16x32_bf16 v[104:107], v[204:207], v[132:135], v[104:107]
	ds_read_b128 v[204:207], v246 offset:22528
	s_waitcnt lgkmcnt(3)
	v_mfma_f32_16x16x32_bf16 v[100:103], v[242:245], v[128:131], v[100:103]
	v_mfma_f32_16x16x32_bf16 v[108:111], v[242:245], v[132:135], v[108:111]
	ds_read_b128 v[242:245], v162 offset:22528
	s_waitcnt lgkmcnt(3)
	v_mfma_f32_16x16x32_bf16 v[80:83], v[196:199], v[128:131], v[80:83]
	v_mfma_f32_16x16x32_bf16 v[88:91], v[196:199], v[132:135], v[88:91]
	s_waitcnt lgkmcnt(2)
	v_mfma_f32_16x16x32_bf16 v[84:87], v[200:203], v[128:131], v[84:87]
	v_mfma_f32_16x16x32_bf16 v[92:95], v[200:203], v[132:135], v[92:95]
	s_waitcnt lgkmcnt(1)
	v_mfma_f32_16x16x32_bf16 v[64:67], v[204:207], v[128:131], v[64:67]
	v_mfma_f32_16x16x32_bf16 v[72:75], v[204:207], v[132:135], v[72:75]
	s_waitcnt lgkmcnt(0)
	v_mfma_f32_16x16x32_bf16 v[68:71], v[242:245], v[128:131], v[68:71]
	v_mfma_f32_16x16x32_bf16 v[76:79], v[242:245], v[132:135], v[76:79]
	global_load_dwordx4 v[128:131], v[248:249], off
	global_load_dwordx4 v[132:135], v[248:249], off offset:256
	s_waitcnt vmcnt(6)
	s_barrier
	s_add_i32 s9, s8, 5
	s_lshl_b32 s96, s9, 13
	s_add_i32 m0, vcc_lo, 16384
	v_lshl_add_u64 v[160:161], v[188:189], 0, s[96:97]
	global_load_lds_dwordx4 v[160:161], off
	global_load_lds_dwordx4 v[160:161], off offset:1024
	ds_read_b128 v[196:199], v246 offset:0
	ds_read_b128 v[200:203], v162 offset:0
	ds_read_b128 v[204:207], v246 offset:2048
	ds_read_b128 v[242:245], v162 offset:2048
	s_add_i32 s9, s8, 5
	s_lshl_b32 s96, s9, 11
	v_lshl_add_u64 v[248:249], v[184:185], 0, s[96:97]
	v_lshl_add_u64 v[250:251], v[186:187], 0, s[96:97]
	s_waitcnt vmcnt(6) lgkmcnt(3)
	v_mfma_f32_16x16x32_bf16 v[112:115], v[196:199], v[144:147], v[112:115]
	v_mfma_f32_16x16x32_bf16 v[120:123], v[196:199], v[148:151], v[120:123]
	ds_read_b128 v[196:199], v246 offset:4096
	s_waitcnt lgkmcnt(3)
	v_mfma_f32_16x16x32_bf16 v[116:119], v[200:203], v[144:147], v[116:119]
	v_mfma_f32_16x16x32_bf16 v[124:127], v[200:203], v[148:151], v[124:127]
	ds_read_b128 v[200:203], v162 offset:4096
	s_waitcnt lgkmcnt(3)
	v_mfma_f32_16x16x32_bf16 v[96:99], v[204:207], v[144:147], v[96:99]
	v_mfma_f32_16x16x32_bf16 v[104:107], v[204:207], v[148:151], v[104:107]
	ds_read_b128 v[204:207], v246 offset:6144
	s_waitcnt lgkmcnt(3)
	v_mfma_f32_16x16x32_bf16 v[100:103], v[242:245], v[144:147], v[100:103]
	v_mfma_f32_16x16x32_bf16 v[108:111], v[242:245], v[148:151], v[108:111]
	ds_read_b128 v[242:245], v162 offset:6144
	s_waitcnt lgkmcnt(3)
	v_mfma_f32_16x16x32_bf16 v[80:83], v[196:199], v[144:147], v[80:83]
	v_mfma_f32_16x16x32_bf16 v[88:91], v[196:199], v[148:151], v[88:91]
	s_waitcnt lgkmcnt(2)
	v_mfma_f32_16x16x32_bf16 v[84:87], v[200:203], v[144:147], v[84:87]
	v_mfma_f32_16x16x32_bf16 v[92:95], v[200:203], v[148:151], v[92:95]
	s_waitcnt lgkmcnt(1)
	v_mfma_f32_16x16x32_bf16 v[64:67], v[204:207], v[144:147], v[64:67]
	v_mfma_f32_16x16x32_bf16 v[72:75], v[204:207], v[148:151], v[72:75]
	s_waitcnt lgkmcnt(0)
	v_mfma_f32_16x16x32_bf16 v[68:71], v[242:245], v[144:147], v[68:71]
	v_mfma_f32_16x16x32_bf16 v[76:79], v[242:245], v[148:151], v[76:79]
	global_load_dwordx4 v[144:147], v[248:249], off
	global_load_dwordx4 v[148:151], v[248:249], off offset:256
	s_waitcnt vmcnt(6)
	s_barrier
	s_add_i32 s9, s8, 6
	s_lshl_b32 s96, s9, 13
	s_mov_b32 m0, vcc_lo
	v_lshl_add_u64 v[160:161], v[188:189], 0, s[96:97]
	global_load_lds_dwordx4 v[160:161], off
	global_load_lds_dwordx4 v[160:161], off offset:1024
	ds_read_b128 v[196:199], v246 offset:8192
	ds_read_b128 v[200:203], v162 offset:8192
	ds_read_b128 v[204:207], v246 offset:10240
	ds_read_b128 v[242:245], v162 offset:10240
	s_add_i32 s9, s8, 6
	s_lshl_b32 s96, s9, 11
	v_lshl_add_u64 v[248:249], v[184:185], 0, s[96:97]
	v_lshl_add_u64 v[250:251], v[186:187], 0, s[96:97]
	s_waitcnt vmcnt(6) lgkmcnt(3)
	v_mfma_f32_16x16x32_bf16 v[112:115], v[196:199], v[128:131], v[112:115]
	v_mfma_f32_16x16x32_bf16 v[120:123], v[196:199], v[132:135], v[120:123]
	ds_read_b128 v[196:199], v246 offset:12288
	s_waitcnt lgkmcnt(3)
	v_mfma_f32_16x16x32_bf16 v[116:119], v[200:203], v[128:131], v[116:119]
	v_mfma_f32_16x16x32_bf16 v[124:127], v[200:203], v[132:135], v[124:127]
	ds_read_b128 v[200:203], v162 offset:12288
	s_waitcnt lgkmcnt(3)
	v_mfma_f32_16x16x32_bf16 v[96:99], v[204:207], v[128:131], v[96:99]
	v_mfma_f32_16x16x32_bf16 v[104:107], v[204:207], v[132:135], v[104:107]
	ds_read_b128 v[204:207], v246 offset:14336
	s_waitcnt lgkmcnt(3)
	v_mfma_f32_16x16x32_bf16 v[100:103], v[242:245], v[128:131], v[100:103]
	v_mfma_f32_16x16x32_bf16 v[108:111], v[242:245], v[132:135], v[108:111]
	ds_read_b128 v[242:245], v162 offset:14336
	s_waitcnt lgkmcnt(3)
	v_mfma_f32_16x16x32_bf16 v[80:83], v[196:199], v[128:131], v[80:83]
	v_mfma_f32_16x16x32_bf16 v[88:91], v[196:199], v[132:135], v[88:91]
	s_waitcnt lgkmcnt(2)
	v_mfma_f32_16x16x32_bf16 v[84:87], v[200:203], v[128:131], v[84:87]
	v_mfma_f32_16x16x32_bf16 v[92:95], v[200:203], v[132:135], v[92:95]
	s_waitcnt lgkmcnt(1)
	v_mfma_f32_16x16x32_bf16 v[64:67], v[204:207], v[128:131], v[64:67]
	v_mfma_f32_16x16x32_bf16 v[72:75], v[204:207], v[132:135], v[72:75]
	s_waitcnt lgkmcnt(0)
	v_mfma_f32_16x16x32_bf16 v[68:71], v[242:245], v[128:131], v[68:71]
	v_mfma_f32_16x16x32_bf16 v[76:79], v[242:245], v[132:135], v[76:79]
	global_load_dwordx4 v[128:131], v[248:249], off
	global_load_dwordx4 v[132:135], v[248:249], off offset:256
	s_waitcnt vmcnt(6)
	s_barrier
	s_add_i32 s9, s8, 7
	s_lshl_b32 s96, s9, 13
	s_add_i32 m0, vcc_lo, 8192
	v_lshl_add_u64 v[160:161], v[188:189], 0, s[96:97]
	global_load_lds_dwordx4 v[160:161], off
	global_load_lds_dwordx4 v[160:161], off offset:1024
	ds_read_b128 v[196:199], v246 offset:16384
	ds_read_b128 v[200:203], v162 offset:16384
	ds_read_b128 v[204:207], v246 offset:18432
	ds_read_b128 v[242:245], v162 offset:18432
	s_add_i32 s9, s8, 7
	s_lshl_b32 s96, s9, 11
	v_lshl_add_u64 v[248:249], v[184:185], 0, s[96:97]
	v_lshl_add_u64 v[250:251], v[186:187], 0, s[96:97]
	s_waitcnt vmcnt(6) lgkmcnt(3)
	v_mfma_f32_16x16x32_bf16 v[112:115], v[196:199], v[144:147], v[112:115]
	v_mfma_f32_16x16x32_bf16 v[120:123], v[196:199], v[148:151], v[120:123]
	ds_read_b128 v[196:199], v246 offset:20480
	s_waitcnt lgkmcnt(3)
	v_mfma_f32_16x16x32_bf16 v[116:119], v[200:203], v[144:147], v[116:119]
	v_mfma_f32_16x16x32_bf16 v[124:127], v[200:203], v[148:151], v[124:127]
	ds_read_b128 v[200:203], v162 offset:20480
	s_waitcnt lgkmcnt(3)
	v_mfma_f32_16x16x32_bf16 v[96:99], v[204:207], v[144:147], v[96:99]
	v_mfma_f32_16x16x32_bf16 v[104:107], v[204:207], v[148:151], v[104:107]
	ds_read_b128 v[204:207], v246 offset:22528
	s_waitcnt lgkmcnt(3)
	v_mfma_f32_16x16x32_bf16 v[100:103], v[242:245], v[144:147], v[100:103]
	v_mfma_f32_16x16x32_bf16 v[108:111], v[242:245], v[148:151], v[108:111]
	ds_read_b128 v[242:245], v162 offset:22528
	s_waitcnt lgkmcnt(3)
	v_mfma_f32_16x16x32_bf16 v[80:83], v[196:199], v[144:147], v[80:83]
	v_mfma_f32_16x16x32_bf16 v[88:91], v[196:199], v[148:151], v[88:91]
	s_waitcnt lgkmcnt(2)
	v_mfma_f32_16x16x32_bf16 v[84:87], v[200:203], v[144:147], v[84:87]
	v_mfma_f32_16x16x32_bf16 v[92:95], v[200:203], v[148:151], v[92:95]
	s_waitcnt lgkmcnt(1)
	v_mfma_f32_16x16x32_bf16 v[64:67], v[204:207], v[144:147], v[64:67]
	v_mfma_f32_16x16x32_bf16 v[72:75], v[204:207], v[148:151], v[72:75]
	s_waitcnt lgkmcnt(0)
	v_mfma_f32_16x16x32_bf16 v[68:71], v[242:245], v[144:147], v[68:71]
	v_mfma_f32_16x16x32_bf16 v[76:79], v[242:245], v[148:151], v[76:79]
	global_load_dwordx4 v[144:147], v[248:249], off
	global_load_dwordx4 v[148:151], v[248:249], off offset:256
	s_waitcnt vmcnt(6)
	s_barrier
	s_add_i32 s8, s8, 6
	s_cmp_lt_u32 s8, 84
	s_cbranch_scc1 .Lg16_downh_k
	s_mov_b32 s96, 0xac000
	s_add_i32 m0, vcc_lo, 16384
	v_lshl_add_u64 v[160:161], v[188:189], 0, s[96:97]
	global_load_lds_dwordx4 v[160:161], off
	global_load_lds_dwordx4 v[160:161], off offset:1024
	ds_read_b128 v[196:199], v246 offset:0
	ds_read_b128 v[200:203], v162 offset:0
	ds_read_b128 v[204:207], v246 offset:2048
	ds_read_b128 v[242:245], v162 offset:2048
	s_mov_b32 s96, 0x2b000
	v_lshl_add_u64 v[248:249], v[184:185], 0, s[96:97]
	v_lshl_add_u64 v[250:251], v[186:187], 0, s[96:97]
	s_waitcnt vmcnt(6) lgkmcnt(3)
	v_mfma_f32_16x16x32_bf16 v[112:115], v[196:199], v[128:131], v[112:115]
	v_mfma_f32_16x16x32_bf16 v[120:123], v[196:199], v[132:135], v[120:123]
	ds_read_b128 v[196:199], v246 offset:4096
	s_waitcnt lgkmcnt(3)
	v_mfma_f32_16x16x32_bf16 v[116:119], v[200:203], v[128:131], v[116:119]
	v_mfma_f32_16x16x32_bf16 v[124:127], v[200:203], v[132:135], v[124:127]
	ds_read_b128 v[200:203], v162 offset:4096
	s_waitcnt lgkmcnt(3)
	v_mfma_f32_16x16x32_bf16 v[96:99], v[204:207], v[128:131], v[96:99]
	v_mfma_f32_16x16x32_bf16 v[104:107], v[204:207], v[132:135], v[104:107]
	ds_read_b128 v[204:207], v246 offset:6144
	s_waitcnt lgkmcnt(3)
	v_mfma_f32_16x16x32_bf16 v[100:103], v[242:245], v[128:131], v[100:103]
	v_mfma_f32_16x16x32_bf16 v[108:111], v[242:245], v[132:135], v[108:111]
	ds_read_b128 v[242:245], v162 offset:6144
	s_waitcnt lgkmcnt(3)
	v_mfma_f32_16x16x32_bf16 v[80:83], v[196:199], v[128:131], v[80:83]
	v_mfma_f32_16x16x32_bf16 v[88:91], v[196:199], v[132:135], v[88:91]
	s_waitcnt lgkmcnt(2)
	v_mfma_f32_16x16x32_bf16 v[84:87], v[200:203], v[128:131], v[84:87]
	v_mfma_f32_16x16x32_bf16 v[92:95], v[200:203], v[132:135], v[92:95]
	s_waitcnt lgkmcnt(1)
	v_mfma_f32_16x16x32_bf16 v[64:67], v[204:207], v[128:131], v[64:67]
	v_mfma_f32_16x16x32_bf16 v[72:75], v[204:207], v[132:135], v[72:75]
	s_waitcnt lgkmcnt(0)
	v_mfma_f32_16x16x32_bf16 v[68:71], v[242:245], v[128:131], v[68:71]
	v_mfma_f32_16x16x32_bf16 v[76:79], v[242:245], v[132:135], v[76:79]
	global_load_dwordx4 v[128:131], v[248:249], off
	global_load_dwordx4 v[132:135], v[248:249], off offset:256
	s_waitcnt vmcnt(6)
	s_barrier
	s_mov_b32 s96, 0xae000
	s_mov_b32 m0, vcc_lo
	v_lshl_add_u64 v[160:161], v[188:189], 0, s[96:97]
	global_load_lds_dwordx4 v[160:161], off
	global_load_lds_dwordx4 v[160:161], off offset:1024
	ds_read_b128 v[196:199], v246 offset:8192
	ds_read_b128 v[200:203], v162 offset:8192
	ds_read_b128 v[204:207], v246 offset:10240
	ds_read_b128 v[242:245], v162 offset:10240
	s_mov_b32 s96, 0x2b800
	v_lshl_add_u64 v[248:249], v[184:185], 0, s[96:97]
	v_lshl_add_u64 v[250:251], v[186:187], 0, s[96:97]
	s_waitcnt vmcnt(6) lgkmcnt(3)
	v_mfma_f32_16x16x32_bf16 v[112:115], v[196:199], v[144:147], v[112:115]
	v_mfma_f32_16x16x32_bf16 v[120:123], v[196:199], v[148:151], v[120:123]
	ds_read_b128 v[196:199], v246 offset:12288
	s_waitcnt lgkmcnt(3)
	v_mfma_f32_16x16x32_bf16 v[116:119], v[200:203], v[144:147], v[116:119]
	v_mfma_f32_16x16x32_bf16 v[124:127], v[200:203], v[148:151], v[124:127]
	ds_read_b128 v[200:203], v162 offset:12288
	s_waitcnt lgkmcnt(3)
	v_mfma_f32_16x16x32_bf16 v[96:99], v[204:207], v[144:147], v[96:99]
	v_mfma_f32_16x16x32_bf16 v[104:107], v[204:207], v[148:151], v[104:107]
	ds_read_b128 v[204:207], v246 offset:14336
	s_waitcnt lgkmcnt(3)
	v_mfma_f32_16x16x32_bf16 v[100:103], v[242:245], v[144:147], v[100:103]
	v_mfma_f32_16x16x32_bf16 v[108:111], v[242:245], v[148:151], v[108:111]
	ds_read_b128 v[242:245], v162 offset:14336
	s_waitcnt lgkmcnt(3)
	v_mfma_f32_16x16x32_bf16 v[80:83], v[196:199], v[144:147], v[80:83]
	v_mfma_f32_16x16x32_bf16 v[88:91], v[196:199], v[148:151], v[88:91]
	s_waitcnt lgkmcnt(2)
	v_mfma_f32_16x16x32_bf16 v[84:87], v[200:203], v[144:147], v[84:87]
	v_mfma_f32_16x16x32_bf16 v[92:95], v[200:203], v[148:151], v[92:95]
	s_waitcnt lgkmcnt(1)
	v_mfma_f32_16x16x32_bf16 v[64:67], v[204:207], v[144:147], v[64:67]
	v_mfma_f32_16x16x32_bf16 v[72:75], v[204:207], v[148:151], v[72:75]
	s_waitcnt lgkmcnt(0)
	v_mfma_f32_16x16x32_bf16 v[68:71], v[242:245], v[144:147], v[68:71]
	v_mfma_f32_16x16x32_bf16 v[76:79], v[242:245], v[148:151], v[76:79]
	global_load_dwordx4 v[144:147], v[248:249], off
	global_load_dwordx4 v[148:151], v[248:249], off offset:256
	s_waitcnt vmcnt(6)
	s_barrier
	ds_read_b128 v[196:199], v246 offset:16384
	ds_read_b128 v[200:203], v162 offset:16384
	ds_read_b128 v[204:207], v246 offset:18432
	ds_read_b128 v[242:245], v162 offset:18432
	s_waitcnt vmcnt(4) lgkmcnt(3)
	v_mfma_f32_16x16x32_bf16 v[112:115], v[196:199], v[128:131], v[112:115]
	v_mfma_f32_16x16x32_bf16 v[120:123], v[196:199], v[132:135], v[120:123]
	ds_read_b128 v[196:199], v246 offset:20480
	s_waitcnt lgkmcnt(3)
	v_mfma_f32_16x16x32_bf16 v[116:119], v[200:203], v[128:131], v[116:119]
	v_mfma_f32_16x16x32_bf16 v[124:127], v[200:203], v[132:135], v[124:127]
	ds_read_b128 v[200:203], v162 offset:20480
	s_waitcnt lgkmcnt(3)
	v_mfma_f32_16x16x32_bf16 v[96:99], v[204:207], v[128:131], v[96:99]
	v_mfma_f32_16x16x32_bf16 v[104:107], v[204:207], v[132:135], v[104:107]
	ds_read_b128 v[204:207], v246 offset:22528
	s_waitcnt lgkmcnt(3)
	v_mfma_f32_16x16x32_bf16 v[100:103], v[242:245], v[128:131], v[100:103]
	v_mfma_f32_16x16x32_bf16 v[108:111], v[242:245], v[132:135], v[108:111]
	ds_read_b128 v[242:245], v162 offset:22528
	s_waitcnt lgkmcnt(3)
	v_mfma_f32_16x16x32_bf16 v[80:83], v[196:199], v[128:131], v[80:83]
	v_mfma_f32_16x16x32_bf16 v[88:91], v[196:199], v[132:135], v[88:91]
	s_waitcnt lgkmcnt(2)
	v_mfma_f32_16x16x32_bf16 v[84:87], v[200:203], v[128:131], v[84:87]
	v_mfma_f32_16x16x32_bf16 v[92:95], v[200:203], v[132:135], v[92:95]
	s_waitcnt lgkmcnt(1)
	v_mfma_f32_16x16x32_bf16 v[64:67], v[204:207], v[128:131], v[64:67]
	v_mfma_f32_16x16x32_bf16 v[72:75], v[204:207], v[132:135], v[72:75]
	s_waitcnt lgkmcnt(0)
	v_mfma_f32_16x16x32_bf16 v[68:71], v[242:245], v[128:131], v[68:71]
	v_mfma_f32_16x16x32_bf16 v[76:79], v[242:245], v[132:135], v[76:79]
	s_waitcnt vmcnt(2)
	s_barrier
	ds_read_b128 v[196:199], v246 offset:0
	ds_read_b128 v[200:203], v162 offset:0
	ds_read_b128 v[204:207], v246 offset:2048
	ds_read_b128 v[242:245], v162 offset:2048
	s_waitcnt vmcnt(0) lgkmcnt(3)
	v_mfma_f32_16x16x32_bf16 v[112:115], v[196:199], v[144:147], v[112:115]
	v_mfma_f32_16x16x32_bf16 v[120:123], v[196:199], v[148:151], v[120:123]
	ds_read_b128 v[196:199], v246 offset:4096
	s_waitcnt lgkmcnt(3)
	v_mfma_f32_16x16x32_bf16 v[116:119], v[200:203], v[144:147], v[116:119]
	v_mfma_f32_16x16x32_bf16 v[124:127], v[200:203], v[148:151], v[124:127]
	ds_read_b128 v[200:203], v162 offset:4096
	s_waitcnt lgkmcnt(3)
	v_mfma_f32_16x16x32_bf16 v[96:99], v[204:207], v[144:147], v[96:99]
	v_mfma_f32_16x16x32_bf16 v[104:107], v[204:207], v[148:151], v[104:107]
	ds_read_b128 v[204:207], v246 offset:6144
	s_waitcnt lgkmcnt(3)
	v_mfma_f32_16x16x32_bf16 v[100:103], v[242:245], v[144:147], v[100:103]
	v_mfma_f32_16x16x32_bf16 v[108:111], v[242:245], v[148:151], v[108:111]
	ds_read_b128 v[242:245], v162 offset:6144
	s_waitcnt lgkmcnt(3)
	v_mfma_f32_16x16x32_bf16 v[80:83], v[196:199], v[144:147], v[80:83]
	v_mfma_f32_16x16x32_bf16 v[88:91], v[196:199], v[148:151], v[88:91]
	s_waitcnt lgkmcnt(2)
	v_mfma_f32_16x16x32_bf16 v[84:87], v[200:203], v[144:147], v[84:87]
	v_mfma_f32_16x16x32_bf16 v[92:95], v[200:203], v[148:151], v[92:95]
	s_waitcnt lgkmcnt(1)
	v_mfma_f32_16x16x32_bf16 v[64:67], v[204:207], v[144:147], v[64:67]
	v_mfma_f32_16x16x32_bf16 v[72:75], v[204:207], v[148:151], v[72:75]
	s_waitcnt lgkmcnt(0)
	v_mfma_f32_16x16x32_bf16 v[68:71], v[242:245], v[144:147], v[68:71]
	v_mfma_f32_16x16x32_bf16 v[76:79], v[242:245], v[148:151], v[76:79]
	s_barrier
	s_nop 7
	s_nop 1
	s_waitcnt vmcnt(0)
	s_waitcnt vmcnt(0)
	v_and_b32_e32 v188, 63, v179
	v_lshrrev_b32_e32 v189, 6, v179
	v_mul_u32_u24_e32 v249, 0x2400, v189
	v_mov_b32_e32 v250, v249
	v_and_b32_e32 v251, 15, v188
	v_mul_u32_u24_e32 v251, 0x110, v251
	v_add_u32_e32 v249, v249, v251
	v_lshrrev_b32_e32 v251, 4, v188
	v_lshl_add_u32 v249, v251, 5, v249
	v_lshrrev_b32_e32 v237, 4, v188
	v_mul_u32_u24_e32 v251, 0x110, v237
	v_add_u32_e32 v250, v250, v251
	v_and_b32_e32 v251, 15, v188
	v_lshlrev_b32_e32 v251, 4, v251
	v_add_u32_e32 v250, v250, v251
	v_lshl_add_u32 v237, v189, 6, v237
	v_lshl_add_u32 v237, v237, 12, v251
	v_add_u32_e32 v238, 16384, v237
	v_add_u32_e32 v239, 32768, v237
	v_add_u32_e32 v240, 49152, v237
	v_add_u32_e32 v241, 65536, v237
	v_add_u32_e32 v242, 81920, v237
	v_add_u32_e32 v243, 98304, v237
	v_add_u32_e32 v248, 114688, v237
	s_lshl_b32 s16, s7, 8
	s_lshl_b32 s18, s6, 9
	s_lshr_b32 s19, s7, 4
	v_readlane_b32 s12, v253, 46
	v_readlane_b32 s13, v253, 47
	v_readlane_b32 s14, v253, 46
	v_readlane_b32 s15, v253, 47
	s_add_i32 s17, s16, 0xffff8000
	s_cmpk_lt_u32 s7, 0x80
	s_cselect_b32 s12, s12, s62
	s_cselect_b32 s13, s13, s63
	s_cselect_b32 s14, s14, s62
	s_cselect_b32 s15, s15, s63
	s_cselect_b32 s19, s19, 8
	s_cselect_b32 s16, s16, s17
	s_mov_b32 s17, 0
	s_lshl_b64 s[16:17], s[16:17], 12
	s_add_u32 s16, s16, s18
	s_addc_u32 s17, s17, 0
	s_add_u32 s12, s12, s16
	s_addc_u32 s13, s13, s17
	s_add_u32 s14, s14, s16
	s_addc_u32 s15, s15, s17
	s_mul_i32 s19, s19, 0x6000
	s_add_u32 s20, s0, s19
	s_addc_u32 s21, s1, 0
	s_add_u32 s20, s20, s18
	s_addc_u32 s21, s21, 0
	s_cmp_eq_u32 s101, 1
	s_cbranch_scc0 .Lre_downh_h0
	s_add_u32 s12, s12, 0x20000
	s_addc_u32 s13, s13, 0
	s_add_u32 s14, s14, 0x20000
	s_addc_u32 s15, s15, 0
